# scan loop: next-chunk LDS-DMA pieces formed straight-line and spread between the MFMAs instead of a branchy burst at the loop top
# baseline (speedup 1.0000x reference)
; #define LAS __attribute__((address_space(3)))
; __device__ __forceinline__ void phase_chunk_prep(const Params& p, LAS unsigned char* lds, int wave_s) {
;     ...
;         if (tid < 256) {
;             const int col = tid; float sol[64];
; #pragma unroll
;             for (int i = 0; i < 64; ++i) sol[i] = 0.f;
; #pragma unroll
;             for (int i = 0; i < 64; ++i) {
;                 float s0 = RHS[i * 256 + col], s1 = 0.f, s2 = 0.f, s3 = 0.f;
; #pragma unroll
;                 for (int j4 = 0; j4 < (i + 3) / 4; ++j4) { const f32x4 a = *(const LAS f32x4*)(AM + i * 64 + 4 * j4);
;                     s0 -= a.x * sol[4 * j4]; s1 -= a.y * sol[4 * j4 + 1]; s2 -= a.z * sol[4 * j4 + 2]; s3 -= a.w * sol[4 * j4 + 3]; }
;                 sol[i] = (s0 + s1) + (s2 + s3);
;             }
.Lcpstage_n_end:
	s_lshr_b32 s84, s24, 6
	v_mbcnt_lo_u32_b32 v32, -1, 0
	v_mbcnt_hi_u32_b32 v32, -1, v32
	v_and_b32_e32 v33, 31, v32
	v_lshrrev_b32_e32 v34, 5, v32
	s_lshl_b32 s85, s84, 5
	v_add_u32_e32 v35, s85, v33
	v_and_b32_e32 v36, 15, v32
	v_lshrrev_b32_e32 v37, 1, v36
	v_lshlrev_b32_e32 v37, 4, v37
	v_and_b32_e32 v38, 1, v36
	v_lshlrev_b32_e32 v38, 2, v38
	v_lshl_add_u32 v37, v34, 3, v37
	v_add_u32_e32 v37, v37, v38
	v_add_u32_e32 v37, 0x8800, v37
	v_lshlrev_b32_e32 v38, 2, v35
	v_add_u32_e32 v38, 0xc800, v38
	v_cmp_eq_u32_e32 vcc, 0, v34
	s_nop 1
	v_cndmask_b32_e64 v39, 0, 1.0, vcc
	v_mov_b32_e32 v0, 0
	v_mov_b32_e32 v1, 0
	v_mov_b32_e32 v2, 0
	v_mov_b32_e32 v3, 0
	v_mov_b32_e32 v4, 0
	v_mov_b32_e32 v5, 0
	v_mov_b32_e32 v6, 0
	v_mov_b32_e32 v7, 0
	v_mov_b32_e32 v8, 0
	v_mov_b32_e32 v9, 0
	v_mov_b32_e32 v10, 0
	v_mov_b32_e32 v11, 0
	v_mov_b32_e32 v12, 0
	v_mov_b32_e32 v13, 0
	v_mov_b32_e32 v14, 0
	v_mov_b32_e32 v15, 0
	v_mov_b32_e32 v16, 0
	v_mov_b32_e32 v17, 0
	v_mov_b32_e32 v18, 0
	v_mov_b32_e32 v19, 0
	v_mov_b32_e32 v20, 0
	v_mov_b32_e32 v21, 0
	v_mov_b32_e32 v22, 0
	v_mov_b32_e32 v23, 0
	v_mov_b32_e32 v24, 0
	v_mov_b32_e32 v25, 0
	v_mov_b32_e32 v26, 0
	v_mov_b32_e32 v27, 0
	v_mov_b32_e32 v28, 0
	v_mov_b32_e32 v29, 0
	v_mov_b32_e32 v30, 0
	v_mov_b32_e32 v31, 0
	ds_read_b32 v56, v38
	ds_read_b32 v48, v37
	ds_read_b32 v57, v38 offset:1024
	ds_read_b32 v50, v37 offset:256
	ds_read_b32 v58, v38 offset:2048
	ds_read_b32 v52, v37 offset:512
	ds_read_b32 v59, v38 offset:3072
	ds_read_b32 v54, v37 offset:768
	s_waitcnt lgkmcnt(6)
	v_mul_f32_e32 v40, v56, v39
	v_mov_b32_e32 v41, 0
	ds_read_b32 v56, v38 offset:4096
	ds_read_b32 v48, v37 offset:1024
	v_add_f32_e32 v42, v40, v41
	v_mov_b32_e32 v43, v42
	s_waitcnt lgkmcnt(6)
	v_mul_f32_e32 v44, v57, v39
	v_mov_b32_e32 v45, 0
	v_permlane32_swap_b32_e32 v42, v43
	s_nop 1
	v_add_f32_dpp v0, v42, v43 quad_perm:[0,1,2,3] row_mask:0x3 bank_mask:0xf
	v_fmac_f32_dpp v44, -v50, v0 row_newbcast:0 row_mask:0xf bank_mask:0xf
	ds_read_b32 v57, v38 offset:5120
	ds_read_b32 v50, v37 offset:1280
	v_add_f32_e32 v46, v44, v45
	v_mov_b32_e32 v47, v46
	s_waitcnt lgkmcnt(6)
	v_mul_f32_e32 v40, v58, v39
	v_mov_b32_e32 v41, 0
	v_permlane32_swap_b32_e32 v46, v47
	v_fmac_f32_dpp v40, -v52, v0 row_newbcast:0 row_mask:0xf bank_mask:0xf
	s_nop 0
	v_add_f32_dpp v1, v46, v47 quad_perm:[0,1,2,3] row_mask:0x3 bank_mask:0xf
	v_fmac_f32_dpp v41, -v52, v1 row_newbcast:1 row_mask:0xf bank_mask:0xf
	ds_read_b32 v58, v38 offset:6144
	ds_read_b32 v52, v37 offset:1536
	v_add_f32_e32 v42, v40, v41
	v_mov_b32_e32 v43, v42
	s_waitcnt lgkmcnt(6)
	v_mul_f32_e32 v44, v59, v39
	v_mov_b32_e32 v45, 0
	v_permlane32_swap_b32_e32 v42, v43
	v_fmac_f32_dpp v45, -v54, v1 row_newbcast:1 row_mask:0xf bank_mask:0xf
	s_nop 0
	v_add_f32_dpp v0, v42, v43 quad_perm:[0,1,2,3] row_mask:0xc bank_mask:0xf
	v_fmac_f32_dpp v44, -v54, v0 row_newbcast:0 row_mask:0xf bank_mask:0xf
	ds_read_b32 v59, v38 offset:7168
	ds_read_b32 v54, v37 offset:1792
	v_add_f32_e32 v46, v44, v45
	v_mov_b32_e32 v47, v46
	s_waitcnt lgkmcnt(6)
	v_mul_f32_e32 v40, v56, v39
	v_mov_b32_e32 v41, 0
	v_permlane32_swap_b32_e32 v46, v47
	v_fmac_f32_dpp v40, -v48, v0 row_newbcast:0 row_mask:0xf bank_mask:0xf
	s_nop 0
	v_add_f32_dpp v1, v46, v47 quad_perm:[0,1,2,3] row_mask:0xc bank_mask:0xf
	v_fmac_f32_dpp v41, -v48, v1 row_newbcast:1 row_mask:0xf bank_mask:0xf
	ds_read_b32 v56, v38 offset:8192
	ds_read_b32 v48, v37 offset:2048
	v_add_f32_e32 v42, v40, v41
	v_mov_b32_e32 v43, v42
	s_waitcnt lgkmcnt(6)
	v_mul_f32_e32 v44, v57, v39
	v_mov_b32_e32 v45, 0
	v_permlane32_swap_b32_e32 v42, v43
	v_fmac_f32_dpp v44, -v50, v0 row_newbcast:0 row_mask:0xf bank_mask:0xf
	v_fmac_f32_dpp v45, -v50, v1 row_newbcast:1 row_mask:0xf bank_mask:0xf
	v_add_f32_dpp v2, v42, v43 quad_perm:[0,1,2,3] row_mask:0x3 bank_mask:0xf
	v_fmac_f32_dpp v44, -v50, v2 row_newbcast:2 row_mask:0xf bank_mask:0xf
	ds_read_b32 v57, v38 offset:9216
	ds_read_b32 v50, v37 offset:2304
	v_add_f32_e32 v46, v44, v45
	v_mov_b32_e32 v47, v46
	s_waitcnt lgkmcnt(6)
	v_mul_f32_e32 v40, v58, v39
	v_mov_b32_e32 v41, 0
	v_permlane32_swap_b32_e32 v46, v47
	v_fmac_f32_dpp v40, -v52, v0 row_newbcast:0 row_mask:0xf bank_mask:0xf
	v_fmac_f32_dpp v41, -v52, v1 row_newbcast:1 row_mask:0xf bank_mask:0xf
	v_add_f32_dpp v3, v46, v47 quad_perm:[0,1,2,3] row_mask:0x3 bank_mask:0xf
	v_fmac_f32_dpp v40, -v52, v2 row_newbcast:2 row_mask:0xf bank_mask:0xf
	v_fmac_f32_dpp v41, -v52, v3 row_newbcast:3 row_mask:0xf bank_mask:0xf
	ds_read_b32 v58, v38 offset:10240
	ds_read_b32 v52, v37 offset:2560
	v_add_f32_e32 v42, v40, v41
	v_mov_b32_e32 v43, v42
	s_waitcnt lgkmcnt(6)
	v_mul_f32_e32 v44, v59, v39
	v_mov_b32_e32 v45, 0
	v_permlane32_swap_b32_e32 v42, v43
	v_fmac_f32_dpp v44, -v54, v0 row_newbcast:0 row_mask:0xf bank_mask:0xf
	v_fmac_f32_dpp v45, -v54, v1 row_newbcast:1 row_mask:0xf bank_mask:0xf
	v_add_f32_dpp v2, v42, v43 quad_perm:[0,1,2,3] row_mask:0xc bank_mask:0xf
	v_fmac_f32_dpp v45, -v54, v3 row_newbcast:3 row_mask:0xf bank_mask:0xf
	v_fmac_f32_dpp v44, -v54, v2 row_newbcast:2 row_mask:0xf bank_mask:0xf
	ds_read_b32 v59, v38 offset:11264
	ds_read_b32 v54, v37 offset:2816
	v_add_f32_e32 v46, v44, v45
	v_mov_b32_e32 v47, v46
	s_waitcnt lgkmcnt(6)
	v_mul_f32_e32 v40, v56, v39
	v_mov_b32_e32 v41, 0
	v_permlane32_swap_b32_e32 v46, v47
	v_fmac_f32_dpp v40, -v48, v0 row_newbcast:0 row_mask:0xf bank_mask:0xf
	v_fmac_f32_dpp v41, -v48, v1 row_newbcast:1 row_mask:0xf bank_mask:0xf
	v_add_f32_dpp v3, v46, v47 quad_perm:[0,1,2,3] row_mask:0xc bank_mask:0xf
	v_fmac_f32_dpp v40, -v48, v2 row_newbcast:2 row_mask:0xf bank_mask:0xf
	v_fmac_f32_dpp v41, -v48, v3 row_newbcast:3 row_mask:0xf bank_mask:0xf
	ds_read_b32 v56, v38 offset:12288
	ds_read_b32 v48, v37 offset:3072
	v_add_f32_e32 v42, v40, v41
	v_mov_b32_e32 v43, v42
	s_waitcnt lgkmcnt(6)
; #define LAS __attribute__((address_space(3)))
; __device__ __forceinline__ void phase_chunk_prep(const Params& p, LAS unsigned char* lds, int wave_s) {
;     ...
;             for (int i = 0; i < 64; ++i) {
;                 float s0 = RHS[i * 256 + col], s1 = 0.f, s2 = 0.f, s3 = 0.f;
; #pragma unroll
;                 for (int j4 = 0; j4 < (i + 3) / 4; ++j4) { const f32x4 a = *(const LAS f32x4*)(AM + i * 64 + 4 * j4);
;                     s0 -= a.x * sol[4 * j4]; s1 -= a.y * sol[4 * j4 + 1]; s2 -= a.z * sol[4 * j4 + 2]; s3 -= a.w * sol[4 * j4 + 3]; }
;                 sol[i] = (s0 + s1) + (s2 + s3);
	v_mul_f32_e32 v44, v57, v39
	v_mov_b32_e32 v45, 0
	v_permlane32_swap_b32_e32 v42, v43
	v_fmac_f32_dpp v44, -v50, v0 row_newbcast:0 row_mask:0xf bank_mask:0xf
	v_fmac_f32_dpp v45, -v50, v1 row_newbcast:1 row_mask:0xf bank_mask:0xf
	v_add_f32_dpp v4, v42, v43 quad_perm:[0,1,2,3] row_mask:0x3 bank_mask:0xf
	v_fmac_f32_dpp v44, -v50, v2 row_newbcast:2 row_mask:0xf bank_mask:0xf
	v_fmac_f32_dpp v45, -v50, v3 row_newbcast:3 row_mask:0xf bank_mask:0xf
	v_fmac_f32_dpp v44, -v50, v4 row_newbcast:4 row_mask:0xf bank_mask:0xf
	ds_read_b32 v57, v38 offset:13312
	ds_read_b32 v50, v37 offset:3328
	v_add_f32_e32 v46, v44, v45
	v_mov_b32_e32 v47, v46
	s_waitcnt lgkmcnt(6)
	v_mul_f32_e32 v40, v58, v39
	v_mov_b32_e32 v41, 0
	v_permlane32_swap_b32_e32 v46, v47
	v_fmac_f32_dpp v40, -v52, v0 row_newbcast:0 row_mask:0xf bank_mask:0xf
	v_fmac_f32_dpp v41, -v52, v1 row_newbcast:1 row_mask:0xf bank_mask:0xf
	v_add_f32_dpp v5, v46, v47 quad_perm:[0,1,2,3] row_mask:0x3 bank_mask:0xf
	v_fmac_f32_dpp v40, -v52, v2 row_newbcast:2 row_mask:0xf bank_mask:0xf
	v_fmac_f32_dpp v41, -v52, v3 row_newbcast:3 row_mask:0xf bank_mask:0xf
	v_fmac_f32_dpp v40, -v52, v4 row_newbcast:4 row_mask:0xf bank_mask:0xf
	v_fmac_f32_dpp v41, -v52, v5 row_newbcast:5 row_mask:0xf bank_mask:0xf
	ds_read_b32 v58, v38 offset:14336
	ds_read_b32 v52, v37 offset:3584
	v_add_f32_e32 v42, v40, v41
	v_mov_b32_e32 v43, v42
	s_waitcnt lgkmcnt(6)
	v_mul_f32_e32 v44, v59, v39
	v_mov_b32_e32 v45, 0
	v_permlane32_swap_b32_e32 v42, v43
	v_fmac_f32_dpp v44, -v54, v0 row_newbcast:0 row_mask:0xf bank_mask:0xf
	v_fmac_f32_dpp v45, -v54, v1 row_newbcast:1 row_mask:0xf bank_mask:0xf
	v_add_f32_dpp v4, v42, v43 quad_perm:[0,1,2,3] row_mask:0xc bank_mask:0xf
	v_fmac_f32_dpp v44, -v54, v2 row_newbcast:2 row_mask:0xf bank_mask:0xf
	v_fmac_f32_dpp v45, -v54, v3 row_newbcast:3 row_mask:0xf bank_mask:0xf
	v_fmac_f32_dpp v45, -v54, v5 row_newbcast:5 row_mask:0xf bank_mask:0xf
	v_fmac_f32_dpp v44, -v54, v4 row_newbcast:4 row_mask:0xf bank_mask:0xf
	ds_read_b32 v59, v38 offset:15360
	ds_read_b32 v54, v37 offset:3840
	v_add_f32_e32 v46, v44, v45
	v_mov_b32_e32 v47, v46
	s_waitcnt lgkmcnt(6)
	v_mul_f32_e32 v40, v56, v39
	v_mov_b32_e32 v41, 0
	v_permlane32_swap_b32_e32 v46, v47
	v_fmac_f32_dpp v40, -v48, v0 row_newbcast:0 row_mask:0xf bank_mask:0xf
	v_fmac_f32_dpp v41, -v48, v1 row_newbcast:1 row_mask:0xf bank_mask:0xf
	v_add_f32_dpp v5, v46, v47 quad_perm:[0,1,2,3] row_mask:0xc bank_mask:0xf
	v_fmac_f32_dpp v40, -v48, v2 row_newbcast:2 row_mask:0xf bank_mask:0xf
	v_fmac_f32_dpp v41, -v48, v3 row_newbcast:3 row_mask:0xf bank_mask:0xf
	v_fmac_f32_dpp v40, -v48, v4 row_newbcast:4 row_mask:0xf bank_mask:0xf
	v_fmac_f32_dpp v41, -v48, v5 row_newbcast:5 row_mask:0xf bank_mask:0xf
	ds_read_b32 v56, v38 offset:16384
	ds_read_b32 v48, v37 offset:4096
	v_add_f32_e32 v42, v40, v41
	v_mov_b32_e32 v43, v42
	s_waitcnt lgkmcnt(6)
	v_mul_f32_e32 v44, v57, v39
	v_mov_b32_e32 v45, 0
	v_permlane32_swap_b32_e32 v42, v43
	v_fmac_f32_dpp v44, -v50, v0 row_newbcast:0 row_mask:0xf bank_mask:0xf
	v_fmac_f32_dpp v45, -v50, v1 row_newbcast:1 row_mask:0xf bank_mask:0xf
	v_add_f32_dpp v6, v42, v43 quad_perm:[0,1,2,3] row_mask:0x3 bank_mask:0xf
	v_fmac_f32_dpp v44, -v50, v2 row_newbcast:2 row_mask:0xf bank_mask:0xf
	v_fmac_f32_dpp v45, -v50, v3 row_newbcast:3 row_mask:0xf bank_mask:0xf
	v_fmac_f32_dpp v44, -v50, v4 row_newbcast:4 row_mask:0xf bank_mask:0xf
	v_fmac_f32_dpp v45, -v50, v5 row_newbcast:5 row_mask:0xf bank_mask:0xf
	v_fmac_f32_dpp v44, -v50, v6 row_newbcast:6 row_mask:0xf bank_mask:0xf
	ds_read_b32 v57, v38 offset:17408
	ds_read_b32 v50, v37 offset:4352
	v_add_f32_e32 v46, v44, v45
	v_mov_b32_e32 v47, v46
	s_waitcnt lgkmcnt(6)
	v_mul_f32_e32 v40, v58, v39
	v_mov_b32_e32 v41, 0
	v_permlane32_swap_b32_e32 v46, v47
	v_fmac_f32_dpp v40, -v52, v0 row_newbcast:0 row_mask:0xf bank_mask:0xf
	v_fmac_f32_dpp v41, -v52, v1 row_newbcast:1 row_mask:0xf bank_mask:0xf
	v_add_f32_dpp v7, v46, v47 quad_perm:[0,1,2,3] row_mask:0x3 bank_mask:0xf
	v_fmac_f32_dpp v40, -v52, v2 row_newbcast:2 row_mask:0xf bank_mask:0xf
	v_fmac_f32_dpp v41, -v52, v3 row_newbcast:3 row_mask:0xf bank_mask:0xf
	v_fmac_f32_dpp v40, -v52, v4 row_newbcast:4 row_mask:0xf bank_mask:0xf
	v_fmac_f32_dpp v41, -v52, v5 row_newbcast:5 row_mask:0xf bank_mask:0xf
	v_fmac_f32_dpp v40, -v52, v6 row_newbcast:6 row_mask:0xf bank_mask:0xf
	v_fmac_f32_dpp v41, -v52, v7 row_newbcast:7 row_mask:0xf bank_mask:0xf
	ds_read_b32 v58, v38 offset:18432
	ds_read_b32 v52, v37 offset:4608
	v_add_f32_e32 v42, v40, v41
	v_mov_b32_e32 v43, v42
	s_waitcnt lgkmcnt(6)
	v_mul_f32_e32 v44, v59, v39
	v_mov_b32_e32 v45, 0
	v_permlane32_swap_b32_e32 v42, v43
	v_fmac_f32_dpp v44, -v54, v0 row_newbcast:0 row_mask:0xf bank_mask:0xf
	v_fmac_f32_dpp v45, -v54, v1 row_newbcast:1 row_mask:0xf bank_mask:0xf
	v_add_f32_dpp v6, v42, v43 quad_perm:[0,1,2,3] row_mask:0xc bank_mask:0xf
	v_fmac_f32_dpp v44, -v54, v2 row_newbcast:2 row_mask:0xf bank_mask:0xf
	v_fmac_f32_dpp v45, -v54, v3 row_newbcast:3 row_mask:0xf bank_mask:0xf
	v_fmac_f32_dpp v44, -v54, v4 row_newbcast:4 row_mask:0xf bank_mask:0xf
	v_fmac_f32_dpp v45, -v54, v5 row_newbcast:5 row_mask:0xf bank_mask:0xf
	v_fmac_f32_dpp v45, -v54, v7 row_newbcast:7 row_mask:0xf bank_mask:0xf
	v_fmac_f32_dpp v44, -v54, v6 row_newbcast:6 row_mask:0xf bank_mask:0xf
	ds_read_b32 v59, v38 offset:19456
	ds_read_b32 v54, v37 offset:4864
	v_add_f32_e32 v46, v44, v45
	v_mov_b32_e32 v47, v46
	s_waitcnt lgkmcnt(6)
; #define LAS __attribute__((address_space(3)))
; __device__ __forceinline__ void phase_chunk_prep(const Params& p, LAS unsigned char* lds, int wave_s) {
;     ...
;             for (int i = 0; i < 64; ++i) {
;                 float s0 = RHS[i * 256 + col], s1 = 0.f, s2 = 0.f, s3 = 0.f;
; #pragma unroll
;                 for (int j4 = 0; j4 < (i + 3) / 4; ++j4) { const f32x4 a = *(const LAS f32x4*)(AM + i * 64 + 4 * j4);
;                     s0 -= a.x * sol[4 * j4]; s1 -= a.y * sol[4 * j4 + 1]; s2 -= a.z * sol[4 * j4 + 2]; s3 -= a.w * sol[4 * j4 + 3]; }
;                 sol[i] = (s0 + s1) + (s2 + s3);
	v_mul_f32_e32 v40, v56, v39
	v_mov_b32_e32 v41, 0
	v_permlane32_swap_b32_e32 v46, v47
	v_fmac_f32_dpp v40, -v48, v0 row_newbcast:0 row_mask:0xf bank_mask:0xf
	v_fmac_f32_dpp v41, -v48, v1 row_newbcast:1 row_mask:0xf bank_mask:0xf
	v_add_f32_dpp v7, v46, v47 quad_perm:[0,1,2,3] row_mask:0xc bank_mask:0xf
	v_fmac_f32_dpp v40, -v48, v2 row_newbcast:2 row_mask:0xf bank_mask:0xf
	v_fmac_f32_dpp v41, -v48, v3 row_newbcast:3 row_mask:0xf bank_mask:0xf
	v_fmac_f32_dpp v40, -v48, v4 row_newbcast:4 row_mask:0xf bank_mask:0xf
	v_fmac_f32_dpp v41, -v48, v5 row_newbcast:5 row_mask:0xf bank_mask:0xf
	v_fmac_f32_dpp v40, -v48, v6 row_newbcast:6 row_mask:0xf bank_mask:0xf
	v_fmac_f32_dpp v41, -v48, v7 row_newbcast:7 row_mask:0xf bank_mask:0xf
	ds_read_b32 v56, v38 offset:20480
	ds_read_b32 v48, v37 offset:5120
	v_add_f32_e32 v42, v40, v41
	v_mov_b32_e32 v43, v42
	s_waitcnt lgkmcnt(6)
	v_mul_f32_e32 v44, v57, v39
	v_mov_b32_e32 v45, 0
	v_permlane32_swap_b32_e32 v42, v43
	v_fmac_f32_dpp v44, -v50, v0 row_newbcast:0 row_mask:0xf bank_mask:0xf
	v_fmac_f32_dpp v45, -v50, v1 row_newbcast:1 row_mask:0xf bank_mask:0xf
	v_add_f32_dpp v8, v42, v43 quad_perm:[0,1,2,3] row_mask:0x3 bank_mask:0xf
	v_fmac_f32_dpp v44, -v50, v2 row_newbcast:2 row_mask:0xf bank_mask:0xf
	v_fmac_f32_dpp v45, -v50, v3 row_newbcast:3 row_mask:0xf bank_mask:0xf
	v_fmac_f32_dpp v44, -v50, v4 row_newbcast:4 row_mask:0xf bank_mask:0xf
	v_fmac_f32_dpp v45, -v50, v5 row_newbcast:5 row_mask:0xf bank_mask:0xf
	v_fmac_f32_dpp v44, -v50, v6 row_newbcast:6 row_mask:0xf bank_mask:0xf
	v_fmac_f32_dpp v45, -v50, v7 row_newbcast:7 row_mask:0xf bank_mask:0xf
	v_fmac_f32_dpp v44, -v50, v8 row_newbcast:8 row_mask:0xf bank_mask:0xf
	ds_read_b32 v57, v38 offset:21504
	ds_read_b32 v50, v37 offset:5376
	v_add_f32_e32 v46, v44, v45
	v_mov_b32_e32 v47, v46
	s_waitcnt lgkmcnt(6)
	v_mul_f32_e32 v40, v58, v39
	v_mov_b32_e32 v41, 0
	v_permlane32_swap_b32_e32 v46, v47
	v_fmac_f32_dpp v40, -v52, v0 row_newbcast:0 row_mask:0xf bank_mask:0xf
	v_fmac_f32_dpp v41, -v52, v1 row_newbcast:1 row_mask:0xf bank_mask:0xf
	v_add_f32_dpp v9, v46, v47 quad_perm:[0,1,2,3] row_mask:0x3 bank_mask:0xf
	v_fmac_f32_dpp v40, -v52, v2 row_newbcast:2 row_mask:0xf bank_mask:0xf
	v_fmac_f32_dpp v41, -v52, v3 row_newbcast:3 row_mask:0xf bank_mask:0xf
	v_fmac_f32_dpp v40, -v52, v4 row_newbcast:4 row_mask:0xf bank_mask:0xf
	v_fmac_f32_dpp v41, -v52, v5 row_newbcast:5 row_mask:0xf bank_mask:0xf
	v_fmac_f32_dpp v40, -v52, v6 row_newbcast:6 row_mask:0xf bank_mask:0xf
	v_fmac_f32_dpp v41, -v52, v7 row_newbcast:7 row_mask:0xf bank_mask:0xf
	v_fmac_f32_dpp v40, -v52, v8 row_newbcast:8 row_mask:0xf bank_mask:0xf
	v_fmac_f32_dpp v41, -v52, v9 row_newbcast:9 row_mask:0xf bank_mask:0xf
	ds_read_b32 v58, v38 offset:22528
	ds_read_b32 v52, v37 offset:5632
	v_add_f32_e32 v42, v40, v41
	v_mov_b32_e32 v43, v42
	s_waitcnt lgkmcnt(6)
	v_mul_f32_e32 v44, v59, v39
	v_mov_b32_e32 v45, 0
	v_permlane32_swap_b32_e32 v42, v43
	v_fmac_f32_dpp v44, -v54, v0 row_newbcast:0 row_mask:0xf bank_mask:0xf
	v_fmac_f32_dpp v45, -v54, v1 row_newbcast:1 row_mask:0xf bank_mask:0xf
	v_add_f32_dpp v8, v42, v43 quad_perm:[0,1,2,3] row_mask:0xc bank_mask:0xf
	v_fmac_f32_dpp v44, -v54, v2 row_newbcast:2 row_mask:0xf bank_mask:0xf
	v_fmac_f32_dpp v45, -v54, v3 row_newbcast:3 row_mask:0xf bank_mask:0xf
	v_fmac_f32_dpp v44, -v54, v4 row_newbcast:4 row_mask:0xf bank_mask:0xf
	v_fmac_f32_dpp v45, -v54, v5 row_newbcast:5 row_mask:0xf bank_mask:0xf
	v_fmac_f32_dpp v44, -v54, v6 row_newbcast:6 row_mask:0xf bank_mask:0xf
	v_fmac_f32_dpp v45, -v54, v7 row_newbcast:7 row_mask:0xf bank_mask:0xf
	v_fmac_f32_dpp v45, -v54, v9 row_newbcast:9 row_mask:0xf bank_mask:0xf
	v_fmac_f32_dpp v44, -v54, v8 row_newbcast:8 row_mask:0xf bank_mask:0xf
	ds_read_b32 v59, v38 offset:23552
	ds_read_b32 v54, v37 offset:5888
	v_add_f32_e32 v46, v44, v45
	v_mov_b32_e32 v47, v46
	s_waitcnt lgkmcnt(6)
	v_mul_f32_e32 v40, v56, v39
	v_mov_b32_e32 v41, 0
	v_permlane32_swap_b32_e32 v46, v47
	v_fmac_f32_dpp v40, -v48, v0 row_newbcast:0 row_mask:0xf bank_mask:0xf
	v_fmac_f32_dpp v41, -v48, v1 row_newbcast:1 row_mask:0xf bank_mask:0xf
	v_add_f32_dpp v9, v46, v47 quad_perm:[0,1,2,3] row_mask:0xc bank_mask:0xf
	v_fmac_f32_dpp v40, -v48, v2 row_newbcast:2 row_mask:0xf bank_mask:0xf
	v_fmac_f32_dpp v41, -v48, v3 row_newbcast:3 row_mask:0xf bank_mask:0xf
	v_fmac_f32_dpp v40, -v48, v4 row_newbcast:4 row_mask:0xf bank_mask:0xf
	v_fmac_f32_dpp v41, -v48, v5 row_newbcast:5 row_mask:0xf bank_mask:0xf
	v_fmac_f32_dpp v40, -v48, v6 row_newbcast:6 row_mask:0xf bank_mask:0xf
	v_fmac_f32_dpp v41, -v48, v7 row_newbcast:7 row_mask:0xf bank_mask:0xf
	v_fmac_f32_dpp v40, -v48, v8 row_newbcast:8 row_mask:0xf bank_mask:0xf
	v_fmac_f32_dpp v41, -v48, v9 row_newbcast:9 row_mask:0xf bank_mask:0xf
	ds_read_b32 v56, v38 offset:24576
	ds_read_b32 v48, v37 offset:6144
	v_add_f32_e32 v42, v40, v41
	v_mov_b32_e32 v43, v42
	s_waitcnt lgkmcnt(6)
	v_mul_f32_e32 v44, v57, v39
	v_mov_b32_e32 v45, 0
	v_permlane32_swap_b32_e32 v42, v43
	v_fmac_f32_dpp v44, -v50, v0 row_newbcast:0 row_mask:0xf bank_mask:0xf
	v_fmac_f32_dpp v45, -v50, v1 row_newbcast:1 row_mask:0xf bank_mask:0xf
	v_add_f32_dpp v10, v42, v43 quad_perm:[0,1,2,3] row_mask:0x3 bank_mask:0xf
	v_fmac_f32_dpp v44, -v50, v2 row_newbcast:2 row_mask:0xf bank_mask:0xf
	v_fmac_f32_dpp v45, -v50, v3 row_newbcast:3 row_mask:0xf bank_mask:0xf
	v_fmac_f32_dpp v44, -v50, v4 row_newbcast:4 row_mask:0xf bank_mask:0xf
	v_fmac_f32_dpp v45, -v50, v5 row_newbcast:5 row_mask:0xf bank_mask:0xf
	v_fmac_f32_dpp v44, -v50, v6 row_newbcast:6 row_mask:0xf bank_mask:0xf
	v_fmac_f32_dpp v45, -v50, v7 row_newbcast:7 row_mask:0xf bank_mask:0xf
	v_fmac_f32_dpp v44, -v50, v8 row_newbcast:8 row_mask:0xf bank_mask:0xf
	v_fmac_f32_dpp v45, -v50, v9 row_newbcast:9 row_mask:0xf bank_mask:0xf
	v_fmac_f32_dpp v44, -v50, v10 row_newbcast:10 row_mask:0xf bank_mask:0xf
	ds_read_b32 v57, v38 offset:25600
	ds_read_b32 v50, v37 offset:6400
	v_add_f32_e32 v46, v44, v45
	v_mov_b32_e32 v47, v46
	s_waitcnt lgkmcnt(6)
; #define LAS __attribute__((address_space(3)))
; __device__ __forceinline__ void phase_chunk_prep(const Params& p, LAS unsigned char* lds, int wave_s) {
;     ...
;             for (int i = 0; i < 64; ++i) {
;                 float s0 = RHS[i * 256 + col], s1 = 0.f, s2 = 0.f, s3 = 0.f;
; #pragma unroll
;                 for (int j4 = 0; j4 < (i + 3) / 4; ++j4) { const f32x4 a = *(const LAS f32x4*)(AM + i * 64 + 4 * j4);
;                     s0 -= a.x * sol[4 * j4]; s1 -= a.y * sol[4 * j4 + 1]; s2 -= a.z * sol[4 * j4 + 2]; s3 -= a.w * sol[4 * j4 + 3]; }
;                 sol[i] = (s0 + s1) + (s2 + s3);
	v_mul_f32_e32 v40, v58, v39
	v_mov_b32_e32 v41, 0
	v_permlane32_swap_b32_e32 v46, v47
	v_fmac_f32_dpp v40, -v52, v0 row_newbcast:0 row_mask:0xf bank_mask:0xf
	v_fmac_f32_dpp v41, -v52, v1 row_newbcast:1 row_mask:0xf bank_mask:0xf
	v_add_f32_dpp v11, v46, v47 quad_perm:[0,1,2,3] row_mask:0x3 bank_mask:0xf
	v_fmac_f32_dpp v40, -v52, v2 row_newbcast:2 row_mask:0xf bank_mask:0xf
	v_fmac_f32_dpp v41, -v52, v3 row_newbcast:3 row_mask:0xf bank_mask:0xf
	v_fmac_f32_dpp v40, -v52, v4 row_newbcast:4 row_mask:0xf bank_mask:0xf
	v_fmac_f32_dpp v41, -v52, v5 row_newbcast:5 row_mask:0xf bank_mask:0xf
	v_fmac_f32_dpp v40, -v52, v6 row_newbcast:6 row_mask:0xf bank_mask:0xf
	v_fmac_f32_dpp v41, -v52, v7 row_newbcast:7 row_mask:0xf bank_mask:0xf
	v_fmac_f32_dpp v40, -v52, v8 row_newbcast:8 row_mask:0xf bank_mask:0xf
	v_fmac_f32_dpp v41, -v52, v9 row_newbcast:9 row_mask:0xf bank_mask:0xf
	v_fmac_f32_dpp v40, -v52, v10 row_newbcast:10 row_mask:0xf bank_mask:0xf
	v_fmac_f32_dpp v41, -v52, v11 row_newbcast:11 row_mask:0xf bank_mask:0xf
	ds_read_b32 v58, v38 offset:26624
	ds_read_b32 v52, v37 offset:6656
	v_add_f32_e32 v42, v40, v41
	v_mov_b32_e32 v43, v42
	s_waitcnt lgkmcnt(6)
	v_mul_f32_e32 v44, v59, v39
	v_mov_b32_e32 v45, 0
	v_permlane32_swap_b32_e32 v42, v43
	v_fmac_f32_dpp v44, -v54, v0 row_newbcast:0 row_mask:0xf bank_mask:0xf
	v_fmac_f32_dpp v45, -v54, v1 row_newbcast:1 row_mask:0xf bank_mask:0xf
	v_add_f32_dpp v10, v42, v43 quad_perm:[0,1,2,3] row_mask:0xc bank_mask:0xf
	v_fmac_f32_dpp v44, -v54, v2 row_newbcast:2 row_mask:0xf bank_mask:0xf
	v_fmac_f32_dpp v45, -v54, v3 row_newbcast:3 row_mask:0xf bank_mask:0xf
	v_fmac_f32_dpp v44, -v54, v4 row_newbcast:4 row_mask:0xf bank_mask:0xf
	v_fmac_f32_dpp v45, -v54, v5 row_newbcast:5 row_mask:0xf bank_mask:0xf
	v_fmac_f32_dpp v44, -v54, v6 row_newbcast:6 row_mask:0xf bank_mask:0xf
	v_fmac_f32_dpp v45, -v54, v7 row_newbcast:7 row_mask:0xf bank_mask:0xf
	v_fmac_f32_dpp v44, -v54, v8 row_newbcast:8 row_mask:0xf bank_mask:0xf
	v_fmac_f32_dpp v45, -v54, v9 row_newbcast:9 row_mask:0xf bank_mask:0xf
	v_fmac_f32_dpp v45, -v54, v11 row_newbcast:11 row_mask:0xf bank_mask:0xf
	v_fmac_f32_dpp v44, -v54, v10 row_newbcast:10 row_mask:0xf bank_mask:0xf
	ds_read_b32 v59, v38 offset:27648
	ds_read_b32 v54, v37 offset:6912
	v_add_f32_e32 v46, v44, v45
	v_mov_b32_e32 v47, v46
	s_waitcnt lgkmcnt(6)
	v_mul_f32_e32 v40, v56, v39
	v_mov_b32_e32 v41, 0
	v_permlane32_swap_b32_e32 v46, v47
	v_fmac_f32_dpp v40, -v48, v0 row_newbcast:0 row_mask:0xf bank_mask:0xf
	v_fmac_f32_dpp v41, -v48, v1 row_newbcast:1 row_mask:0xf bank_mask:0xf
	v_add_f32_dpp v11, v46, v47 quad_perm:[0,1,2,3] row_mask:0xc bank_mask:0xf
	v_fmac_f32_dpp v40, -v48, v2 row_newbcast:2 row_mask:0xf bank_mask:0xf
	v_fmac_f32_dpp v41, -v48, v3 row_newbcast:3 row_mask:0xf bank_mask:0xf
	v_fmac_f32_dpp v40, -v48, v4 row_newbcast:4 row_mask:0xf bank_mask:0xf
	v_fmac_f32_dpp v41, -v48, v5 row_newbcast:5 row_mask:0xf bank_mask:0xf
	v_fmac_f32_dpp v40, -v48, v6 row_newbcast:6 row_mask:0xf bank_mask:0xf
	v_fmac_f32_dpp v41, -v48, v7 row_newbcast:7 row_mask:0xf bank_mask:0xf
	v_fmac_f32_dpp v40, -v48, v8 row_newbcast:8 row_mask:0xf bank_mask:0xf
	v_fmac_f32_dpp v41, -v48, v9 row_newbcast:9 row_mask:0xf bank_mask:0xf
	v_fmac_f32_dpp v40, -v48, v10 row_newbcast:10 row_mask:0xf bank_mask:0xf
	v_fmac_f32_dpp v41, -v48, v11 row_newbcast:11 row_mask:0xf bank_mask:0xf
	ds_read_b32 v56, v38 offset:28672
	ds_read_b32 v48, v37 offset:7168
	v_add_f32_e32 v42, v40, v41
	v_mov_b32_e32 v43, v42
	s_waitcnt lgkmcnt(6)
	v_mul_f32_e32 v44, v57, v39
	v_mov_b32_e32 v45, 0
	v_permlane32_swap_b32_e32 v42, v43
	v_fmac_f32_dpp v44, -v50, v0 row_newbcast:0 row_mask:0xf bank_mask:0xf
	v_fmac_f32_dpp v45, -v50, v1 row_newbcast:1 row_mask:0xf bank_mask:0xf
	v_add_f32_dpp v12, v42, v43 quad_perm:[0,1,2,3] row_mask:0x3 bank_mask:0xf
	v_fmac_f32_dpp v44, -v50, v2 row_newbcast:2 row_mask:0xf bank_mask:0xf
	v_fmac_f32_dpp v45, -v50, v3 row_newbcast:3 row_mask:0xf bank_mask:0xf
	v_fmac_f32_dpp v44, -v50, v4 row_newbcast:4 row_mask:0xf bank_mask:0xf
	v_fmac_f32_dpp v45, -v50, v5 row_newbcast:5 row_mask:0xf bank_mask:0xf
	v_fmac_f32_dpp v44, -v50, v6 row_newbcast:6 row_mask:0xf bank_mask:0xf
	v_fmac_f32_dpp v45, -v50, v7 row_newbcast:7 row_mask:0xf bank_mask:0xf
	v_fmac_f32_dpp v44, -v50, v8 row_newbcast:8 row_mask:0xf bank_mask:0xf
	v_fmac_f32_dpp v45, -v50, v9 row_newbcast:9 row_mask:0xf bank_mask:0xf
	v_fmac_f32_dpp v44, -v50, v10 row_newbcast:10 row_mask:0xf bank_mask:0xf
	v_fmac_f32_dpp v45, -v50, v11 row_newbcast:11 row_mask:0xf bank_mask:0xf
	v_fmac_f32_dpp v44, -v50, v12 row_newbcast:12 row_mask:0xf bank_mask:0xf
	ds_read_b32 v57, v38 offset:29696
	ds_read_b32 v50, v37 offset:7424
	v_add_f32_e32 v46, v44, v45
	v_mov_b32_e32 v47, v46
	s_waitcnt lgkmcnt(6)
	v_mul_f32_e32 v40, v58, v39
	v_mov_b32_e32 v41, 0
	v_permlane32_swap_b32_e32 v46, v47
	v_fmac_f32_dpp v40, -v52, v0 row_newbcast:0 row_mask:0xf bank_mask:0xf
	v_fmac_f32_dpp v41, -v52, v1 row_newbcast:1 row_mask:0xf bank_mask:0xf
	v_add_f32_dpp v13, v46, v47 quad_perm:[0,1,2,3] row_mask:0x3 bank_mask:0xf
	v_fmac_f32_dpp v40, -v52, v2 row_newbcast:2 row_mask:0xf bank_mask:0xf
	v_fmac_f32_dpp v41, -v52, v3 row_newbcast:3 row_mask:0xf bank_mask:0xf
	v_fmac_f32_dpp v40, -v52, v4 row_newbcast:4 row_mask:0xf bank_mask:0xf
	v_fmac_f32_dpp v41, -v52, v5 row_newbcast:5 row_mask:0xf bank_mask:0xf
	v_fmac_f32_dpp v40, -v52, v6 row_newbcast:6 row_mask:0xf bank_mask:0xf
	v_fmac_f32_dpp v41, -v52, v7 row_newbcast:7 row_mask:0xf bank_mask:0xf
	v_fmac_f32_dpp v40, -v52, v8 row_newbcast:8 row_mask:0xf bank_mask:0xf
	v_fmac_f32_dpp v41, -v52, v9 row_newbcast:9 row_mask:0xf bank_mask:0xf
	v_fmac_f32_dpp v40, -v52, v10 row_newbcast:10 row_mask:0xf bank_mask:0xf
	v_fmac_f32_dpp v41, -v52, v11 row_newbcast:11 row_mask:0xf bank_mask:0xf
	v_fmac_f32_dpp v40, -v52, v12 row_newbcast:12 row_mask:0xf bank_mask:0xf
	v_fmac_f32_dpp v41, -v52, v13 row_newbcast:13 row_mask:0xf bank_mask:0xf
	ds_read_b32 v58, v38 offset:30720
	ds_read_b32 v52, v37 offset:7680
	v_add_f32_e32 v42, v40, v41
	v_mov_b32_e32 v43, v42
	s_waitcnt lgkmcnt(6)
; #define LAS __attribute__((address_space(3)))
; __device__ __forceinline__ void phase_chunk_prep(const Params& p, LAS unsigned char* lds, int wave_s) {
;     ...
;             for (int i = 0; i < 64; ++i) {
;                 float s0 = RHS[i * 256 + col], s1 = 0.f, s2 = 0.f, s3 = 0.f;
; #pragma unroll
;                 for (int j4 = 0; j4 < (i + 3) / 4; ++j4) { const f32x4 a = *(const LAS f32x4*)(AM + i * 64 + 4 * j4);
;                     s0 -= a.x * sol[4 * j4]; s1 -= a.y * sol[4 * j4 + 1]; s2 -= a.z * sol[4 * j4 + 2]; s3 -= a.w * sol[4 * j4 + 3]; }
;                 sol[i] = (s0 + s1) + (s2 + s3);
	v_mul_f32_e32 v44, v59, v39
	v_mov_b32_e32 v45, 0
	v_permlane32_swap_b32_e32 v42, v43
	v_fmac_f32_dpp v44, -v54, v0 row_newbcast:0 row_mask:0xf bank_mask:0xf
	v_fmac_f32_dpp v45, -v54, v1 row_newbcast:1 row_mask:0xf bank_mask:0xf
	v_add_f32_dpp v12, v42, v43 quad_perm:[0,1,2,3] row_mask:0xc bank_mask:0xf
	v_fmac_f32_dpp v44, -v54, v2 row_newbcast:2 row_mask:0xf bank_mask:0xf
	v_fmac_f32_dpp v45, -v54, v3 row_newbcast:3 row_mask:0xf bank_mask:0xf
	v_fmac_f32_dpp v44, -v54, v4 row_newbcast:4 row_mask:0xf bank_mask:0xf
	v_fmac_f32_dpp v45, -v54, v5 row_newbcast:5 row_mask:0xf bank_mask:0xf
	v_fmac_f32_dpp v44, -v54, v6 row_newbcast:6 row_mask:0xf bank_mask:0xf
	v_fmac_f32_dpp v45, -v54, v7 row_newbcast:7 row_mask:0xf bank_mask:0xf
	v_fmac_f32_dpp v44, -v54, v8 row_newbcast:8 row_mask:0xf bank_mask:0xf
	v_fmac_f32_dpp v45, -v54, v9 row_newbcast:9 row_mask:0xf bank_mask:0xf
	v_fmac_f32_dpp v44, -v54, v10 row_newbcast:10 row_mask:0xf bank_mask:0xf
	v_fmac_f32_dpp v45, -v54, v11 row_newbcast:11 row_mask:0xf bank_mask:0xf
	v_fmac_f32_dpp v45, -v54, v13 row_newbcast:13 row_mask:0xf bank_mask:0xf
	v_fmac_f32_dpp v44, -v54, v12 row_newbcast:12 row_mask:0xf bank_mask:0xf
	ds_read_b32 v59, v38 offset:31744
	ds_read_b32 v54, v37 offset:7936
	v_add_f32_e32 v46, v44, v45
	v_mov_b32_e32 v47, v46
	s_waitcnt lgkmcnt(6)
	v_mul_f32_e32 v40, v56, v39
	v_mov_b32_e32 v41, 0
	v_permlane32_swap_b32_e32 v46, v47
	v_fmac_f32_dpp v40, -v48, v0 row_newbcast:0 row_mask:0xf bank_mask:0xf
	v_fmac_f32_dpp v41, -v48, v1 row_newbcast:1 row_mask:0xf bank_mask:0xf
	v_add_f32_dpp v13, v46, v47 quad_perm:[0,1,2,3] row_mask:0xc bank_mask:0xf
	v_fmac_f32_dpp v40, -v48, v2 row_newbcast:2 row_mask:0xf bank_mask:0xf
	v_fmac_f32_dpp v41, -v48, v3 row_newbcast:3 row_mask:0xf bank_mask:0xf
	v_fmac_f32_dpp v40, -v48, v4 row_newbcast:4 row_mask:0xf bank_mask:0xf
	v_fmac_f32_dpp v41, -v48, v5 row_newbcast:5 row_mask:0xf bank_mask:0xf
	v_fmac_f32_dpp v40, -v48, v6 row_newbcast:6 row_mask:0xf bank_mask:0xf
	v_fmac_f32_dpp v41, -v48, v7 row_newbcast:7 row_mask:0xf bank_mask:0xf
	v_fmac_f32_dpp v40, -v48, v8 row_newbcast:8 row_mask:0xf bank_mask:0xf
	v_fmac_f32_dpp v41, -v48, v9 row_newbcast:9 row_mask:0xf bank_mask:0xf
	v_fmac_f32_dpp v40, -v48, v10 row_newbcast:10 row_mask:0xf bank_mask:0xf
	v_fmac_f32_dpp v41, -v48, v11 row_newbcast:11 row_mask:0xf bank_mask:0xf
	v_fmac_f32_dpp v40, -v48, v12 row_newbcast:12 row_mask:0xf bank_mask:0xf
	v_fmac_f32_dpp v41, -v48, v13 row_newbcast:13 row_mask:0xf bank_mask:0xf
	ds_read_b32 v56, v38 offset:32768
	ds_read_b32 v48, v37 offset:8192
	v_add_f32_e32 v42, v40, v41
	v_mov_b32_e32 v43, v42
	s_waitcnt lgkmcnt(6)
	v_mul_f32_e32 v44, v57, v39
	v_mov_b32_e32 v45, 0
	v_permlane32_swap_b32_e32 v42, v43
	v_fmac_f32_dpp v44, -v50, v0 row_newbcast:0 row_mask:0xf bank_mask:0xf
	v_fmac_f32_dpp v45, -v50, v1 row_newbcast:1 row_mask:0xf bank_mask:0xf
	v_add_f32_dpp v14, v42, v43 quad_perm:[0,1,2,3] row_mask:0x3 bank_mask:0xf
	v_fmac_f32_dpp v44, -v50, v2 row_newbcast:2 row_mask:0xf bank_mask:0xf
	v_fmac_f32_dpp v45, -v50, v3 row_newbcast:3 row_mask:0xf bank_mask:0xf
	v_fmac_f32_dpp v44, -v50, v4 row_newbcast:4 row_mask:0xf bank_mask:0xf
	v_fmac_f32_dpp v45, -v50, v5 row_newbcast:5 row_mask:0xf bank_mask:0xf
	v_fmac_f32_dpp v44, -v50, v6 row_newbcast:6 row_mask:0xf bank_mask:0xf
	v_fmac_f32_dpp v45, -v50, v7 row_newbcast:7 row_mask:0xf bank_mask:0xf
	v_fmac_f32_dpp v44, -v50, v8 row_newbcast:8 row_mask:0xf bank_mask:0xf
	v_fmac_f32_dpp v45, -v50, v9 row_newbcast:9 row_mask:0xf bank_mask:0xf
	v_fmac_f32_dpp v44, -v50, v10 row_newbcast:10 row_mask:0xf bank_mask:0xf
	v_fmac_f32_dpp v45, -v50, v11 row_newbcast:11 row_mask:0xf bank_mask:0xf
	v_fmac_f32_dpp v44, -v50, v12 row_newbcast:12 row_mask:0xf bank_mask:0xf
	v_fmac_f32_dpp v45, -v50, v13 row_newbcast:13 row_mask:0xf bank_mask:0xf
	v_fmac_f32_dpp v44, -v50, v14 row_newbcast:14 row_mask:0xf bank_mask:0xf
	ds_read_b32 v57, v38 offset:33792
	ds_read_b32 v50, v37 offset:8448
	ds_read_b32 v51, v37 offset:8576
	v_add_f32_e32 v46, v44, v45
	v_mov_b32_e32 v47, v46
	s_waitcnt lgkmcnt(7)
	v_mul_f32_e32 v40, v58, v39
	v_mov_b32_e32 v41, 0
	v_permlane32_swap_b32_e32 v46, v47
	v_fmac_f32_dpp v40, -v52, v0 row_newbcast:0 row_mask:0xf bank_mask:0xf
	v_fmac_f32_dpp v41, -v52, v1 row_newbcast:1 row_mask:0xf bank_mask:0xf
	v_add_f32_dpp v15, v46, v47 quad_perm:[0,1,2,3] row_mask:0x3 bank_mask:0xf
	v_fmac_f32_dpp v40, -v52, v2 row_newbcast:2 row_mask:0xf bank_mask:0xf
	v_fmac_f32_dpp v41, -v52, v3 row_newbcast:3 row_mask:0xf bank_mask:0xf
	v_fmac_f32_dpp v40, -v52, v4 row_newbcast:4 row_mask:0xf bank_mask:0xf
	v_fmac_f32_dpp v41, -v52, v5 row_newbcast:5 row_mask:0xf bank_mask:0xf
	v_fmac_f32_dpp v40, -v52, v6 row_newbcast:6 row_mask:0xf bank_mask:0xf
	v_fmac_f32_dpp v41, -v52, v7 row_newbcast:7 row_mask:0xf bank_mask:0xf
	v_fmac_f32_dpp v40, -v52, v8 row_newbcast:8 row_mask:0xf bank_mask:0xf
	v_fmac_f32_dpp v41, -v52, v9 row_newbcast:9 row_mask:0xf bank_mask:0xf
	v_fmac_f32_dpp v40, -v52, v10 row_newbcast:10 row_mask:0xf bank_mask:0xf
	v_fmac_f32_dpp v41, -v52, v11 row_newbcast:11 row_mask:0xf bank_mask:0xf
	v_fmac_f32_dpp v40, -v52, v12 row_newbcast:12 row_mask:0xf bank_mask:0xf
	v_fmac_f32_dpp v41, -v52, v13 row_newbcast:13 row_mask:0xf bank_mask:0xf
	v_fmac_f32_dpp v40, -v52, v14 row_newbcast:14 row_mask:0xf bank_mask:0xf
	v_fmac_f32_dpp v41, -v52, v15 row_newbcast:15 row_mask:0xf bank_mask:0xf
	ds_read_b32 v58, v38 offset:34816
	ds_read_b32 v52, v37 offset:8704
	ds_read_b32 v53, v37 offset:8832
	v_add_f32_e32 v42, v40, v41
	v_mov_b32_e32 v43, v42
	s_waitcnt lgkmcnt(8)
; #define LAS __attribute__((address_space(3)))
; __device__ __forceinline__ void phase_chunk_prep(const Params& p, LAS unsigned char* lds, int wave_s) {
;     ...
;             for (int i = 0; i < 64; ++i) {
;                 float s0 = RHS[i * 256 + col], s1 = 0.f, s2 = 0.f, s3 = 0.f;
; #pragma unroll
;                 for (int j4 = 0; j4 < (i + 3) / 4; ++j4) { const f32x4 a = *(const LAS f32x4*)(AM + i * 64 + 4 * j4);
;                     s0 -= a.x * sol[4 * j4]; s1 -= a.y * sol[4 * j4 + 1]; s2 -= a.z * sol[4 * j4 + 2]; s3 -= a.w * sol[4 * j4 + 3]; }
;                 sol[i] = (s0 + s1) + (s2 + s3);
	v_mul_f32_e32 v44, v59, v39
	v_mov_b32_e32 v45, 0
	v_permlane32_swap_b32_e32 v42, v43
	v_fmac_f32_dpp v44, -v54, v0 row_newbcast:0 row_mask:0xf bank_mask:0xf
	v_fmac_f32_dpp v45, -v54, v1 row_newbcast:1 row_mask:0xf bank_mask:0xf
	v_add_f32_dpp v14, v42, v43 quad_perm:[0,1,2,3] row_mask:0xc bank_mask:0xf
	v_fmac_f32_dpp v44, -v54, v2 row_newbcast:2 row_mask:0xf bank_mask:0xf
	v_fmac_f32_dpp v45, -v54, v3 row_newbcast:3 row_mask:0xf bank_mask:0xf
	v_fmac_f32_dpp v44, -v54, v4 row_newbcast:4 row_mask:0xf bank_mask:0xf
	v_fmac_f32_dpp v45, -v54, v5 row_newbcast:5 row_mask:0xf bank_mask:0xf
	v_fmac_f32_dpp v44, -v54, v6 row_newbcast:6 row_mask:0xf bank_mask:0xf
	v_fmac_f32_dpp v45, -v54, v7 row_newbcast:7 row_mask:0xf bank_mask:0xf
	v_fmac_f32_dpp v44, -v54, v8 row_newbcast:8 row_mask:0xf bank_mask:0xf
	v_fmac_f32_dpp v45, -v54, v9 row_newbcast:9 row_mask:0xf bank_mask:0xf
	v_fmac_f32_dpp v44, -v54, v10 row_newbcast:10 row_mask:0xf bank_mask:0xf
	v_fmac_f32_dpp v45, -v54, v11 row_newbcast:11 row_mask:0xf bank_mask:0xf
	v_fmac_f32_dpp v44, -v54, v12 row_newbcast:12 row_mask:0xf bank_mask:0xf
	v_fmac_f32_dpp v45, -v54, v13 row_newbcast:13 row_mask:0xf bank_mask:0xf
	v_fmac_f32_dpp v45, -v54, v15 row_newbcast:15 row_mask:0xf bank_mask:0xf
	v_fmac_f32_dpp v44, -v54, v14 row_newbcast:14 row_mask:0xf bank_mask:0xf
	ds_read_b32 v59, v38 offset:35840
	ds_read_b32 v54, v37 offset:8960
	ds_read_b32 v55, v37 offset:9088
	v_add_f32_e32 v46, v44, v45
	v_mov_b32_e32 v47, v46
	s_waitcnt lgkmcnt(9)
	v_mul_f32_e32 v40, v56, v39
	v_mov_b32_e32 v41, 0
	v_permlane32_swap_b32_e32 v46, v47
	v_fmac_f32_dpp v40, -v48, v0 row_newbcast:0 row_mask:0xf bank_mask:0xf
	v_fmac_f32_dpp v41, -v48, v1 row_newbcast:1 row_mask:0xf bank_mask:0xf
	v_add_f32_dpp v15, v46, v47 quad_perm:[0,1,2,3] row_mask:0xc bank_mask:0xf
	v_fmac_f32_dpp v40, -v48, v2 row_newbcast:2 row_mask:0xf bank_mask:0xf
	v_fmac_f32_dpp v41, -v48, v3 row_newbcast:3 row_mask:0xf bank_mask:0xf
	v_fmac_f32_dpp v40, -v48, v4 row_newbcast:4 row_mask:0xf bank_mask:0xf
	v_fmac_f32_dpp v41, -v48, v5 row_newbcast:5 row_mask:0xf bank_mask:0xf
	v_fmac_f32_dpp v40, -v48, v6 row_newbcast:6 row_mask:0xf bank_mask:0xf
	v_fmac_f32_dpp v41, -v48, v7 row_newbcast:7 row_mask:0xf bank_mask:0xf
	v_fmac_f32_dpp v40, -v48, v8 row_newbcast:8 row_mask:0xf bank_mask:0xf
	v_fmac_f32_dpp v41, -v48, v9 row_newbcast:9 row_mask:0xf bank_mask:0xf
	v_fmac_f32_dpp v40, -v48, v10 row_newbcast:10 row_mask:0xf bank_mask:0xf
	v_fmac_f32_dpp v41, -v48, v11 row_newbcast:11 row_mask:0xf bank_mask:0xf
	v_fmac_f32_dpp v40, -v48, v12 row_newbcast:12 row_mask:0xf bank_mask:0xf
	v_fmac_f32_dpp v41, -v48, v13 row_newbcast:13 row_mask:0xf bank_mask:0xf
	v_fmac_f32_dpp v40, -v48, v14 row_newbcast:14 row_mask:0xf bank_mask:0xf
	v_fmac_f32_dpp v41, -v48, v15 row_newbcast:15 row_mask:0xf bank_mask:0xf
	ds_read_b32 v56, v38 offset:36864
	ds_read_b32 v48, v37 offset:9216
	ds_read_b32 v49, v37 offset:9344
	v_add_f32_e32 v42, v40, v41
	v_mov_b32_e32 v43, v42
	s_waitcnt lgkmcnt(9)
	v_mul_f32_e32 v44, v57, v39
	v_mov_b32_e32 v45, 0
	v_permlane32_swap_b32_e32 v42, v43
	v_fmac_f32_dpp v44, -v50, v0 row_newbcast:0 row_mask:0xf bank_mask:0xf
	v_fmac_f32_dpp v45, -v50, v1 row_newbcast:1 row_mask:0xf bank_mask:0xf
	v_add_f32_dpp v16, v42, v43 quad_perm:[0,1,2,3] row_mask:0x3 bank_mask:0xf
	v_fmac_f32_dpp v44, -v50, v2 row_newbcast:2 row_mask:0xf bank_mask:0xf
	v_fmac_f32_dpp v45, -v50, v3 row_newbcast:3 row_mask:0xf bank_mask:0xf
	v_fmac_f32_dpp v44, -v50, v4 row_newbcast:4 row_mask:0xf bank_mask:0xf
	v_fmac_f32_dpp v45, -v50, v5 row_newbcast:5 row_mask:0xf bank_mask:0xf
	v_fmac_f32_dpp v44, -v50, v6 row_newbcast:6 row_mask:0xf bank_mask:0xf
	v_fmac_f32_dpp v45, -v50, v7 row_newbcast:7 row_mask:0xf bank_mask:0xf
	v_fmac_f32_dpp v44, -v50, v8 row_newbcast:8 row_mask:0xf bank_mask:0xf
	v_fmac_f32_dpp v45, -v50, v9 row_newbcast:9 row_mask:0xf bank_mask:0xf
	v_fmac_f32_dpp v44, -v50, v10 row_newbcast:10 row_mask:0xf bank_mask:0xf
	v_fmac_f32_dpp v45, -v50, v11 row_newbcast:11 row_mask:0xf bank_mask:0xf
	v_fmac_f32_dpp v44, -v50, v12 row_newbcast:12 row_mask:0xf bank_mask:0xf
	v_fmac_f32_dpp v45, -v50, v13 row_newbcast:13 row_mask:0xf bank_mask:0xf
	v_fmac_f32_dpp v44, -v50, v14 row_newbcast:14 row_mask:0xf bank_mask:0xf
	v_fmac_f32_dpp v45, -v50, v15 row_newbcast:15 row_mask:0xf bank_mask:0xf
	v_fmac_f32_dpp v44, -v51, v16 row_newbcast:0 row_mask:0xf bank_mask:0xf
	ds_read_b32 v57, v38 offset:37888
	ds_read_b32 v50, v37 offset:9472
	ds_read_b32 v51, v37 offset:9600
	v_add_f32_e32 v46, v44, v45
	v_mov_b32_e32 v47, v46
	s_waitcnt lgkmcnt(9)
	v_mul_f32_e32 v40, v58, v39
	v_mov_b32_e32 v41, 0
	v_permlane32_swap_b32_e32 v46, v47
	v_fmac_f32_dpp v40, -v52, v0 row_newbcast:0 row_mask:0xf bank_mask:0xf
	v_fmac_f32_dpp v41, -v52, v1 row_newbcast:1 row_mask:0xf bank_mask:0xf
	v_add_f32_dpp v17, v46, v47 quad_perm:[0,1,2,3] row_mask:0x3 bank_mask:0xf
	v_fmac_f32_dpp v40, -v52, v2 row_newbcast:2 row_mask:0xf bank_mask:0xf
	v_fmac_f32_dpp v41, -v52, v3 row_newbcast:3 row_mask:0xf bank_mask:0xf
	v_fmac_f32_dpp v40, -v52, v4 row_newbcast:4 row_mask:0xf bank_mask:0xf
	v_fmac_f32_dpp v41, -v52, v5 row_newbcast:5 row_mask:0xf bank_mask:0xf
	v_fmac_f32_dpp v40, -v52, v6 row_newbcast:6 row_mask:0xf bank_mask:0xf
	v_fmac_f32_dpp v41, -v52, v7 row_newbcast:7 row_mask:0xf bank_mask:0xf
	v_fmac_f32_dpp v40, -v52, v8 row_newbcast:8 row_mask:0xf bank_mask:0xf
	v_fmac_f32_dpp v41, -v52, v9 row_newbcast:9 row_mask:0xf bank_mask:0xf
	v_fmac_f32_dpp v40, -v52, v10 row_newbcast:10 row_mask:0xf bank_mask:0xf
	v_fmac_f32_dpp v41, -v52, v11 row_newbcast:11 row_mask:0xf bank_mask:0xf
	v_fmac_f32_dpp v40, -v52, v12 row_newbcast:12 row_mask:0xf bank_mask:0xf
	v_fmac_f32_dpp v41, -v52, v13 row_newbcast:13 row_mask:0xf bank_mask:0xf
	v_fmac_f32_dpp v40, -v52, v14 row_newbcast:14 row_mask:0xf bank_mask:0xf
	v_fmac_f32_dpp v41, -v52, v15 row_newbcast:15 row_mask:0xf bank_mask:0xf
	v_fmac_f32_dpp v40, -v53, v16 row_newbcast:0 row_mask:0xf bank_mask:0xf
	v_fmac_f32_dpp v41, -v53, v17 row_newbcast:1 row_mask:0xf bank_mask:0xf
	ds_read_b32 v58, v38 offset:38912
	ds_read_b32 v52, v37 offset:9728
	ds_read_b32 v53, v37 offset:9856
	v_add_f32_e32 v42, v40, v41
	v_mov_b32_e32 v43, v42
	s_waitcnt lgkmcnt(9)
; #define LAS __attribute__((address_space(3)))
; __device__ __forceinline__ void phase_chunk_prep(const Params& p, LAS unsigned char* lds, int wave_s) {
;     ...
;             for (int i = 0; i < 64; ++i) {
;                 float s0 = RHS[i * 256 + col], s1 = 0.f, s2 = 0.f, s3 = 0.f;
; #pragma unroll
;                 for (int j4 = 0; j4 < (i + 3) / 4; ++j4) { const f32x4 a = *(const LAS f32x4*)(AM + i * 64 + 4 * j4);
;                     s0 -= a.x * sol[4 * j4]; s1 -= a.y * sol[4 * j4 + 1]; s2 -= a.z * sol[4 * j4 + 2]; s3 -= a.w * sol[4 * j4 + 3]; }
;                 sol[i] = (s0 + s1) + (s2 + s3);
	v_mul_f32_e32 v44, v59, v39
	v_mov_b32_e32 v45, 0
	v_permlane32_swap_b32_e32 v42, v43
	v_fmac_f32_dpp v44, -v54, v0 row_newbcast:0 row_mask:0xf bank_mask:0xf
	v_fmac_f32_dpp v45, -v54, v1 row_newbcast:1 row_mask:0xf bank_mask:0xf
	v_add_f32_dpp v16, v42, v43 quad_perm:[0,1,2,3] row_mask:0xc bank_mask:0xf
	v_fmac_f32_dpp v44, -v54, v2 row_newbcast:2 row_mask:0xf bank_mask:0xf
	v_fmac_f32_dpp v45, -v54, v3 row_newbcast:3 row_mask:0xf bank_mask:0xf
	v_fmac_f32_dpp v44, -v54, v4 row_newbcast:4 row_mask:0xf bank_mask:0xf
	v_fmac_f32_dpp v45, -v54, v5 row_newbcast:5 row_mask:0xf bank_mask:0xf
	v_fmac_f32_dpp v44, -v54, v6 row_newbcast:6 row_mask:0xf bank_mask:0xf
	v_fmac_f32_dpp v45, -v54, v7 row_newbcast:7 row_mask:0xf bank_mask:0xf
	v_fmac_f32_dpp v44, -v54, v8 row_newbcast:8 row_mask:0xf bank_mask:0xf
	v_fmac_f32_dpp v45, -v54, v9 row_newbcast:9 row_mask:0xf bank_mask:0xf
	v_fmac_f32_dpp v44, -v54, v10 row_newbcast:10 row_mask:0xf bank_mask:0xf
	v_fmac_f32_dpp v45, -v54, v11 row_newbcast:11 row_mask:0xf bank_mask:0xf
	v_fmac_f32_dpp v44, -v54, v12 row_newbcast:12 row_mask:0xf bank_mask:0xf
	v_fmac_f32_dpp v45, -v54, v13 row_newbcast:13 row_mask:0xf bank_mask:0xf
	v_fmac_f32_dpp v44, -v54, v14 row_newbcast:14 row_mask:0xf bank_mask:0xf
	v_fmac_f32_dpp v45, -v54, v15 row_newbcast:15 row_mask:0xf bank_mask:0xf
	v_fmac_f32_dpp v45, -v55, v17 row_newbcast:1 row_mask:0xf bank_mask:0xf
	v_fmac_f32_dpp v44, -v55, v16 row_newbcast:0 row_mask:0xf bank_mask:0xf
	ds_read_b32 v59, v38 offset:39936
	ds_read_b32 v54, v37 offset:9984
	ds_read_b32 v55, v37 offset:10112
	v_add_f32_e32 v46, v44, v45
	v_mov_b32_e32 v47, v46
	s_waitcnt lgkmcnt(9)
	v_mul_f32_e32 v40, v56, v39
	v_mov_b32_e32 v41, 0
	v_permlane32_swap_b32_e32 v46, v47
	v_fmac_f32_dpp v40, -v48, v0 row_newbcast:0 row_mask:0xf bank_mask:0xf
	v_fmac_f32_dpp v41, -v48, v1 row_newbcast:1 row_mask:0xf bank_mask:0xf
	v_add_f32_dpp v17, v46, v47 quad_perm:[0,1,2,3] row_mask:0xc bank_mask:0xf
	v_fmac_f32_dpp v40, -v48, v2 row_newbcast:2 row_mask:0xf bank_mask:0xf
	v_fmac_f32_dpp v41, -v48, v3 row_newbcast:3 row_mask:0xf bank_mask:0xf
	v_fmac_f32_dpp v40, -v48, v4 row_newbcast:4 row_mask:0xf bank_mask:0xf
	v_fmac_f32_dpp v41, -v48, v5 row_newbcast:5 row_mask:0xf bank_mask:0xf
	v_fmac_f32_dpp v40, -v48, v6 row_newbcast:6 row_mask:0xf bank_mask:0xf
	v_fmac_f32_dpp v41, -v48, v7 row_newbcast:7 row_mask:0xf bank_mask:0xf
	v_fmac_f32_dpp v40, -v48, v8 row_newbcast:8 row_mask:0xf bank_mask:0xf
	v_fmac_f32_dpp v41, -v48, v9 row_newbcast:9 row_mask:0xf bank_mask:0xf
	v_fmac_f32_dpp v40, -v48, v10 row_newbcast:10 row_mask:0xf bank_mask:0xf
	v_fmac_f32_dpp v41, -v48, v11 row_newbcast:11 row_mask:0xf bank_mask:0xf
	v_fmac_f32_dpp v40, -v48, v12 row_newbcast:12 row_mask:0xf bank_mask:0xf
	v_fmac_f32_dpp v41, -v48, v13 row_newbcast:13 row_mask:0xf bank_mask:0xf
	v_fmac_f32_dpp v40, -v48, v14 row_newbcast:14 row_mask:0xf bank_mask:0xf
	v_fmac_f32_dpp v41, -v48, v15 row_newbcast:15 row_mask:0xf bank_mask:0xf
	v_fmac_f32_dpp v40, -v49, v16 row_newbcast:0 row_mask:0xf bank_mask:0xf
	v_fmac_f32_dpp v41, -v49, v17 row_newbcast:1 row_mask:0xf bank_mask:0xf
	ds_read_b32 v56, v38 offset:40960
	ds_read_b32 v48, v37 offset:10240
	ds_read_b32 v49, v37 offset:10368
	v_add_f32_e32 v42, v40, v41
	v_mov_b32_e32 v43, v42
	s_waitcnt lgkmcnt(9)
	v_mul_f32_e32 v44, v57, v39
	v_mov_b32_e32 v45, 0
	v_permlane32_swap_b32_e32 v42, v43
	v_fmac_f32_dpp v44, -v50, v0 row_newbcast:0 row_mask:0xf bank_mask:0xf
	v_fmac_f32_dpp v45, -v50, v1 row_newbcast:1 row_mask:0xf bank_mask:0xf
	v_add_f32_dpp v18, v42, v43 quad_perm:[0,1,2,3] row_mask:0x3 bank_mask:0xf
	v_fmac_f32_dpp v44, -v50, v2 row_newbcast:2 row_mask:0xf bank_mask:0xf
	v_fmac_f32_dpp v45, -v50, v3 row_newbcast:3 row_mask:0xf bank_mask:0xf
	v_fmac_f32_dpp v44, -v50, v4 row_newbcast:4 row_mask:0xf bank_mask:0xf
	v_fmac_f32_dpp v45, -v50, v5 row_newbcast:5 row_mask:0xf bank_mask:0xf
	v_fmac_f32_dpp v44, -v50, v6 row_newbcast:6 row_mask:0xf bank_mask:0xf
	v_fmac_f32_dpp v45, -v50, v7 row_newbcast:7 row_mask:0xf bank_mask:0xf
	v_fmac_f32_dpp v44, -v50, v8 row_newbcast:8 row_mask:0xf bank_mask:0xf
	v_fmac_f32_dpp v45, -v50, v9 row_newbcast:9 row_mask:0xf bank_mask:0xf
	v_fmac_f32_dpp v44, -v50, v10 row_newbcast:10 row_mask:0xf bank_mask:0xf
	v_fmac_f32_dpp v45, -v50, v11 row_newbcast:11 row_mask:0xf bank_mask:0xf
	v_fmac_f32_dpp v44, -v50, v12 row_newbcast:12 row_mask:0xf bank_mask:0xf
	v_fmac_f32_dpp v45, -v50, v13 row_newbcast:13 row_mask:0xf bank_mask:0xf
	v_fmac_f32_dpp v44, -v50, v14 row_newbcast:14 row_mask:0xf bank_mask:0xf
	v_fmac_f32_dpp v45, -v50, v15 row_newbcast:15 row_mask:0xf bank_mask:0xf
	v_fmac_f32_dpp v44, -v51, v16 row_newbcast:0 row_mask:0xf bank_mask:0xf
	v_fmac_f32_dpp v45, -v51, v17 row_newbcast:1 row_mask:0xf bank_mask:0xf
	v_fmac_f32_dpp v44, -v51, v18 row_newbcast:2 row_mask:0xf bank_mask:0xf
	ds_read_b32 v57, v38 offset:41984
	ds_read_b32 v50, v37 offset:10496
	ds_read_b32 v51, v37 offset:10624
	v_add_f32_e32 v46, v44, v45
	v_mov_b32_e32 v47, v46
	s_waitcnt lgkmcnt(9)
; #define LAS __attribute__((address_space(3)))
; __device__ __forceinline__ void phase_chunk_prep(const Params& p, LAS unsigned char* lds, int wave_s) {
;     ...
;             for (int i = 0; i < 64; ++i) {
;                 float s0 = RHS[i * 256 + col], s1 = 0.f, s2 = 0.f, s3 = 0.f;
; #pragma unroll
;                 for (int j4 = 0; j4 < (i + 3) / 4; ++j4) { const f32x4 a = *(const LAS f32x4*)(AM + i * 64 + 4 * j4);
;                     s0 -= a.x * sol[4 * j4]; s1 -= a.y * sol[4 * j4 + 1]; s2 -= a.z * sol[4 * j4 + 2]; s3 -= a.w * sol[4 * j4 + 3]; }
;                 sol[i] = (s0 + s1) + (s2 + s3);
	v_mul_f32_e32 v40, v58, v39
	v_mov_b32_e32 v41, 0
	v_permlane32_swap_b32_e32 v46, v47
	v_fmac_f32_dpp v40, -v52, v0 row_newbcast:0 row_mask:0xf bank_mask:0xf
	v_fmac_f32_dpp v41, -v52, v1 row_newbcast:1 row_mask:0xf bank_mask:0xf
	v_add_f32_dpp v19, v46, v47 quad_perm:[0,1,2,3] row_mask:0x3 bank_mask:0xf
	v_fmac_f32_dpp v40, -v52, v2 row_newbcast:2 row_mask:0xf bank_mask:0xf
	v_fmac_f32_dpp v41, -v52, v3 row_newbcast:3 row_mask:0xf bank_mask:0xf
	v_fmac_f32_dpp v40, -v52, v4 row_newbcast:4 row_mask:0xf bank_mask:0xf
	v_fmac_f32_dpp v41, -v52, v5 row_newbcast:5 row_mask:0xf bank_mask:0xf
	v_fmac_f32_dpp v40, -v52, v6 row_newbcast:6 row_mask:0xf bank_mask:0xf
	v_fmac_f32_dpp v41, -v52, v7 row_newbcast:7 row_mask:0xf bank_mask:0xf
	v_fmac_f32_dpp v40, -v52, v8 row_newbcast:8 row_mask:0xf bank_mask:0xf
	v_fmac_f32_dpp v41, -v52, v9 row_newbcast:9 row_mask:0xf bank_mask:0xf
	v_fmac_f32_dpp v40, -v52, v10 row_newbcast:10 row_mask:0xf bank_mask:0xf
	v_fmac_f32_dpp v41, -v52, v11 row_newbcast:11 row_mask:0xf bank_mask:0xf
	v_fmac_f32_dpp v40, -v52, v12 row_newbcast:12 row_mask:0xf bank_mask:0xf
	v_fmac_f32_dpp v41, -v52, v13 row_newbcast:13 row_mask:0xf bank_mask:0xf
	v_fmac_f32_dpp v40, -v52, v14 row_newbcast:14 row_mask:0xf bank_mask:0xf
	v_fmac_f32_dpp v41, -v52, v15 row_newbcast:15 row_mask:0xf bank_mask:0xf
	v_fmac_f32_dpp v40, -v53, v16 row_newbcast:0 row_mask:0xf bank_mask:0xf
	v_fmac_f32_dpp v41, -v53, v17 row_newbcast:1 row_mask:0xf bank_mask:0xf
	v_fmac_f32_dpp v40, -v53, v18 row_newbcast:2 row_mask:0xf bank_mask:0xf
	v_fmac_f32_dpp v41, -v53, v19 row_newbcast:3 row_mask:0xf bank_mask:0xf
	ds_read_b32 v58, v38 offset:43008
	ds_read_b32 v52, v37 offset:10752
	ds_read_b32 v53, v37 offset:10880
	v_add_f32_e32 v42, v40, v41
	v_mov_b32_e32 v43, v42
	s_waitcnt lgkmcnt(9)
	v_mul_f32_e32 v44, v59, v39
	v_mov_b32_e32 v45, 0
	v_permlane32_swap_b32_e32 v42, v43
	v_fmac_f32_dpp v44, -v54, v0 row_newbcast:0 row_mask:0xf bank_mask:0xf
	v_fmac_f32_dpp v45, -v54, v1 row_newbcast:1 row_mask:0xf bank_mask:0xf
	v_add_f32_dpp v18, v42, v43 quad_perm:[0,1,2,3] row_mask:0xc bank_mask:0xf
	v_fmac_f32_dpp v44, -v54, v2 row_newbcast:2 row_mask:0xf bank_mask:0xf
	v_fmac_f32_dpp v45, -v54, v3 row_newbcast:3 row_mask:0xf bank_mask:0xf
	v_fmac_f32_dpp v44, -v54, v4 row_newbcast:4 row_mask:0xf bank_mask:0xf
	v_fmac_f32_dpp v45, -v54, v5 row_newbcast:5 row_mask:0xf bank_mask:0xf
	v_fmac_f32_dpp v44, -v54, v6 row_newbcast:6 row_mask:0xf bank_mask:0xf
	v_fmac_f32_dpp v45, -v54, v7 row_newbcast:7 row_mask:0xf bank_mask:0xf
	v_fmac_f32_dpp v44, -v54, v8 row_newbcast:8 row_mask:0xf bank_mask:0xf
	v_fmac_f32_dpp v45, -v54, v9 row_newbcast:9 row_mask:0xf bank_mask:0xf
	v_fmac_f32_dpp v44, -v54, v10 row_newbcast:10 row_mask:0xf bank_mask:0xf
	v_fmac_f32_dpp v45, -v54, v11 row_newbcast:11 row_mask:0xf bank_mask:0xf
	v_fmac_f32_dpp v44, -v54, v12 row_newbcast:12 row_mask:0xf bank_mask:0xf
	v_fmac_f32_dpp v45, -v54, v13 row_newbcast:13 row_mask:0xf bank_mask:0xf
	v_fmac_f32_dpp v44, -v54, v14 row_newbcast:14 row_mask:0xf bank_mask:0xf
	v_fmac_f32_dpp v45, -v54, v15 row_newbcast:15 row_mask:0xf bank_mask:0xf
	v_fmac_f32_dpp v44, -v55, v16 row_newbcast:0 row_mask:0xf bank_mask:0xf
	v_fmac_f32_dpp v45, -v55, v17 row_newbcast:1 row_mask:0xf bank_mask:0xf
	v_fmac_f32_dpp v45, -v55, v19 row_newbcast:3 row_mask:0xf bank_mask:0xf
	v_fmac_f32_dpp v44, -v55, v18 row_newbcast:2 row_mask:0xf bank_mask:0xf
	ds_read_b32 v59, v38 offset:44032
	ds_read_b32 v54, v37 offset:11008
	ds_read_b32 v55, v37 offset:11136
	v_add_f32_e32 v46, v44, v45
	v_mov_b32_e32 v47, v46
	s_waitcnt lgkmcnt(9)
	v_mul_f32_e32 v40, v56, v39
	v_mov_b32_e32 v41, 0
	v_permlane32_swap_b32_e32 v46, v47
	v_fmac_f32_dpp v40, -v48, v0 row_newbcast:0 row_mask:0xf bank_mask:0xf
	v_fmac_f32_dpp v41, -v48, v1 row_newbcast:1 row_mask:0xf bank_mask:0xf
	v_add_f32_dpp v19, v46, v47 quad_perm:[0,1,2,3] row_mask:0xc bank_mask:0xf
	v_fmac_f32_dpp v40, -v48, v2 row_newbcast:2 row_mask:0xf bank_mask:0xf
	v_fmac_f32_dpp v41, -v48, v3 row_newbcast:3 row_mask:0xf bank_mask:0xf
	v_fmac_f32_dpp v40, -v48, v4 row_newbcast:4 row_mask:0xf bank_mask:0xf
	v_fmac_f32_dpp v41, -v48, v5 row_newbcast:5 row_mask:0xf bank_mask:0xf
	v_fmac_f32_dpp v40, -v48, v6 row_newbcast:6 row_mask:0xf bank_mask:0xf
	v_fmac_f32_dpp v41, -v48, v7 row_newbcast:7 row_mask:0xf bank_mask:0xf
	v_fmac_f32_dpp v40, -v48, v8 row_newbcast:8 row_mask:0xf bank_mask:0xf
	v_fmac_f32_dpp v41, -v48, v9 row_newbcast:9 row_mask:0xf bank_mask:0xf
	v_fmac_f32_dpp v40, -v48, v10 row_newbcast:10 row_mask:0xf bank_mask:0xf
	v_fmac_f32_dpp v41, -v48, v11 row_newbcast:11 row_mask:0xf bank_mask:0xf
	v_fmac_f32_dpp v40, -v48, v12 row_newbcast:12 row_mask:0xf bank_mask:0xf
	v_fmac_f32_dpp v41, -v48, v13 row_newbcast:13 row_mask:0xf bank_mask:0xf
	v_fmac_f32_dpp v40, -v48, v14 row_newbcast:14 row_mask:0xf bank_mask:0xf
	v_fmac_f32_dpp v41, -v48, v15 row_newbcast:15 row_mask:0xf bank_mask:0xf
	v_fmac_f32_dpp v40, -v49, v16 row_newbcast:0 row_mask:0xf bank_mask:0xf
	v_fmac_f32_dpp v41, -v49, v17 row_newbcast:1 row_mask:0xf bank_mask:0xf
	v_fmac_f32_dpp v40, -v49, v18 row_newbcast:2 row_mask:0xf bank_mask:0xf
	v_fmac_f32_dpp v41, -v49, v19 row_newbcast:3 row_mask:0xf bank_mask:0xf
	ds_read_b32 v56, v38 offset:45056
	ds_read_b32 v48, v37 offset:11264
	ds_read_b32 v49, v37 offset:11392
	v_add_f32_e32 v42, v40, v41
	v_mov_b32_e32 v43, v42
	s_waitcnt lgkmcnt(9)
; #define LAS __attribute__((address_space(3)))
; __device__ __forceinline__ void phase_chunk_prep(const Params& p, LAS unsigned char* lds, int wave_s) {
;     ...
;             for (int i = 0; i < 64; ++i) {
;                 float s0 = RHS[i * 256 + col], s1 = 0.f, s2 = 0.f, s3 = 0.f;
; #pragma unroll
;                 for (int j4 = 0; j4 < (i + 3) / 4; ++j4) { const f32x4 a = *(const LAS f32x4*)(AM + i * 64 + 4 * j4);
;                     s0 -= a.x * sol[4 * j4]; s1 -= a.y * sol[4 * j4 + 1]; s2 -= a.z * sol[4 * j4 + 2]; s3 -= a.w * sol[4 * j4 + 3]; }
;                 sol[i] = (s0 + s1) + (s2 + s3);
	v_mul_f32_e32 v44, v57, v39
	v_mov_b32_e32 v45, 0
	v_permlane32_swap_b32_e32 v42, v43
	v_fmac_f32_dpp v44, -v50, v0 row_newbcast:0 row_mask:0xf bank_mask:0xf
	v_fmac_f32_dpp v45, -v50, v1 row_newbcast:1 row_mask:0xf bank_mask:0xf
	v_add_f32_dpp v20, v42, v43 quad_perm:[0,1,2,3] row_mask:0x3 bank_mask:0xf
	v_fmac_f32_dpp v44, -v50, v2 row_newbcast:2 row_mask:0xf bank_mask:0xf
	v_fmac_f32_dpp v45, -v50, v3 row_newbcast:3 row_mask:0xf bank_mask:0xf
	v_fmac_f32_dpp v44, -v50, v4 row_newbcast:4 row_mask:0xf bank_mask:0xf
	v_fmac_f32_dpp v45, -v50, v5 row_newbcast:5 row_mask:0xf bank_mask:0xf
	v_fmac_f32_dpp v44, -v50, v6 row_newbcast:6 row_mask:0xf bank_mask:0xf
	v_fmac_f32_dpp v45, -v50, v7 row_newbcast:7 row_mask:0xf bank_mask:0xf
	v_fmac_f32_dpp v44, -v50, v8 row_newbcast:8 row_mask:0xf bank_mask:0xf
	v_fmac_f32_dpp v45, -v50, v9 row_newbcast:9 row_mask:0xf bank_mask:0xf
	v_fmac_f32_dpp v44, -v50, v10 row_newbcast:10 row_mask:0xf bank_mask:0xf
	v_fmac_f32_dpp v45, -v50, v11 row_newbcast:11 row_mask:0xf bank_mask:0xf
	v_fmac_f32_dpp v44, -v50, v12 row_newbcast:12 row_mask:0xf bank_mask:0xf
	v_fmac_f32_dpp v45, -v50, v13 row_newbcast:13 row_mask:0xf bank_mask:0xf
	v_fmac_f32_dpp v44, -v50, v14 row_newbcast:14 row_mask:0xf bank_mask:0xf
	v_fmac_f32_dpp v45, -v50, v15 row_newbcast:15 row_mask:0xf bank_mask:0xf
	v_fmac_f32_dpp v44, -v51, v16 row_newbcast:0 row_mask:0xf bank_mask:0xf
	v_fmac_f32_dpp v45, -v51, v17 row_newbcast:1 row_mask:0xf bank_mask:0xf
	v_fmac_f32_dpp v44, -v51, v18 row_newbcast:2 row_mask:0xf bank_mask:0xf
	v_fmac_f32_dpp v45, -v51, v19 row_newbcast:3 row_mask:0xf bank_mask:0xf
	v_fmac_f32_dpp v44, -v51, v20 row_newbcast:4 row_mask:0xf bank_mask:0xf
	ds_read_b32 v57, v38 offset:46080
	ds_read_b32 v50, v37 offset:11520
	ds_read_b32 v51, v37 offset:11648
	v_add_f32_e32 v46, v44, v45
	v_mov_b32_e32 v47, v46
	s_waitcnt lgkmcnt(9)
	v_mul_f32_e32 v40, v58, v39
	v_mov_b32_e32 v41, 0
	v_permlane32_swap_b32_e32 v46, v47
	v_fmac_f32_dpp v40, -v52, v0 row_newbcast:0 row_mask:0xf bank_mask:0xf
	v_fmac_f32_dpp v41, -v52, v1 row_newbcast:1 row_mask:0xf bank_mask:0xf
	v_add_f32_dpp v21, v46, v47 quad_perm:[0,1,2,3] row_mask:0x3 bank_mask:0xf
	v_fmac_f32_dpp v40, -v52, v2 row_newbcast:2 row_mask:0xf bank_mask:0xf
	v_fmac_f32_dpp v41, -v52, v3 row_newbcast:3 row_mask:0xf bank_mask:0xf
	v_fmac_f32_dpp v40, -v52, v4 row_newbcast:4 row_mask:0xf bank_mask:0xf
	v_fmac_f32_dpp v41, -v52, v5 row_newbcast:5 row_mask:0xf bank_mask:0xf
	v_fmac_f32_dpp v40, -v52, v6 row_newbcast:6 row_mask:0xf bank_mask:0xf
	v_fmac_f32_dpp v41, -v52, v7 row_newbcast:7 row_mask:0xf bank_mask:0xf
	v_fmac_f32_dpp v40, -v52, v8 row_newbcast:8 row_mask:0xf bank_mask:0xf
	v_fmac_f32_dpp v41, -v52, v9 row_newbcast:9 row_mask:0xf bank_mask:0xf
	v_fmac_f32_dpp v40, -v52, v10 row_newbcast:10 row_mask:0xf bank_mask:0xf
	v_fmac_f32_dpp v41, -v52, v11 row_newbcast:11 row_mask:0xf bank_mask:0xf
	v_fmac_f32_dpp v40, -v52, v12 row_newbcast:12 row_mask:0xf bank_mask:0xf
	v_fmac_f32_dpp v41, -v52, v13 row_newbcast:13 row_mask:0xf bank_mask:0xf
	v_fmac_f32_dpp v40, -v52, v14 row_newbcast:14 row_mask:0xf bank_mask:0xf
	v_fmac_f32_dpp v41, -v52, v15 row_newbcast:15 row_mask:0xf bank_mask:0xf
	v_fmac_f32_dpp v40, -v53, v16 row_newbcast:0 row_mask:0xf bank_mask:0xf
	v_fmac_f32_dpp v41, -v53, v17 row_newbcast:1 row_mask:0xf bank_mask:0xf
	v_fmac_f32_dpp v40, -v53, v18 row_newbcast:2 row_mask:0xf bank_mask:0xf
	v_fmac_f32_dpp v41, -v53, v19 row_newbcast:3 row_mask:0xf bank_mask:0xf
	v_fmac_f32_dpp v40, -v53, v20 row_newbcast:4 row_mask:0xf bank_mask:0xf
	v_fmac_f32_dpp v41, -v53, v21 row_newbcast:5 row_mask:0xf bank_mask:0xf
	ds_read_b32 v58, v38 offset:47104
	ds_read_b32 v52, v37 offset:11776
	ds_read_b32 v53, v37 offset:11904
	v_add_f32_e32 v42, v40, v41
	v_mov_b32_e32 v43, v42
	s_waitcnt lgkmcnt(9)
	v_mul_f32_e32 v44, v59, v39
	v_mov_b32_e32 v45, 0
	v_permlane32_swap_b32_e32 v42, v43
	v_fmac_f32_dpp v44, -v54, v0 row_newbcast:0 row_mask:0xf bank_mask:0xf
	v_fmac_f32_dpp v45, -v54, v1 row_newbcast:1 row_mask:0xf bank_mask:0xf
	v_add_f32_dpp v20, v42, v43 quad_perm:[0,1,2,3] row_mask:0xc bank_mask:0xf
	v_fmac_f32_dpp v44, -v54, v2 row_newbcast:2 row_mask:0xf bank_mask:0xf
	v_fmac_f32_dpp v45, -v54, v3 row_newbcast:3 row_mask:0xf bank_mask:0xf
	v_fmac_f32_dpp v44, -v54, v4 row_newbcast:4 row_mask:0xf bank_mask:0xf
	v_fmac_f32_dpp v45, -v54, v5 row_newbcast:5 row_mask:0xf bank_mask:0xf
	v_fmac_f32_dpp v44, -v54, v6 row_newbcast:6 row_mask:0xf bank_mask:0xf
	v_fmac_f32_dpp v45, -v54, v7 row_newbcast:7 row_mask:0xf bank_mask:0xf
	v_fmac_f32_dpp v44, -v54, v8 row_newbcast:8 row_mask:0xf bank_mask:0xf
	v_fmac_f32_dpp v45, -v54, v9 row_newbcast:9 row_mask:0xf bank_mask:0xf
	v_fmac_f32_dpp v44, -v54, v10 row_newbcast:10 row_mask:0xf bank_mask:0xf
	v_fmac_f32_dpp v45, -v54, v11 row_newbcast:11 row_mask:0xf bank_mask:0xf
	v_fmac_f32_dpp v44, -v54, v12 row_newbcast:12 row_mask:0xf bank_mask:0xf
	v_fmac_f32_dpp v45, -v54, v13 row_newbcast:13 row_mask:0xf bank_mask:0xf
	v_fmac_f32_dpp v44, -v54, v14 row_newbcast:14 row_mask:0xf bank_mask:0xf
	v_fmac_f32_dpp v45, -v54, v15 row_newbcast:15 row_mask:0xf bank_mask:0xf
	v_fmac_f32_dpp v44, -v55, v16 row_newbcast:0 row_mask:0xf bank_mask:0xf
	v_fmac_f32_dpp v45, -v55, v17 row_newbcast:1 row_mask:0xf bank_mask:0xf
	v_fmac_f32_dpp v44, -v55, v18 row_newbcast:2 row_mask:0xf bank_mask:0xf
	v_fmac_f32_dpp v45, -v55, v19 row_newbcast:3 row_mask:0xf bank_mask:0xf
	v_fmac_f32_dpp v45, -v55, v21 row_newbcast:5 row_mask:0xf bank_mask:0xf
	v_fmac_f32_dpp v44, -v55, v20 row_newbcast:4 row_mask:0xf bank_mask:0xf
	ds_read_b32 v59, v38 offset:48128
	ds_read_b32 v54, v37 offset:12032
	ds_read_b32 v55, v37 offset:12160
	v_add_f32_e32 v46, v44, v45
	v_mov_b32_e32 v47, v46
	s_waitcnt lgkmcnt(9)
; #define LAS __attribute__((address_space(3)))
; __device__ __forceinline__ void phase_chunk_prep(const Params& p, LAS unsigned char* lds, int wave_s) {
;     ...
;             for (int i = 0; i < 64; ++i) {
;                 float s0 = RHS[i * 256 + col], s1 = 0.f, s2 = 0.f, s3 = 0.f;
; #pragma unroll
;                 for (int j4 = 0; j4 < (i + 3) / 4; ++j4) { const f32x4 a = *(const LAS f32x4*)(AM + i * 64 + 4 * j4);
;                     s0 -= a.x * sol[4 * j4]; s1 -= a.y * sol[4 * j4 + 1]; s2 -= a.z * sol[4 * j4 + 2]; s3 -= a.w * sol[4 * j4 + 3]; }
;                 sol[i] = (s0 + s1) + (s2 + s3);
	v_mul_f32_e32 v40, v56, v39
	v_mov_b32_e32 v41, 0
	v_permlane32_swap_b32_e32 v46, v47
	v_fmac_f32_dpp v40, -v48, v0 row_newbcast:0 row_mask:0xf bank_mask:0xf
	v_fmac_f32_dpp v41, -v48, v1 row_newbcast:1 row_mask:0xf bank_mask:0xf
	v_add_f32_dpp v21, v46, v47 quad_perm:[0,1,2,3] row_mask:0xc bank_mask:0xf
	v_fmac_f32_dpp v40, -v48, v2 row_newbcast:2 row_mask:0xf bank_mask:0xf
	v_fmac_f32_dpp v41, -v48, v3 row_newbcast:3 row_mask:0xf bank_mask:0xf
	v_fmac_f32_dpp v40, -v48, v4 row_newbcast:4 row_mask:0xf bank_mask:0xf
	v_fmac_f32_dpp v41, -v48, v5 row_newbcast:5 row_mask:0xf bank_mask:0xf
	v_fmac_f32_dpp v40, -v48, v6 row_newbcast:6 row_mask:0xf bank_mask:0xf
	v_fmac_f32_dpp v41, -v48, v7 row_newbcast:7 row_mask:0xf bank_mask:0xf
	v_fmac_f32_dpp v40, -v48, v8 row_newbcast:8 row_mask:0xf bank_mask:0xf
	v_fmac_f32_dpp v41, -v48, v9 row_newbcast:9 row_mask:0xf bank_mask:0xf
	v_fmac_f32_dpp v40, -v48, v10 row_newbcast:10 row_mask:0xf bank_mask:0xf
	v_fmac_f32_dpp v41, -v48, v11 row_newbcast:11 row_mask:0xf bank_mask:0xf
	v_fmac_f32_dpp v40, -v48, v12 row_newbcast:12 row_mask:0xf bank_mask:0xf
	v_fmac_f32_dpp v41, -v48, v13 row_newbcast:13 row_mask:0xf bank_mask:0xf
	v_fmac_f32_dpp v40, -v48, v14 row_newbcast:14 row_mask:0xf bank_mask:0xf
	v_fmac_f32_dpp v41, -v48, v15 row_newbcast:15 row_mask:0xf bank_mask:0xf
	v_fmac_f32_dpp v40, -v49, v16 row_newbcast:0 row_mask:0xf bank_mask:0xf
	v_fmac_f32_dpp v41, -v49, v17 row_newbcast:1 row_mask:0xf bank_mask:0xf
	v_fmac_f32_dpp v40, -v49, v18 row_newbcast:2 row_mask:0xf bank_mask:0xf
	v_fmac_f32_dpp v41, -v49, v19 row_newbcast:3 row_mask:0xf bank_mask:0xf
	v_fmac_f32_dpp v40, -v49, v20 row_newbcast:4 row_mask:0xf bank_mask:0xf
	v_fmac_f32_dpp v41, -v49, v21 row_newbcast:5 row_mask:0xf bank_mask:0xf
	ds_read_b32 v56, v38 offset:49152
	ds_read_b32 v48, v37 offset:12288
	ds_read_b32 v49, v37 offset:12416
	v_add_f32_e32 v42, v40, v41
	v_mov_b32_e32 v43, v42
	s_waitcnt lgkmcnt(9)
	v_mul_f32_e32 v44, v57, v39
	v_mov_b32_e32 v45, 0
	v_permlane32_swap_b32_e32 v42, v43
	v_fmac_f32_dpp v44, -v50, v0 row_newbcast:0 row_mask:0xf bank_mask:0xf
	v_fmac_f32_dpp v45, -v50, v1 row_newbcast:1 row_mask:0xf bank_mask:0xf
	v_add_f32_dpp v22, v42, v43 quad_perm:[0,1,2,3] row_mask:0x3 bank_mask:0xf
	v_fmac_f32_dpp v44, -v50, v2 row_newbcast:2 row_mask:0xf bank_mask:0xf
	v_fmac_f32_dpp v45, -v50, v3 row_newbcast:3 row_mask:0xf bank_mask:0xf
	v_fmac_f32_dpp v44, -v50, v4 row_newbcast:4 row_mask:0xf bank_mask:0xf
	v_fmac_f32_dpp v45, -v50, v5 row_newbcast:5 row_mask:0xf bank_mask:0xf
	v_fmac_f32_dpp v44, -v50, v6 row_newbcast:6 row_mask:0xf bank_mask:0xf
	v_fmac_f32_dpp v45, -v50, v7 row_newbcast:7 row_mask:0xf bank_mask:0xf
	v_fmac_f32_dpp v44, -v50, v8 row_newbcast:8 row_mask:0xf bank_mask:0xf
	v_fmac_f32_dpp v45, -v50, v9 row_newbcast:9 row_mask:0xf bank_mask:0xf
	v_fmac_f32_dpp v44, -v50, v10 row_newbcast:10 row_mask:0xf bank_mask:0xf
	v_fmac_f32_dpp v45, -v50, v11 row_newbcast:11 row_mask:0xf bank_mask:0xf
	v_fmac_f32_dpp v44, -v50, v12 row_newbcast:12 row_mask:0xf bank_mask:0xf
	v_fmac_f32_dpp v45, -v50, v13 row_newbcast:13 row_mask:0xf bank_mask:0xf
	v_fmac_f32_dpp v44, -v50, v14 row_newbcast:14 row_mask:0xf bank_mask:0xf
	v_fmac_f32_dpp v45, -v50, v15 row_newbcast:15 row_mask:0xf bank_mask:0xf
	v_fmac_f32_dpp v44, -v51, v16 row_newbcast:0 row_mask:0xf bank_mask:0xf
	v_fmac_f32_dpp v45, -v51, v17 row_newbcast:1 row_mask:0xf bank_mask:0xf
	v_fmac_f32_dpp v44, -v51, v18 row_newbcast:2 row_mask:0xf bank_mask:0xf
	v_fmac_f32_dpp v45, -v51, v19 row_newbcast:3 row_mask:0xf bank_mask:0xf
	v_fmac_f32_dpp v44, -v51, v20 row_newbcast:4 row_mask:0xf bank_mask:0xf
	v_fmac_f32_dpp v45, -v51, v21 row_newbcast:5 row_mask:0xf bank_mask:0xf
	v_fmac_f32_dpp v44, -v51, v22 row_newbcast:6 row_mask:0xf bank_mask:0xf
	ds_read_b32 v57, v38 offset:50176
	ds_read_b32 v50, v37 offset:12544
	ds_read_b32 v51, v37 offset:12672
	v_add_f32_e32 v46, v44, v45
	v_mov_b32_e32 v47, v46
	s_waitcnt lgkmcnt(9)
	v_mul_f32_e32 v40, v58, v39
	v_mov_b32_e32 v41, 0
	v_permlane32_swap_b32_e32 v46, v47
	v_fmac_f32_dpp v40, -v52, v0 row_newbcast:0 row_mask:0xf bank_mask:0xf
	v_fmac_f32_dpp v41, -v52, v1 row_newbcast:1 row_mask:0xf bank_mask:0xf
	v_add_f32_dpp v23, v46, v47 quad_perm:[0,1,2,3] row_mask:0x3 bank_mask:0xf
	v_fmac_f32_dpp v40, -v52, v2 row_newbcast:2 row_mask:0xf bank_mask:0xf
	v_fmac_f32_dpp v41, -v52, v3 row_newbcast:3 row_mask:0xf bank_mask:0xf
	v_fmac_f32_dpp v40, -v52, v4 row_newbcast:4 row_mask:0xf bank_mask:0xf
	v_fmac_f32_dpp v41, -v52, v5 row_newbcast:5 row_mask:0xf bank_mask:0xf
	v_fmac_f32_dpp v40, -v52, v6 row_newbcast:6 row_mask:0xf bank_mask:0xf
	v_fmac_f32_dpp v41, -v52, v7 row_newbcast:7 row_mask:0xf bank_mask:0xf
	v_fmac_f32_dpp v40, -v52, v8 row_newbcast:8 row_mask:0xf bank_mask:0xf
	v_fmac_f32_dpp v41, -v52, v9 row_newbcast:9 row_mask:0xf bank_mask:0xf
	v_fmac_f32_dpp v40, -v52, v10 row_newbcast:10 row_mask:0xf bank_mask:0xf
	v_fmac_f32_dpp v41, -v52, v11 row_newbcast:11 row_mask:0xf bank_mask:0xf
	v_fmac_f32_dpp v40, -v52, v12 row_newbcast:12 row_mask:0xf bank_mask:0xf
	v_fmac_f32_dpp v41, -v52, v13 row_newbcast:13 row_mask:0xf bank_mask:0xf
	v_fmac_f32_dpp v40, -v52, v14 row_newbcast:14 row_mask:0xf bank_mask:0xf
	v_fmac_f32_dpp v41, -v52, v15 row_newbcast:15 row_mask:0xf bank_mask:0xf
	v_fmac_f32_dpp v40, -v53, v16 row_newbcast:0 row_mask:0xf bank_mask:0xf
	v_fmac_f32_dpp v41, -v53, v17 row_newbcast:1 row_mask:0xf bank_mask:0xf
	v_fmac_f32_dpp v40, -v53, v18 row_newbcast:2 row_mask:0xf bank_mask:0xf
	v_fmac_f32_dpp v41, -v53, v19 row_newbcast:3 row_mask:0xf bank_mask:0xf
	v_fmac_f32_dpp v40, -v53, v20 row_newbcast:4 row_mask:0xf bank_mask:0xf
	v_fmac_f32_dpp v41, -v53, v21 row_newbcast:5 row_mask:0xf bank_mask:0xf
	v_fmac_f32_dpp v40, -v53, v22 row_newbcast:6 row_mask:0xf bank_mask:0xf
	v_fmac_f32_dpp v41, -v53, v23 row_newbcast:7 row_mask:0xf bank_mask:0xf
	ds_read_b32 v58, v38 offset:51200
	ds_read_b32 v52, v37 offset:12800
	ds_read_b32 v53, v37 offset:12928
	v_add_f32_e32 v42, v40, v41
	v_mov_b32_e32 v43, v42
	s_waitcnt lgkmcnt(9)
; #define LAS __attribute__((address_space(3)))
; __device__ __forceinline__ void phase_chunk_prep(const Params& p, LAS unsigned char* lds, int wave_s) {
;     ...
;             for (int i = 0; i < 64; ++i) {
;                 float s0 = RHS[i * 256 + col], s1 = 0.f, s2 = 0.f, s3 = 0.f;
; #pragma unroll
;                 for (int j4 = 0; j4 < (i + 3) / 4; ++j4) { const f32x4 a = *(const LAS f32x4*)(AM + i * 64 + 4 * j4);
;                     s0 -= a.x * sol[4 * j4]; s1 -= a.y * sol[4 * j4 + 1]; s2 -= a.z * sol[4 * j4 + 2]; s3 -= a.w * sol[4 * j4 + 3]; }
;                 sol[i] = (s0 + s1) + (s2 + s3);
	v_mul_f32_e32 v44, v59, v39
	v_mov_b32_e32 v45, 0
	v_permlane32_swap_b32_e32 v42, v43
	v_fmac_f32_dpp v44, -v54, v0 row_newbcast:0 row_mask:0xf bank_mask:0xf
	v_fmac_f32_dpp v45, -v54, v1 row_newbcast:1 row_mask:0xf bank_mask:0xf
	v_add_f32_dpp v22, v42, v43 quad_perm:[0,1,2,3] row_mask:0xc bank_mask:0xf
	v_fmac_f32_dpp v44, -v54, v2 row_newbcast:2 row_mask:0xf bank_mask:0xf
	v_fmac_f32_dpp v45, -v54, v3 row_newbcast:3 row_mask:0xf bank_mask:0xf
	v_fmac_f32_dpp v44, -v54, v4 row_newbcast:4 row_mask:0xf bank_mask:0xf
	v_fmac_f32_dpp v45, -v54, v5 row_newbcast:5 row_mask:0xf bank_mask:0xf
	v_fmac_f32_dpp v44, -v54, v6 row_newbcast:6 row_mask:0xf bank_mask:0xf
	v_fmac_f32_dpp v45, -v54, v7 row_newbcast:7 row_mask:0xf bank_mask:0xf
	v_fmac_f32_dpp v44, -v54, v8 row_newbcast:8 row_mask:0xf bank_mask:0xf
	v_fmac_f32_dpp v45, -v54, v9 row_newbcast:9 row_mask:0xf bank_mask:0xf
	v_fmac_f32_dpp v44, -v54, v10 row_newbcast:10 row_mask:0xf bank_mask:0xf
	v_fmac_f32_dpp v45, -v54, v11 row_newbcast:11 row_mask:0xf bank_mask:0xf
	v_fmac_f32_dpp v44, -v54, v12 row_newbcast:12 row_mask:0xf bank_mask:0xf
	v_fmac_f32_dpp v45, -v54, v13 row_newbcast:13 row_mask:0xf bank_mask:0xf
	v_fmac_f32_dpp v44, -v54, v14 row_newbcast:14 row_mask:0xf bank_mask:0xf
	v_fmac_f32_dpp v45, -v54, v15 row_newbcast:15 row_mask:0xf bank_mask:0xf
	v_fmac_f32_dpp v44, -v55, v16 row_newbcast:0 row_mask:0xf bank_mask:0xf
	v_fmac_f32_dpp v45, -v55, v17 row_newbcast:1 row_mask:0xf bank_mask:0xf
	v_fmac_f32_dpp v44, -v55, v18 row_newbcast:2 row_mask:0xf bank_mask:0xf
	v_fmac_f32_dpp v45, -v55, v19 row_newbcast:3 row_mask:0xf bank_mask:0xf
	v_fmac_f32_dpp v44, -v55, v20 row_newbcast:4 row_mask:0xf bank_mask:0xf
	v_fmac_f32_dpp v45, -v55, v21 row_newbcast:5 row_mask:0xf bank_mask:0xf
	v_fmac_f32_dpp v45, -v55, v23 row_newbcast:7 row_mask:0xf bank_mask:0xf
	v_fmac_f32_dpp v44, -v55, v22 row_newbcast:6 row_mask:0xf bank_mask:0xf
	ds_read_b32 v59, v38 offset:52224
	ds_read_b32 v54, v37 offset:13056
	ds_read_b32 v55, v37 offset:13184
	v_add_f32_e32 v46, v44, v45
	v_mov_b32_e32 v47, v46
	s_waitcnt lgkmcnt(9)
	v_mul_f32_e32 v40, v56, v39
	v_mov_b32_e32 v41, 0
	v_permlane32_swap_b32_e32 v46, v47
	v_fmac_f32_dpp v40, -v48, v0 row_newbcast:0 row_mask:0xf bank_mask:0xf
	v_fmac_f32_dpp v41, -v48, v1 row_newbcast:1 row_mask:0xf bank_mask:0xf
	v_add_f32_dpp v23, v46, v47 quad_perm:[0,1,2,3] row_mask:0xc bank_mask:0xf
	v_fmac_f32_dpp v40, -v48, v2 row_newbcast:2 row_mask:0xf bank_mask:0xf
	v_fmac_f32_dpp v41, -v48, v3 row_newbcast:3 row_mask:0xf bank_mask:0xf
	v_fmac_f32_dpp v40, -v48, v4 row_newbcast:4 row_mask:0xf bank_mask:0xf
	v_fmac_f32_dpp v41, -v48, v5 row_newbcast:5 row_mask:0xf bank_mask:0xf
	v_fmac_f32_dpp v40, -v48, v6 row_newbcast:6 row_mask:0xf bank_mask:0xf
	v_fmac_f32_dpp v41, -v48, v7 row_newbcast:7 row_mask:0xf bank_mask:0xf
	v_fmac_f32_dpp v40, -v48, v8 row_newbcast:8 row_mask:0xf bank_mask:0xf
	v_fmac_f32_dpp v41, -v48, v9 row_newbcast:9 row_mask:0xf bank_mask:0xf
	v_fmac_f32_dpp v40, -v48, v10 row_newbcast:10 row_mask:0xf bank_mask:0xf
	v_fmac_f32_dpp v41, -v48, v11 row_newbcast:11 row_mask:0xf bank_mask:0xf
	v_fmac_f32_dpp v40, -v48, v12 row_newbcast:12 row_mask:0xf bank_mask:0xf
	v_fmac_f32_dpp v41, -v48, v13 row_newbcast:13 row_mask:0xf bank_mask:0xf
	v_fmac_f32_dpp v40, -v48, v14 row_newbcast:14 row_mask:0xf bank_mask:0xf
	v_fmac_f32_dpp v41, -v48, v15 row_newbcast:15 row_mask:0xf bank_mask:0xf
	v_fmac_f32_dpp v40, -v49, v16 row_newbcast:0 row_mask:0xf bank_mask:0xf
	v_fmac_f32_dpp v41, -v49, v17 row_newbcast:1 row_mask:0xf bank_mask:0xf
	v_fmac_f32_dpp v40, -v49, v18 row_newbcast:2 row_mask:0xf bank_mask:0xf
	v_fmac_f32_dpp v41, -v49, v19 row_newbcast:3 row_mask:0xf bank_mask:0xf
	v_fmac_f32_dpp v40, -v49, v20 row_newbcast:4 row_mask:0xf bank_mask:0xf
	v_fmac_f32_dpp v41, -v49, v21 row_newbcast:5 row_mask:0xf bank_mask:0xf
	v_fmac_f32_dpp v40, -v49, v22 row_newbcast:6 row_mask:0xf bank_mask:0xf
	v_fmac_f32_dpp v41, -v49, v23 row_newbcast:7 row_mask:0xf bank_mask:0xf
	ds_read_b32 v56, v38 offset:53248
	ds_read_b32 v48, v37 offset:13312
	ds_read_b32 v49, v37 offset:13440
	v_add_f32_e32 v42, v40, v41
	v_mov_b32_e32 v43, v42
	s_waitcnt lgkmcnt(9)
	v_mul_f32_e32 v44, v57, v39
	v_mov_b32_e32 v45, 0
	v_permlane32_swap_b32_e32 v42, v43
	v_fmac_f32_dpp v44, -v50, v0 row_newbcast:0 row_mask:0xf bank_mask:0xf
	v_fmac_f32_dpp v45, -v50, v1 row_newbcast:1 row_mask:0xf bank_mask:0xf
	v_add_f32_dpp v24, v42, v43 quad_perm:[0,1,2,3] row_mask:0x3 bank_mask:0xf
	v_fmac_f32_dpp v44, -v50, v2 row_newbcast:2 row_mask:0xf bank_mask:0xf
	v_fmac_f32_dpp v45, -v50, v3 row_newbcast:3 row_mask:0xf bank_mask:0xf
	v_fmac_f32_dpp v44, -v50, v4 row_newbcast:4 row_mask:0xf bank_mask:0xf
	v_fmac_f32_dpp v45, -v50, v5 row_newbcast:5 row_mask:0xf bank_mask:0xf
	v_fmac_f32_dpp v44, -v50, v6 row_newbcast:6 row_mask:0xf bank_mask:0xf
	v_fmac_f32_dpp v45, -v50, v7 row_newbcast:7 row_mask:0xf bank_mask:0xf
	v_fmac_f32_dpp v44, -v50, v8 row_newbcast:8 row_mask:0xf bank_mask:0xf
	v_fmac_f32_dpp v45, -v50, v9 row_newbcast:9 row_mask:0xf bank_mask:0xf
	v_fmac_f32_dpp v44, -v50, v10 row_newbcast:10 row_mask:0xf bank_mask:0xf
	v_fmac_f32_dpp v45, -v50, v11 row_newbcast:11 row_mask:0xf bank_mask:0xf
	v_fmac_f32_dpp v44, -v50, v12 row_newbcast:12 row_mask:0xf bank_mask:0xf
	v_fmac_f32_dpp v45, -v50, v13 row_newbcast:13 row_mask:0xf bank_mask:0xf
	v_fmac_f32_dpp v44, -v50, v14 row_newbcast:14 row_mask:0xf bank_mask:0xf
	v_fmac_f32_dpp v45, -v50, v15 row_newbcast:15 row_mask:0xf bank_mask:0xf
	v_fmac_f32_dpp v44, -v51, v16 row_newbcast:0 row_mask:0xf bank_mask:0xf
	v_fmac_f32_dpp v45, -v51, v17 row_newbcast:1 row_mask:0xf bank_mask:0xf
	v_fmac_f32_dpp v44, -v51, v18 row_newbcast:2 row_mask:0xf bank_mask:0xf
	v_fmac_f32_dpp v45, -v51, v19 row_newbcast:3 row_mask:0xf bank_mask:0xf
	v_fmac_f32_dpp v44, -v51, v20 row_newbcast:4 row_mask:0xf bank_mask:0xf
	v_fmac_f32_dpp v45, -v51, v21 row_newbcast:5 row_mask:0xf bank_mask:0xf
	v_fmac_f32_dpp v44, -v51, v22 row_newbcast:6 row_mask:0xf bank_mask:0xf
	v_fmac_f32_dpp v45, -v51, v23 row_newbcast:7 row_mask:0xf bank_mask:0xf
	v_fmac_f32_dpp v44, -v51, v24 row_newbcast:8 row_mask:0xf bank_mask:0xf
	ds_read_b32 v57, v38 offset:54272
	ds_read_b32 v50, v37 offset:13568
	ds_read_b32 v51, v37 offset:13696
	v_add_f32_e32 v46, v44, v45
	v_mov_b32_e32 v47, v46
	s_waitcnt lgkmcnt(9)
; #define LAS __attribute__((address_space(3)))
; __device__ __forceinline__ void phase_chunk_prep(const Params& p, LAS unsigned char* lds, int wave_s) {
;     ...
;             for (int i = 0; i < 64; ++i) {
;                 float s0 = RHS[i * 256 + col], s1 = 0.f, s2 = 0.f, s3 = 0.f;
; #pragma unroll
;                 for (int j4 = 0; j4 < (i + 3) / 4; ++j4) { const f32x4 a = *(const LAS f32x4*)(AM + i * 64 + 4 * j4);
;                     s0 -= a.x * sol[4 * j4]; s1 -= a.y * sol[4 * j4 + 1]; s2 -= a.z * sol[4 * j4 + 2]; s3 -= a.w * sol[4 * j4 + 3]; }
;                 sol[i] = (s0 + s1) + (s2 + s3);
	v_mul_f32_e32 v40, v58, v39
	v_mov_b32_e32 v41, 0
	v_permlane32_swap_b32_e32 v46, v47
	v_fmac_f32_dpp v40, -v52, v0 row_newbcast:0 row_mask:0xf bank_mask:0xf
	v_fmac_f32_dpp v41, -v52, v1 row_newbcast:1 row_mask:0xf bank_mask:0xf
	v_add_f32_dpp v25, v46, v47 quad_perm:[0,1,2,3] row_mask:0x3 bank_mask:0xf
	v_fmac_f32_dpp v40, -v52, v2 row_newbcast:2 row_mask:0xf bank_mask:0xf
	v_fmac_f32_dpp v41, -v52, v3 row_newbcast:3 row_mask:0xf bank_mask:0xf
	v_fmac_f32_dpp v40, -v52, v4 row_newbcast:4 row_mask:0xf bank_mask:0xf
	v_fmac_f32_dpp v41, -v52, v5 row_newbcast:5 row_mask:0xf bank_mask:0xf
	v_fmac_f32_dpp v40, -v52, v6 row_newbcast:6 row_mask:0xf bank_mask:0xf
	v_fmac_f32_dpp v41, -v52, v7 row_newbcast:7 row_mask:0xf bank_mask:0xf
	v_fmac_f32_dpp v40, -v52, v8 row_newbcast:8 row_mask:0xf bank_mask:0xf
	v_fmac_f32_dpp v41, -v52, v9 row_newbcast:9 row_mask:0xf bank_mask:0xf
	v_fmac_f32_dpp v40, -v52, v10 row_newbcast:10 row_mask:0xf bank_mask:0xf
	v_fmac_f32_dpp v41, -v52, v11 row_newbcast:11 row_mask:0xf bank_mask:0xf
	v_fmac_f32_dpp v40, -v52, v12 row_newbcast:12 row_mask:0xf bank_mask:0xf
	v_fmac_f32_dpp v41, -v52, v13 row_newbcast:13 row_mask:0xf bank_mask:0xf
	v_fmac_f32_dpp v40, -v52, v14 row_newbcast:14 row_mask:0xf bank_mask:0xf
	v_fmac_f32_dpp v41, -v52, v15 row_newbcast:15 row_mask:0xf bank_mask:0xf
	v_fmac_f32_dpp v40, -v53, v16 row_newbcast:0 row_mask:0xf bank_mask:0xf
	v_fmac_f32_dpp v41, -v53, v17 row_newbcast:1 row_mask:0xf bank_mask:0xf
	v_fmac_f32_dpp v40, -v53, v18 row_newbcast:2 row_mask:0xf bank_mask:0xf
	v_fmac_f32_dpp v41, -v53, v19 row_newbcast:3 row_mask:0xf bank_mask:0xf
	v_fmac_f32_dpp v40, -v53, v20 row_newbcast:4 row_mask:0xf bank_mask:0xf
	v_fmac_f32_dpp v41, -v53, v21 row_newbcast:5 row_mask:0xf bank_mask:0xf
	v_fmac_f32_dpp v40, -v53, v22 row_newbcast:6 row_mask:0xf bank_mask:0xf
	v_fmac_f32_dpp v41, -v53, v23 row_newbcast:7 row_mask:0xf bank_mask:0xf
	v_fmac_f32_dpp v40, -v53, v24 row_newbcast:8 row_mask:0xf bank_mask:0xf
	v_fmac_f32_dpp v41, -v53, v25 row_newbcast:9 row_mask:0xf bank_mask:0xf
	ds_read_b32 v58, v38 offset:55296
	ds_read_b32 v52, v37 offset:13824
	ds_read_b32 v53, v37 offset:13952
	v_add_f32_e32 v42, v40, v41
	v_mov_b32_e32 v43, v42
	s_waitcnt lgkmcnt(9)
	v_mul_f32_e32 v44, v59, v39
	v_mov_b32_e32 v45, 0
	v_permlane32_swap_b32_e32 v42, v43
	v_fmac_f32_dpp v44, -v54, v0 row_newbcast:0 row_mask:0xf bank_mask:0xf
	v_fmac_f32_dpp v45, -v54, v1 row_newbcast:1 row_mask:0xf bank_mask:0xf
	v_add_f32_dpp v24, v42, v43 quad_perm:[0,1,2,3] row_mask:0xc bank_mask:0xf
	v_fmac_f32_dpp v44, -v54, v2 row_newbcast:2 row_mask:0xf bank_mask:0xf
	v_fmac_f32_dpp v45, -v54, v3 row_newbcast:3 row_mask:0xf bank_mask:0xf
	v_fmac_f32_dpp v44, -v54, v4 row_newbcast:4 row_mask:0xf bank_mask:0xf
	v_fmac_f32_dpp v45, -v54, v5 row_newbcast:5 row_mask:0xf bank_mask:0xf
	v_fmac_f32_dpp v44, -v54, v6 row_newbcast:6 row_mask:0xf bank_mask:0xf
	v_fmac_f32_dpp v45, -v54, v7 row_newbcast:7 row_mask:0xf bank_mask:0xf
	v_fmac_f32_dpp v44, -v54, v8 row_newbcast:8 row_mask:0xf bank_mask:0xf
	v_fmac_f32_dpp v45, -v54, v9 row_newbcast:9 row_mask:0xf bank_mask:0xf
	v_fmac_f32_dpp v44, -v54, v10 row_newbcast:10 row_mask:0xf bank_mask:0xf
	v_fmac_f32_dpp v45, -v54, v11 row_newbcast:11 row_mask:0xf bank_mask:0xf
	v_fmac_f32_dpp v44, -v54, v12 row_newbcast:12 row_mask:0xf bank_mask:0xf
	v_fmac_f32_dpp v45, -v54, v13 row_newbcast:13 row_mask:0xf bank_mask:0xf
	v_fmac_f32_dpp v44, -v54, v14 row_newbcast:14 row_mask:0xf bank_mask:0xf
	v_fmac_f32_dpp v45, -v54, v15 row_newbcast:15 row_mask:0xf bank_mask:0xf
	v_fmac_f32_dpp v44, -v55, v16 row_newbcast:0 row_mask:0xf bank_mask:0xf
	v_fmac_f32_dpp v45, -v55, v17 row_newbcast:1 row_mask:0xf bank_mask:0xf
	v_fmac_f32_dpp v44, -v55, v18 row_newbcast:2 row_mask:0xf bank_mask:0xf
	v_fmac_f32_dpp v45, -v55, v19 row_newbcast:3 row_mask:0xf bank_mask:0xf
	v_fmac_f32_dpp v44, -v55, v20 row_newbcast:4 row_mask:0xf bank_mask:0xf
	v_fmac_f32_dpp v45, -v55, v21 row_newbcast:5 row_mask:0xf bank_mask:0xf
	v_fmac_f32_dpp v44, -v55, v22 row_newbcast:6 row_mask:0xf bank_mask:0xf
	v_fmac_f32_dpp v45, -v55, v23 row_newbcast:7 row_mask:0xf bank_mask:0xf
	v_fmac_f32_dpp v45, -v55, v25 row_newbcast:9 row_mask:0xf bank_mask:0xf
	v_fmac_f32_dpp v44, -v55, v24 row_newbcast:8 row_mask:0xf bank_mask:0xf
	ds_read_b32 v59, v38 offset:56320
	ds_read_b32 v54, v37 offset:14080
	ds_read_b32 v55, v37 offset:14208
	v_add_f32_e32 v46, v44, v45
	v_mov_b32_e32 v47, v46
	s_waitcnt lgkmcnt(9)
	v_mul_f32_e32 v40, v56, v39
	v_mov_b32_e32 v41, 0
	v_permlane32_swap_b32_e32 v46, v47
	v_fmac_f32_dpp v40, -v48, v0 row_newbcast:0 row_mask:0xf bank_mask:0xf
	v_fmac_f32_dpp v41, -v48, v1 row_newbcast:1 row_mask:0xf bank_mask:0xf
	v_add_f32_dpp v25, v46, v47 quad_perm:[0,1,2,3] row_mask:0xc bank_mask:0xf
	v_fmac_f32_dpp v40, -v48, v2 row_newbcast:2 row_mask:0xf bank_mask:0xf
	v_fmac_f32_dpp v41, -v48, v3 row_newbcast:3 row_mask:0xf bank_mask:0xf
	v_fmac_f32_dpp v40, -v48, v4 row_newbcast:4 row_mask:0xf bank_mask:0xf
	v_fmac_f32_dpp v41, -v48, v5 row_newbcast:5 row_mask:0xf bank_mask:0xf
	v_fmac_f32_dpp v40, -v48, v6 row_newbcast:6 row_mask:0xf bank_mask:0xf
	v_fmac_f32_dpp v41, -v48, v7 row_newbcast:7 row_mask:0xf bank_mask:0xf
	v_fmac_f32_dpp v40, -v48, v8 row_newbcast:8 row_mask:0xf bank_mask:0xf
	v_fmac_f32_dpp v41, -v48, v9 row_newbcast:9 row_mask:0xf bank_mask:0xf
	v_fmac_f32_dpp v40, -v48, v10 row_newbcast:10 row_mask:0xf bank_mask:0xf
	v_fmac_f32_dpp v41, -v48, v11 row_newbcast:11 row_mask:0xf bank_mask:0xf
	v_fmac_f32_dpp v40, -v48, v12 row_newbcast:12 row_mask:0xf bank_mask:0xf
	v_fmac_f32_dpp v41, -v48, v13 row_newbcast:13 row_mask:0xf bank_mask:0xf
	v_fmac_f32_dpp v40, -v48, v14 row_newbcast:14 row_mask:0xf bank_mask:0xf
	v_fmac_f32_dpp v41, -v48, v15 row_newbcast:15 row_mask:0xf bank_mask:0xf
	v_fmac_f32_dpp v40, -v49, v16 row_newbcast:0 row_mask:0xf bank_mask:0xf
	v_fmac_f32_dpp v41, -v49, v17 row_newbcast:1 row_mask:0xf bank_mask:0xf
	v_fmac_f32_dpp v40, -v49, v18 row_newbcast:2 row_mask:0xf bank_mask:0xf
	v_fmac_f32_dpp v41, -v49, v19 row_newbcast:3 row_mask:0xf bank_mask:0xf
	v_fmac_f32_dpp v40, -v49, v20 row_newbcast:4 row_mask:0xf bank_mask:0xf
	v_fmac_f32_dpp v41, -v49, v21 row_newbcast:5 row_mask:0xf bank_mask:0xf
	v_fmac_f32_dpp v40, -v49, v22 row_newbcast:6 row_mask:0xf bank_mask:0xf
	v_fmac_f32_dpp v41, -v49, v23 row_newbcast:7 row_mask:0xf bank_mask:0xf
	v_fmac_f32_dpp v40, -v49, v24 row_newbcast:8 row_mask:0xf bank_mask:0xf
	v_fmac_f32_dpp v41, -v49, v25 row_newbcast:9 row_mask:0xf bank_mask:0xf
	ds_read_b32 v56, v38 offset:57344
	ds_read_b32 v48, v37 offset:14336
	ds_read_b32 v49, v37 offset:14464
	v_add_f32_e32 v42, v40, v41
	v_mov_b32_e32 v43, v42
	s_waitcnt lgkmcnt(9)
; #define LAS __attribute__((address_space(3)))
; __device__ __forceinline__ void phase_chunk_prep(const Params& p, LAS unsigned char* lds, int wave_s) {
;     ...
;             for (int i = 0; i < 64; ++i) {
;                 float s0 = RHS[i * 256 + col], s1 = 0.f, s2 = 0.f, s3 = 0.f;
; #pragma unroll
;                 for (int j4 = 0; j4 < (i + 3) / 4; ++j4) { const f32x4 a = *(const LAS f32x4*)(AM + i * 64 + 4 * j4);
;                     s0 -= a.x * sol[4 * j4]; s1 -= a.y * sol[4 * j4 + 1]; s2 -= a.z * sol[4 * j4 + 2]; s3 -= a.w * sol[4 * j4 + 3]; }
;                 sol[i] = (s0 + s1) + (s2 + s3);
	v_mul_f32_e32 v44, v57, v39
	v_mov_b32_e32 v45, 0
	v_permlane32_swap_b32_e32 v42, v43
	v_fmac_f32_dpp v44, -v50, v0 row_newbcast:0 row_mask:0xf bank_mask:0xf
	v_fmac_f32_dpp v45, -v50, v1 row_newbcast:1 row_mask:0xf bank_mask:0xf
	v_add_f32_dpp v26, v42, v43 quad_perm:[0,1,2,3] row_mask:0x3 bank_mask:0xf
	v_fmac_f32_dpp v44, -v50, v2 row_newbcast:2 row_mask:0xf bank_mask:0xf
	v_fmac_f32_dpp v45, -v50, v3 row_newbcast:3 row_mask:0xf bank_mask:0xf
	v_fmac_f32_dpp v44, -v50, v4 row_newbcast:4 row_mask:0xf bank_mask:0xf
	v_fmac_f32_dpp v45, -v50, v5 row_newbcast:5 row_mask:0xf bank_mask:0xf
	v_fmac_f32_dpp v44, -v50, v6 row_newbcast:6 row_mask:0xf bank_mask:0xf
	v_fmac_f32_dpp v45, -v50, v7 row_newbcast:7 row_mask:0xf bank_mask:0xf
	v_fmac_f32_dpp v44, -v50, v8 row_newbcast:8 row_mask:0xf bank_mask:0xf
	v_fmac_f32_dpp v45, -v50, v9 row_newbcast:9 row_mask:0xf bank_mask:0xf
	v_fmac_f32_dpp v44, -v50, v10 row_newbcast:10 row_mask:0xf bank_mask:0xf
	v_fmac_f32_dpp v45, -v50, v11 row_newbcast:11 row_mask:0xf bank_mask:0xf
	v_fmac_f32_dpp v44, -v50, v12 row_newbcast:12 row_mask:0xf bank_mask:0xf
	v_fmac_f32_dpp v45, -v50, v13 row_newbcast:13 row_mask:0xf bank_mask:0xf
	v_fmac_f32_dpp v44, -v50, v14 row_newbcast:14 row_mask:0xf bank_mask:0xf
	v_fmac_f32_dpp v45, -v50, v15 row_newbcast:15 row_mask:0xf bank_mask:0xf
	v_fmac_f32_dpp v44, -v51, v16 row_newbcast:0 row_mask:0xf bank_mask:0xf
	v_fmac_f32_dpp v45, -v51, v17 row_newbcast:1 row_mask:0xf bank_mask:0xf
	v_fmac_f32_dpp v44, -v51, v18 row_newbcast:2 row_mask:0xf bank_mask:0xf
	v_fmac_f32_dpp v45, -v51, v19 row_newbcast:3 row_mask:0xf bank_mask:0xf
	v_fmac_f32_dpp v44, -v51, v20 row_newbcast:4 row_mask:0xf bank_mask:0xf
	v_fmac_f32_dpp v45, -v51, v21 row_newbcast:5 row_mask:0xf bank_mask:0xf
	v_fmac_f32_dpp v44, -v51, v22 row_newbcast:6 row_mask:0xf bank_mask:0xf
	v_fmac_f32_dpp v45, -v51, v23 row_newbcast:7 row_mask:0xf bank_mask:0xf
	v_fmac_f32_dpp v44, -v51, v24 row_newbcast:8 row_mask:0xf bank_mask:0xf
	v_fmac_f32_dpp v45, -v51, v25 row_newbcast:9 row_mask:0xf bank_mask:0xf
	v_fmac_f32_dpp v44, -v51, v26 row_newbcast:10 row_mask:0xf bank_mask:0xf
	ds_read_b32 v57, v38 offset:58368
	ds_read_b32 v50, v37 offset:14592
	ds_read_b32 v51, v37 offset:14720
	v_add_f32_e32 v46, v44, v45
	v_mov_b32_e32 v47, v46
	s_waitcnt lgkmcnt(9)
	v_mul_f32_e32 v40, v58, v39
	v_mov_b32_e32 v41, 0
	v_permlane32_swap_b32_e32 v46, v47
	v_fmac_f32_dpp v40, -v52, v0 row_newbcast:0 row_mask:0xf bank_mask:0xf
	v_fmac_f32_dpp v41, -v52, v1 row_newbcast:1 row_mask:0xf bank_mask:0xf
	v_add_f32_dpp v27, v46, v47 quad_perm:[0,1,2,3] row_mask:0x3 bank_mask:0xf
	v_fmac_f32_dpp v40, -v52, v2 row_newbcast:2 row_mask:0xf bank_mask:0xf
	v_fmac_f32_dpp v41, -v52, v3 row_newbcast:3 row_mask:0xf bank_mask:0xf
	v_fmac_f32_dpp v40, -v52, v4 row_newbcast:4 row_mask:0xf bank_mask:0xf
	v_fmac_f32_dpp v41, -v52, v5 row_newbcast:5 row_mask:0xf bank_mask:0xf
	v_fmac_f32_dpp v40, -v52, v6 row_newbcast:6 row_mask:0xf bank_mask:0xf
	v_fmac_f32_dpp v41, -v52, v7 row_newbcast:7 row_mask:0xf bank_mask:0xf
	v_fmac_f32_dpp v40, -v52, v8 row_newbcast:8 row_mask:0xf bank_mask:0xf
	v_fmac_f32_dpp v41, -v52, v9 row_newbcast:9 row_mask:0xf bank_mask:0xf
	v_fmac_f32_dpp v40, -v52, v10 row_newbcast:10 row_mask:0xf bank_mask:0xf
	v_fmac_f32_dpp v41, -v52, v11 row_newbcast:11 row_mask:0xf bank_mask:0xf
	v_fmac_f32_dpp v40, -v52, v12 row_newbcast:12 row_mask:0xf bank_mask:0xf
	v_fmac_f32_dpp v41, -v52, v13 row_newbcast:13 row_mask:0xf bank_mask:0xf
	v_fmac_f32_dpp v40, -v52, v14 row_newbcast:14 row_mask:0xf bank_mask:0xf
	v_fmac_f32_dpp v41, -v52, v15 row_newbcast:15 row_mask:0xf bank_mask:0xf
	v_fmac_f32_dpp v40, -v53, v16 row_newbcast:0 row_mask:0xf bank_mask:0xf
	v_fmac_f32_dpp v41, -v53, v17 row_newbcast:1 row_mask:0xf bank_mask:0xf
	v_fmac_f32_dpp v40, -v53, v18 row_newbcast:2 row_mask:0xf bank_mask:0xf
	v_fmac_f32_dpp v41, -v53, v19 row_newbcast:3 row_mask:0xf bank_mask:0xf
	v_fmac_f32_dpp v40, -v53, v20 row_newbcast:4 row_mask:0xf bank_mask:0xf
	v_fmac_f32_dpp v41, -v53, v21 row_newbcast:5 row_mask:0xf bank_mask:0xf
	v_fmac_f32_dpp v40, -v53, v22 row_newbcast:6 row_mask:0xf bank_mask:0xf
	v_fmac_f32_dpp v41, -v53, v23 row_newbcast:7 row_mask:0xf bank_mask:0xf
	v_fmac_f32_dpp v40, -v53, v24 row_newbcast:8 row_mask:0xf bank_mask:0xf
	v_fmac_f32_dpp v41, -v53, v25 row_newbcast:9 row_mask:0xf bank_mask:0xf
	v_fmac_f32_dpp v40, -v53, v26 row_newbcast:10 row_mask:0xf bank_mask:0xf
	v_fmac_f32_dpp v41, -v53, v27 row_newbcast:11 row_mask:0xf bank_mask:0xf
	ds_read_b32 v58, v38 offset:59392
	ds_read_b32 v52, v37 offset:14848
	ds_read_b32 v53, v37 offset:14976
	v_add_f32_e32 v42, v40, v41
	v_mov_b32_e32 v43, v42
	s_waitcnt lgkmcnt(9)
; #define LAS __attribute__((address_space(3)))
; __device__ __forceinline__ void phase_chunk_prep(const Params& p, LAS unsigned char* lds, int wave_s) {
;     ...
;             for (int i = 0; i < 64; ++i) {
;                 float s0 = RHS[i * 256 + col], s1 = 0.f, s2 = 0.f, s3 = 0.f;
; #pragma unroll
;                 for (int j4 = 0; j4 < (i + 3) / 4; ++j4) { const f32x4 a = *(const LAS f32x4*)(AM + i * 64 + 4 * j4);
;                     s0 -= a.x * sol[4 * j4]; s1 -= a.y * sol[4 * j4 + 1]; s2 -= a.z * sol[4 * j4 + 2]; s3 -= a.w * sol[4 * j4 + 3]; }
;                 sol[i] = (s0 + s1) + (s2 + s3);
	v_mul_f32_e32 v44, v59, v39
	v_mov_b32_e32 v45, 0
	v_permlane32_swap_b32_e32 v42, v43
	v_fmac_f32_dpp v44, -v54, v0 row_newbcast:0 row_mask:0xf bank_mask:0xf
	v_fmac_f32_dpp v45, -v54, v1 row_newbcast:1 row_mask:0xf bank_mask:0xf
	v_add_f32_dpp v26, v42, v43 quad_perm:[0,1,2,3] row_mask:0xc bank_mask:0xf
	v_fmac_f32_dpp v44, -v54, v2 row_newbcast:2 row_mask:0xf bank_mask:0xf
	v_fmac_f32_dpp v45, -v54, v3 row_newbcast:3 row_mask:0xf bank_mask:0xf
	v_fmac_f32_dpp v44, -v54, v4 row_newbcast:4 row_mask:0xf bank_mask:0xf
	v_fmac_f32_dpp v45, -v54, v5 row_newbcast:5 row_mask:0xf bank_mask:0xf
	v_fmac_f32_dpp v44, -v54, v6 row_newbcast:6 row_mask:0xf bank_mask:0xf
	v_fmac_f32_dpp v45, -v54, v7 row_newbcast:7 row_mask:0xf bank_mask:0xf
	v_fmac_f32_dpp v44, -v54, v8 row_newbcast:8 row_mask:0xf bank_mask:0xf
	v_fmac_f32_dpp v45, -v54, v9 row_newbcast:9 row_mask:0xf bank_mask:0xf
	v_fmac_f32_dpp v44, -v54, v10 row_newbcast:10 row_mask:0xf bank_mask:0xf
	v_fmac_f32_dpp v45, -v54, v11 row_newbcast:11 row_mask:0xf bank_mask:0xf
	v_fmac_f32_dpp v44, -v54, v12 row_newbcast:12 row_mask:0xf bank_mask:0xf
	v_fmac_f32_dpp v45, -v54, v13 row_newbcast:13 row_mask:0xf bank_mask:0xf
	v_fmac_f32_dpp v44, -v54, v14 row_newbcast:14 row_mask:0xf bank_mask:0xf
	v_fmac_f32_dpp v45, -v54, v15 row_newbcast:15 row_mask:0xf bank_mask:0xf
	v_fmac_f32_dpp v44, -v55, v16 row_newbcast:0 row_mask:0xf bank_mask:0xf
	v_fmac_f32_dpp v45, -v55, v17 row_newbcast:1 row_mask:0xf bank_mask:0xf
	v_fmac_f32_dpp v44, -v55, v18 row_newbcast:2 row_mask:0xf bank_mask:0xf
	v_fmac_f32_dpp v45, -v55, v19 row_newbcast:3 row_mask:0xf bank_mask:0xf
	v_fmac_f32_dpp v44, -v55, v20 row_newbcast:4 row_mask:0xf bank_mask:0xf
	v_fmac_f32_dpp v45, -v55, v21 row_newbcast:5 row_mask:0xf bank_mask:0xf
	v_fmac_f32_dpp v44, -v55, v22 row_newbcast:6 row_mask:0xf bank_mask:0xf
	v_fmac_f32_dpp v45, -v55, v23 row_newbcast:7 row_mask:0xf bank_mask:0xf
	v_fmac_f32_dpp v44, -v55, v24 row_newbcast:8 row_mask:0xf bank_mask:0xf
	v_fmac_f32_dpp v45, -v55, v25 row_newbcast:9 row_mask:0xf bank_mask:0xf
	v_fmac_f32_dpp v45, -v55, v27 row_newbcast:11 row_mask:0xf bank_mask:0xf
	v_fmac_f32_dpp v44, -v55, v26 row_newbcast:10 row_mask:0xf bank_mask:0xf
	ds_read_b32 v59, v38 offset:60416
	ds_read_b32 v54, v37 offset:15104
	ds_read_b32 v55, v37 offset:15232
	v_add_f32_e32 v46, v44, v45
	v_mov_b32_e32 v47, v46
	s_waitcnt lgkmcnt(9)
	v_mul_f32_e32 v40, v56, v39
	v_mov_b32_e32 v41, 0
	v_permlane32_swap_b32_e32 v46, v47
	v_fmac_f32_dpp v40, -v48, v0 row_newbcast:0 row_mask:0xf bank_mask:0xf
	v_fmac_f32_dpp v41, -v48, v1 row_newbcast:1 row_mask:0xf bank_mask:0xf
	v_add_f32_dpp v27, v46, v47 quad_perm:[0,1,2,3] row_mask:0xc bank_mask:0xf
	v_fmac_f32_dpp v40, -v48, v2 row_newbcast:2 row_mask:0xf bank_mask:0xf
	v_fmac_f32_dpp v41, -v48, v3 row_newbcast:3 row_mask:0xf bank_mask:0xf
	v_fmac_f32_dpp v40, -v48, v4 row_newbcast:4 row_mask:0xf bank_mask:0xf
	v_fmac_f32_dpp v41, -v48, v5 row_newbcast:5 row_mask:0xf bank_mask:0xf
	v_fmac_f32_dpp v40, -v48, v6 row_newbcast:6 row_mask:0xf bank_mask:0xf
	v_fmac_f32_dpp v41, -v48, v7 row_newbcast:7 row_mask:0xf bank_mask:0xf
	v_fmac_f32_dpp v40, -v48, v8 row_newbcast:8 row_mask:0xf bank_mask:0xf
	v_fmac_f32_dpp v41, -v48, v9 row_newbcast:9 row_mask:0xf bank_mask:0xf
	v_fmac_f32_dpp v40, -v48, v10 row_newbcast:10 row_mask:0xf bank_mask:0xf
	v_fmac_f32_dpp v41, -v48, v11 row_newbcast:11 row_mask:0xf bank_mask:0xf
	v_fmac_f32_dpp v40, -v48, v12 row_newbcast:12 row_mask:0xf bank_mask:0xf
	v_fmac_f32_dpp v41, -v48, v13 row_newbcast:13 row_mask:0xf bank_mask:0xf
	v_fmac_f32_dpp v40, -v48, v14 row_newbcast:14 row_mask:0xf bank_mask:0xf
	v_fmac_f32_dpp v41, -v48, v15 row_newbcast:15 row_mask:0xf bank_mask:0xf
	v_fmac_f32_dpp v40, -v49, v16 row_newbcast:0 row_mask:0xf bank_mask:0xf
	v_fmac_f32_dpp v41, -v49, v17 row_newbcast:1 row_mask:0xf bank_mask:0xf
	v_fmac_f32_dpp v40, -v49, v18 row_newbcast:2 row_mask:0xf bank_mask:0xf
	v_fmac_f32_dpp v41, -v49, v19 row_newbcast:3 row_mask:0xf bank_mask:0xf
	v_fmac_f32_dpp v40, -v49, v20 row_newbcast:4 row_mask:0xf bank_mask:0xf
	v_fmac_f32_dpp v41, -v49, v21 row_newbcast:5 row_mask:0xf bank_mask:0xf
	v_fmac_f32_dpp v40, -v49, v22 row_newbcast:6 row_mask:0xf bank_mask:0xf
	v_fmac_f32_dpp v41, -v49, v23 row_newbcast:7 row_mask:0xf bank_mask:0xf
	v_fmac_f32_dpp v40, -v49, v24 row_newbcast:8 row_mask:0xf bank_mask:0xf
	v_fmac_f32_dpp v41, -v49, v25 row_newbcast:9 row_mask:0xf bank_mask:0xf
	v_fmac_f32_dpp v40, -v49, v26 row_newbcast:10 row_mask:0xf bank_mask:0xf
	v_fmac_f32_dpp v41, -v49, v27 row_newbcast:11 row_mask:0xf bank_mask:0xf
	ds_read_b32 v56, v38 offset:61440
	ds_read_b32 v48, v37 offset:15360
	ds_read_b32 v49, v37 offset:15488
	v_add_f32_e32 v42, v40, v41
	v_mov_b32_e32 v43, v42
	s_waitcnt lgkmcnt(9)
; #define LAS __attribute__((address_space(3)))
; __device__ __forceinline__ void phase_chunk_prep(const Params& p, LAS unsigned char* lds, int wave_s) {
;     ...
;             for (int i = 0; i < 64; ++i) {
;                 float s0 = RHS[i * 256 + col], s1 = 0.f, s2 = 0.f, s3 = 0.f;
; #pragma unroll
;                 for (int j4 = 0; j4 < (i + 3) / 4; ++j4) { const f32x4 a = *(const LAS f32x4*)(AM + i * 64 + 4 * j4);
;                     s0 -= a.x * sol[4 * j4]; s1 -= a.y * sol[4 * j4 + 1]; s2 -= a.z * sol[4 * j4 + 2]; s3 -= a.w * sol[4 * j4 + 3]; }
;                 sol[i] = (s0 + s1) + (s2 + s3);
	v_mul_f32_e32 v44, v57, v39
	v_mov_b32_e32 v45, 0
	v_permlane32_swap_b32_e32 v42, v43
	v_fmac_f32_dpp v44, -v50, v0 row_newbcast:0 row_mask:0xf bank_mask:0xf
	v_fmac_f32_dpp v45, -v50, v1 row_newbcast:1 row_mask:0xf bank_mask:0xf
	v_add_f32_dpp v28, v42, v43 quad_perm:[0,1,2,3] row_mask:0x3 bank_mask:0xf
	v_fmac_f32_dpp v44, -v50, v2 row_newbcast:2 row_mask:0xf bank_mask:0xf
	v_fmac_f32_dpp v45, -v50, v3 row_newbcast:3 row_mask:0xf bank_mask:0xf
	v_fmac_f32_dpp v44, -v50, v4 row_newbcast:4 row_mask:0xf bank_mask:0xf
	v_fmac_f32_dpp v45, -v50, v5 row_newbcast:5 row_mask:0xf bank_mask:0xf
	v_fmac_f32_dpp v44, -v50, v6 row_newbcast:6 row_mask:0xf bank_mask:0xf
	v_fmac_f32_dpp v45, -v50, v7 row_newbcast:7 row_mask:0xf bank_mask:0xf
	v_fmac_f32_dpp v44, -v50, v8 row_newbcast:8 row_mask:0xf bank_mask:0xf
	v_fmac_f32_dpp v45, -v50, v9 row_newbcast:9 row_mask:0xf bank_mask:0xf
	v_fmac_f32_dpp v44, -v50, v10 row_newbcast:10 row_mask:0xf bank_mask:0xf
	v_fmac_f32_dpp v45, -v50, v11 row_newbcast:11 row_mask:0xf bank_mask:0xf
	v_fmac_f32_dpp v44, -v50, v12 row_newbcast:12 row_mask:0xf bank_mask:0xf
	v_fmac_f32_dpp v45, -v50, v13 row_newbcast:13 row_mask:0xf bank_mask:0xf
	v_fmac_f32_dpp v44, -v50, v14 row_newbcast:14 row_mask:0xf bank_mask:0xf
	v_fmac_f32_dpp v45, -v50, v15 row_newbcast:15 row_mask:0xf bank_mask:0xf
	v_fmac_f32_dpp v44, -v51, v16 row_newbcast:0 row_mask:0xf bank_mask:0xf
	v_fmac_f32_dpp v45, -v51, v17 row_newbcast:1 row_mask:0xf bank_mask:0xf
	v_fmac_f32_dpp v44, -v51, v18 row_newbcast:2 row_mask:0xf bank_mask:0xf
	v_fmac_f32_dpp v45, -v51, v19 row_newbcast:3 row_mask:0xf bank_mask:0xf
	v_fmac_f32_dpp v44, -v51, v20 row_newbcast:4 row_mask:0xf bank_mask:0xf
	v_fmac_f32_dpp v45, -v51, v21 row_newbcast:5 row_mask:0xf bank_mask:0xf
	v_fmac_f32_dpp v44, -v51, v22 row_newbcast:6 row_mask:0xf bank_mask:0xf
	v_fmac_f32_dpp v45, -v51, v23 row_newbcast:7 row_mask:0xf bank_mask:0xf
	v_fmac_f32_dpp v44, -v51, v24 row_newbcast:8 row_mask:0xf bank_mask:0xf
	v_fmac_f32_dpp v45, -v51, v25 row_newbcast:9 row_mask:0xf bank_mask:0xf
	v_fmac_f32_dpp v44, -v51, v26 row_newbcast:10 row_mask:0xf bank_mask:0xf
	v_fmac_f32_dpp v45, -v51, v27 row_newbcast:11 row_mask:0xf bank_mask:0xf
	v_fmac_f32_dpp v44, -v51, v28 row_newbcast:12 row_mask:0xf bank_mask:0xf
	ds_read_b32 v57, v38 offset:62464
	ds_read_b32 v50, v37 offset:15616
	ds_read_b32 v51, v37 offset:15744
	v_add_f32_e32 v46, v44, v45
	v_mov_b32_e32 v47, v46
	s_waitcnt lgkmcnt(9)
	v_mul_f32_e32 v40, v58, v39
	v_mov_b32_e32 v41, 0
	v_permlane32_swap_b32_e32 v46, v47
	v_fmac_f32_dpp v40, -v52, v0 row_newbcast:0 row_mask:0xf bank_mask:0xf
	v_fmac_f32_dpp v41, -v52, v1 row_newbcast:1 row_mask:0xf bank_mask:0xf
	v_add_f32_dpp v29, v46, v47 quad_perm:[0,1,2,3] row_mask:0x3 bank_mask:0xf
	v_fmac_f32_dpp v40, -v52, v2 row_newbcast:2 row_mask:0xf bank_mask:0xf
	v_fmac_f32_dpp v41, -v52, v3 row_newbcast:3 row_mask:0xf bank_mask:0xf
	v_fmac_f32_dpp v40, -v52, v4 row_newbcast:4 row_mask:0xf bank_mask:0xf
	v_fmac_f32_dpp v41, -v52, v5 row_newbcast:5 row_mask:0xf bank_mask:0xf
	v_fmac_f32_dpp v40, -v52, v6 row_newbcast:6 row_mask:0xf bank_mask:0xf
	v_fmac_f32_dpp v41, -v52, v7 row_newbcast:7 row_mask:0xf bank_mask:0xf
	v_fmac_f32_dpp v40, -v52, v8 row_newbcast:8 row_mask:0xf bank_mask:0xf
	v_fmac_f32_dpp v41, -v52, v9 row_newbcast:9 row_mask:0xf bank_mask:0xf
	v_fmac_f32_dpp v40, -v52, v10 row_newbcast:10 row_mask:0xf bank_mask:0xf
	v_fmac_f32_dpp v41, -v52, v11 row_newbcast:11 row_mask:0xf bank_mask:0xf
	v_fmac_f32_dpp v40, -v52, v12 row_newbcast:12 row_mask:0xf bank_mask:0xf
	v_fmac_f32_dpp v41, -v52, v13 row_newbcast:13 row_mask:0xf bank_mask:0xf
	v_fmac_f32_dpp v40, -v52, v14 row_newbcast:14 row_mask:0xf bank_mask:0xf
	v_fmac_f32_dpp v41, -v52, v15 row_newbcast:15 row_mask:0xf bank_mask:0xf
	v_fmac_f32_dpp v40, -v53, v16 row_newbcast:0 row_mask:0xf bank_mask:0xf
	v_fmac_f32_dpp v41, -v53, v17 row_newbcast:1 row_mask:0xf bank_mask:0xf
	v_fmac_f32_dpp v40, -v53, v18 row_newbcast:2 row_mask:0xf bank_mask:0xf
	v_fmac_f32_dpp v41, -v53, v19 row_newbcast:3 row_mask:0xf bank_mask:0xf
	v_fmac_f32_dpp v40, -v53, v20 row_newbcast:4 row_mask:0xf bank_mask:0xf
	v_fmac_f32_dpp v41, -v53, v21 row_newbcast:5 row_mask:0xf bank_mask:0xf
	v_fmac_f32_dpp v40, -v53, v22 row_newbcast:6 row_mask:0xf bank_mask:0xf
	v_fmac_f32_dpp v41, -v53, v23 row_newbcast:7 row_mask:0xf bank_mask:0xf
	v_fmac_f32_dpp v40, -v53, v24 row_newbcast:8 row_mask:0xf bank_mask:0xf
	v_fmac_f32_dpp v41, -v53, v25 row_newbcast:9 row_mask:0xf bank_mask:0xf
	v_fmac_f32_dpp v40, -v53, v26 row_newbcast:10 row_mask:0xf bank_mask:0xf
	v_fmac_f32_dpp v41, -v53, v27 row_newbcast:11 row_mask:0xf bank_mask:0xf
	v_fmac_f32_dpp v40, -v53, v28 row_newbcast:12 row_mask:0xf bank_mask:0xf
	v_fmac_f32_dpp v41, -v53, v29 row_newbcast:13 row_mask:0xf bank_mask:0xf
	ds_read_b32 v58, v38 offset:63488
	ds_read_b32 v52, v37 offset:15872
	ds_read_b32 v53, v37 offset:16000
	v_add_f32_e32 v42, v40, v41
	v_mov_b32_e32 v43, v42
	s_waitcnt lgkmcnt(9)
; #define LAS __attribute__((address_space(3)))
; __device__ __forceinline__ void phase_chunk_prep(const Params& p, LAS unsigned char* lds, int wave_s) {
;     ...
;             for (int i = 0; i < 64; ++i) {
;                 float s0 = RHS[i * 256 + col], s1 = 0.f, s2 = 0.f, s3 = 0.f;
; #pragma unroll
;                 for (int j4 = 0; j4 < (i + 3) / 4; ++j4) { const f32x4 a = *(const LAS f32x4*)(AM + i * 64 + 4 * j4);
;                     s0 -= a.x * sol[4 * j4]; s1 -= a.y * sol[4 * j4 + 1]; s2 -= a.z * sol[4 * j4 + 2]; s3 -= a.w * sol[4 * j4 + 3]; }
;                 sol[i] = (s0 + s1) + (s2 + s3);
	v_mul_f32_e32 v44, v59, v39
	v_mov_b32_e32 v45, 0
	v_permlane32_swap_b32_e32 v42, v43
	v_fmac_f32_dpp v44, -v54, v0 row_newbcast:0 row_mask:0xf bank_mask:0xf
	v_fmac_f32_dpp v45, -v54, v1 row_newbcast:1 row_mask:0xf bank_mask:0xf
	v_add_f32_dpp v28, v42, v43 quad_perm:[0,1,2,3] row_mask:0xc bank_mask:0xf
	v_fmac_f32_dpp v44, -v54, v2 row_newbcast:2 row_mask:0xf bank_mask:0xf
	v_fmac_f32_dpp v45, -v54, v3 row_newbcast:3 row_mask:0xf bank_mask:0xf
	v_fmac_f32_dpp v44, -v54, v4 row_newbcast:4 row_mask:0xf bank_mask:0xf
	v_fmac_f32_dpp v45, -v54, v5 row_newbcast:5 row_mask:0xf bank_mask:0xf
	v_fmac_f32_dpp v44, -v54, v6 row_newbcast:6 row_mask:0xf bank_mask:0xf
	v_fmac_f32_dpp v45, -v54, v7 row_newbcast:7 row_mask:0xf bank_mask:0xf
	v_fmac_f32_dpp v44, -v54, v8 row_newbcast:8 row_mask:0xf bank_mask:0xf
	v_fmac_f32_dpp v45, -v54, v9 row_newbcast:9 row_mask:0xf bank_mask:0xf
	v_fmac_f32_dpp v44, -v54, v10 row_newbcast:10 row_mask:0xf bank_mask:0xf
	v_fmac_f32_dpp v45, -v54, v11 row_newbcast:11 row_mask:0xf bank_mask:0xf
	v_fmac_f32_dpp v44, -v54, v12 row_newbcast:12 row_mask:0xf bank_mask:0xf
	v_fmac_f32_dpp v45, -v54, v13 row_newbcast:13 row_mask:0xf bank_mask:0xf
	v_fmac_f32_dpp v44, -v54, v14 row_newbcast:14 row_mask:0xf bank_mask:0xf
	v_fmac_f32_dpp v45, -v54, v15 row_newbcast:15 row_mask:0xf bank_mask:0xf
	v_fmac_f32_dpp v44, -v55, v16 row_newbcast:0 row_mask:0xf bank_mask:0xf
	v_fmac_f32_dpp v45, -v55, v17 row_newbcast:1 row_mask:0xf bank_mask:0xf
	v_fmac_f32_dpp v44, -v55, v18 row_newbcast:2 row_mask:0xf bank_mask:0xf
	v_fmac_f32_dpp v45, -v55, v19 row_newbcast:3 row_mask:0xf bank_mask:0xf
	v_fmac_f32_dpp v44, -v55, v20 row_newbcast:4 row_mask:0xf bank_mask:0xf
	v_fmac_f32_dpp v45, -v55, v21 row_newbcast:5 row_mask:0xf bank_mask:0xf
	v_fmac_f32_dpp v44, -v55, v22 row_newbcast:6 row_mask:0xf bank_mask:0xf
	v_fmac_f32_dpp v45, -v55, v23 row_newbcast:7 row_mask:0xf bank_mask:0xf
	v_fmac_f32_dpp v44, -v55, v24 row_newbcast:8 row_mask:0xf bank_mask:0xf
	v_fmac_f32_dpp v45, -v55, v25 row_newbcast:9 row_mask:0xf bank_mask:0xf
	v_fmac_f32_dpp v44, -v55, v26 row_newbcast:10 row_mask:0xf bank_mask:0xf
	v_fmac_f32_dpp v45, -v55, v27 row_newbcast:11 row_mask:0xf bank_mask:0xf
	v_fmac_f32_dpp v45, -v55, v29 row_newbcast:13 row_mask:0xf bank_mask:0xf
	v_fmac_f32_dpp v44, -v55, v28 row_newbcast:12 row_mask:0xf bank_mask:0xf
	ds_read_b32 v59, v38 offset:64512
	ds_read_b32 v54, v37 offset:16128
	ds_read_b32 v55, v37 offset:16256
	v_add_f32_e32 v46, v44, v45
	v_mov_b32_e32 v47, v46
	s_waitcnt lgkmcnt(9)
	v_mul_f32_e32 v40, v56, v39
	v_mov_b32_e32 v41, 0
	v_permlane32_swap_b32_e32 v46, v47
	v_fmac_f32_dpp v40, -v48, v0 row_newbcast:0 row_mask:0xf bank_mask:0xf
	v_fmac_f32_dpp v41, -v48, v1 row_newbcast:1 row_mask:0xf bank_mask:0xf
	v_add_f32_dpp v29, v46, v47 quad_perm:[0,1,2,3] row_mask:0xc bank_mask:0xf
	v_fmac_f32_dpp v40, -v48, v2 row_newbcast:2 row_mask:0xf bank_mask:0xf
	v_fmac_f32_dpp v41, -v48, v3 row_newbcast:3 row_mask:0xf bank_mask:0xf
	v_fmac_f32_dpp v40, -v48, v4 row_newbcast:4 row_mask:0xf bank_mask:0xf
	v_fmac_f32_dpp v41, -v48, v5 row_newbcast:5 row_mask:0xf bank_mask:0xf
	v_fmac_f32_dpp v40, -v48, v6 row_newbcast:6 row_mask:0xf bank_mask:0xf
	v_fmac_f32_dpp v41, -v48, v7 row_newbcast:7 row_mask:0xf bank_mask:0xf
	v_fmac_f32_dpp v40, -v48, v8 row_newbcast:8 row_mask:0xf bank_mask:0xf
	v_fmac_f32_dpp v41, -v48, v9 row_newbcast:9 row_mask:0xf bank_mask:0xf
	v_fmac_f32_dpp v40, -v48, v10 row_newbcast:10 row_mask:0xf bank_mask:0xf
	v_fmac_f32_dpp v41, -v48, v11 row_newbcast:11 row_mask:0xf bank_mask:0xf
	v_fmac_f32_dpp v40, -v48, v12 row_newbcast:12 row_mask:0xf bank_mask:0xf
	v_fmac_f32_dpp v41, -v48, v13 row_newbcast:13 row_mask:0xf bank_mask:0xf
	v_fmac_f32_dpp v40, -v48, v14 row_newbcast:14 row_mask:0xf bank_mask:0xf
	v_fmac_f32_dpp v41, -v48, v15 row_newbcast:15 row_mask:0xf bank_mask:0xf
	v_fmac_f32_dpp v40, -v49, v16 row_newbcast:0 row_mask:0xf bank_mask:0xf
	v_fmac_f32_dpp v41, -v49, v17 row_newbcast:1 row_mask:0xf bank_mask:0xf
	v_fmac_f32_dpp v40, -v49, v18 row_newbcast:2 row_mask:0xf bank_mask:0xf
	v_fmac_f32_dpp v41, -v49, v19 row_newbcast:3 row_mask:0xf bank_mask:0xf
	v_fmac_f32_dpp v40, -v49, v20 row_newbcast:4 row_mask:0xf bank_mask:0xf
	v_fmac_f32_dpp v41, -v49, v21 row_newbcast:5 row_mask:0xf bank_mask:0xf
	v_fmac_f32_dpp v40, -v49, v22 row_newbcast:6 row_mask:0xf bank_mask:0xf
	v_fmac_f32_dpp v41, -v49, v23 row_newbcast:7 row_mask:0xf bank_mask:0xf
	v_fmac_f32_dpp v40, -v49, v24 row_newbcast:8 row_mask:0xf bank_mask:0xf
	v_fmac_f32_dpp v41, -v49, v25 row_newbcast:9 row_mask:0xf bank_mask:0xf
	v_fmac_f32_dpp v40, -v49, v26 row_newbcast:10 row_mask:0xf bank_mask:0xf
	v_fmac_f32_dpp v41, -v49, v27 row_newbcast:11 row_mask:0xf bank_mask:0xf
	v_fmac_f32_dpp v40, -v49, v28 row_newbcast:12 row_mask:0xf bank_mask:0xf
	v_fmac_f32_dpp v41, -v49, v29 row_newbcast:13 row_mask:0xf bank_mask:0xf
	v_add_f32_e32 v42, v40, v41
	v_mov_b32_e32 v43, v42
	s_waitcnt lgkmcnt(6)
; #define LAS __attribute__((address_space(3)))
; __device__ __forceinline__ void phase_chunk_prep(const Params& p, LAS unsigned char* lds, int wave_s) {
;     ...
; #pragma unroll
;             for (int i = 0; i < 64; ++i) {
;                 float s0 = RHS[i * 256 + col], s1 = 0.f, s2 = 0.f, s3 = 0.f;
; #pragma unroll
;                 for (int j4 = 0; j4 < (i + 3) / 4; ++j4) { const f32x4 a = *(const LAS f32x4*)(AM + i * 64 + 4 * j4);
;                     s0 -= a.x * sol[4 * j4]; s1 -= a.y * sol[4 * j4 + 1]; s2 -= a.z * sol[4 * j4 + 2]; s3 -= a.w * sol[4 * j4 + 3]; }
;                 sol[i] = (s0 + s1) + (s2 + s3);
;             }
	v_mul_f32_e32 v44, v57, v39
	v_mov_b32_e32 v45, 0
	v_permlane32_swap_b32_e32 v42, v43
	v_fmac_f32_dpp v44, -v50, v0 row_newbcast:0 row_mask:0xf bank_mask:0xf
	v_fmac_f32_dpp v45, -v50, v1 row_newbcast:1 row_mask:0xf bank_mask:0xf
	v_add_f32_dpp v30, v42, v43 quad_perm:[0,1,2,3] row_mask:0x3 bank_mask:0xf
	v_fmac_f32_dpp v44, -v50, v2 row_newbcast:2 row_mask:0xf bank_mask:0xf
	v_fmac_f32_dpp v45, -v50, v3 row_newbcast:3 row_mask:0xf bank_mask:0xf
	v_fmac_f32_dpp v44, -v50, v4 row_newbcast:4 row_mask:0xf bank_mask:0xf
	v_fmac_f32_dpp v45, -v50, v5 row_newbcast:5 row_mask:0xf bank_mask:0xf
	v_fmac_f32_dpp v44, -v50, v6 row_newbcast:6 row_mask:0xf bank_mask:0xf
	v_fmac_f32_dpp v45, -v50, v7 row_newbcast:7 row_mask:0xf bank_mask:0xf
	v_fmac_f32_dpp v44, -v50, v8 row_newbcast:8 row_mask:0xf bank_mask:0xf
	v_fmac_f32_dpp v45, -v50, v9 row_newbcast:9 row_mask:0xf bank_mask:0xf
	v_fmac_f32_dpp v44, -v50, v10 row_newbcast:10 row_mask:0xf bank_mask:0xf
	v_fmac_f32_dpp v45, -v50, v11 row_newbcast:11 row_mask:0xf bank_mask:0xf
	v_fmac_f32_dpp v44, -v50, v12 row_newbcast:12 row_mask:0xf bank_mask:0xf
	v_fmac_f32_dpp v45, -v50, v13 row_newbcast:13 row_mask:0xf bank_mask:0xf
	v_fmac_f32_dpp v44, -v50, v14 row_newbcast:14 row_mask:0xf bank_mask:0xf
	v_fmac_f32_dpp v45, -v50, v15 row_newbcast:15 row_mask:0xf bank_mask:0xf
	v_fmac_f32_dpp v44, -v51, v16 row_newbcast:0 row_mask:0xf bank_mask:0xf
	v_fmac_f32_dpp v45, -v51, v17 row_newbcast:1 row_mask:0xf bank_mask:0xf
	v_fmac_f32_dpp v44, -v51, v18 row_newbcast:2 row_mask:0xf bank_mask:0xf
	v_fmac_f32_dpp v45, -v51, v19 row_newbcast:3 row_mask:0xf bank_mask:0xf
	v_fmac_f32_dpp v44, -v51, v20 row_newbcast:4 row_mask:0xf bank_mask:0xf
	v_fmac_f32_dpp v45, -v51, v21 row_newbcast:5 row_mask:0xf bank_mask:0xf
	v_fmac_f32_dpp v44, -v51, v22 row_newbcast:6 row_mask:0xf bank_mask:0xf
	v_fmac_f32_dpp v45, -v51, v23 row_newbcast:7 row_mask:0xf bank_mask:0xf
	v_fmac_f32_dpp v44, -v51, v24 row_newbcast:8 row_mask:0xf bank_mask:0xf
	v_fmac_f32_dpp v45, -v51, v25 row_newbcast:9 row_mask:0xf bank_mask:0xf
	v_fmac_f32_dpp v44, -v51, v26 row_newbcast:10 row_mask:0xf bank_mask:0xf
	v_fmac_f32_dpp v45, -v51, v27 row_newbcast:11 row_mask:0xf bank_mask:0xf
	v_fmac_f32_dpp v44, -v51, v28 row_newbcast:12 row_mask:0xf bank_mask:0xf
	v_fmac_f32_dpp v45, -v51, v29 row_newbcast:13 row_mask:0xf bank_mask:0xf
	v_fmac_f32_dpp v44, -v51, v30 row_newbcast:14 row_mask:0xf bank_mask:0xf
	v_add_f32_e32 v46, v44, v45
	v_mov_b32_e32 v47, v46
	s_waitcnt lgkmcnt(3)
	v_mul_f32_e32 v40, v58, v39
	v_mov_b32_e32 v41, 0
	v_permlane32_swap_b32_e32 v46, v47
	v_fmac_f32_dpp v40, -v52, v0 row_newbcast:0 row_mask:0xf bank_mask:0xf
	v_fmac_f32_dpp v41, -v52, v1 row_newbcast:1 row_mask:0xf bank_mask:0xf
	v_add_f32_dpp v31, v46, v47 quad_perm:[0,1,2,3] row_mask:0x3 bank_mask:0xf
	v_fmac_f32_dpp v40, -v52, v2 row_newbcast:2 row_mask:0xf bank_mask:0xf
	v_fmac_f32_dpp v41, -v52, v3 row_newbcast:3 row_mask:0xf bank_mask:0xf
	v_fmac_f32_dpp v40, -v52, v4 row_newbcast:4 row_mask:0xf bank_mask:0xf
	v_fmac_f32_dpp v41, -v52, v5 row_newbcast:5 row_mask:0xf bank_mask:0xf
	v_fmac_f32_dpp v40, -v52, v6 row_newbcast:6 row_mask:0xf bank_mask:0xf
	v_fmac_f32_dpp v41, -v52, v7 row_newbcast:7 row_mask:0xf bank_mask:0xf
	v_fmac_f32_dpp v40, -v52, v8 row_newbcast:8 row_mask:0xf bank_mask:0xf
	v_fmac_f32_dpp v41, -v52, v9 row_newbcast:9 row_mask:0xf bank_mask:0xf
	v_fmac_f32_dpp v40, -v52, v10 row_newbcast:10 row_mask:0xf bank_mask:0xf
	v_fmac_f32_dpp v41, -v52, v11 row_newbcast:11 row_mask:0xf bank_mask:0xf
	v_fmac_f32_dpp v40, -v52, v12 row_newbcast:12 row_mask:0xf bank_mask:0xf
	v_fmac_f32_dpp v41, -v52, v13 row_newbcast:13 row_mask:0xf bank_mask:0xf
	v_fmac_f32_dpp v40, -v52, v14 row_newbcast:14 row_mask:0xf bank_mask:0xf
	v_fmac_f32_dpp v41, -v52, v15 row_newbcast:15 row_mask:0xf bank_mask:0xf
	v_fmac_f32_dpp v40, -v53, v16 row_newbcast:0 row_mask:0xf bank_mask:0xf
	v_fmac_f32_dpp v41, -v53, v17 row_newbcast:1 row_mask:0xf bank_mask:0xf
	v_fmac_f32_dpp v40, -v53, v18 row_newbcast:2 row_mask:0xf bank_mask:0xf
	v_fmac_f32_dpp v41, -v53, v19 row_newbcast:3 row_mask:0xf bank_mask:0xf
	v_fmac_f32_dpp v40, -v53, v20 row_newbcast:4 row_mask:0xf bank_mask:0xf
	v_fmac_f32_dpp v41, -v53, v21 row_newbcast:5 row_mask:0xf bank_mask:0xf
	v_fmac_f32_dpp v40, -v53, v22 row_newbcast:6 row_mask:0xf bank_mask:0xf
	v_fmac_f32_dpp v41, -v53, v23 row_newbcast:7 row_mask:0xf bank_mask:0xf
	v_fmac_f32_dpp v40, -v53, v24 row_newbcast:8 row_mask:0xf bank_mask:0xf
	v_fmac_f32_dpp v41, -v53, v25 row_newbcast:9 row_mask:0xf bank_mask:0xf
	v_fmac_f32_dpp v40, -v53, v26 row_newbcast:10 row_mask:0xf bank_mask:0xf
	v_fmac_f32_dpp v41, -v53, v27 row_newbcast:11 row_mask:0xf bank_mask:0xf
	v_fmac_f32_dpp v40, -v53, v28 row_newbcast:12 row_mask:0xf bank_mask:0xf
	v_fmac_f32_dpp v41, -v53, v29 row_newbcast:13 row_mask:0xf bank_mask:0xf
	v_fmac_f32_dpp v40, -v53, v30 row_newbcast:14 row_mask:0xf bank_mask:0xf
	v_fmac_f32_dpp v41, -v53, v31 row_newbcast:15 row_mask:0xf bank_mask:0xf
	v_add_f32_e32 v42, v40, v41
	v_mov_b32_e32 v43, v42
	s_waitcnt lgkmcnt(0)
; #define LAS __attribute__((address_space(3)))
; __device__ __forceinline__ void phase_chunk_prep(const Params& p, LAS unsigned char* lds, int wave_s) {
;     ...
; #pragma unroll
;             for (int i = 0; i < 64; ++i) {
;                 float s0 = RHS[i * 256 + col], s1 = 0.f, s2 = 0.f, s3 = 0.f;
; #pragma unroll
;                 for (int j4 = 0; j4 < (i + 3) / 4; ++j4) { const f32x4 a = *(const LAS f32x4*)(AM + i * 64 + 4 * j4);
;                     s0 -= a.x * sol[4 * j4]; s1 -= a.y * sol[4 * j4 + 1]; s2 -= a.z * sol[4 * j4 + 2]; s3 -= a.w * sol[4 * j4 + 3]; }
;                 sol[i] = (s0 + s1) + (s2 + s3);
;             }
;             if (col < 128) {
; #pragma unroll
;                 for (int mm = 0; mm < 4; ++mm)
; #pragma unroll
;                     for (int q4 = 0; q4 < 4; ++q4)
;                         *(f32x4*)(U + ((((col >> 4) * 4 + mm) * 64 + q4 * 16 + (col & 15)) << 2)) = (f32x4){sol[16 * mm + 4 * q4], sol[16 * mm + 4 * q4 + 1], sol[16 * mm + 4 * q4 + 2], sol[16 * mm + 4 * q4 + 3]};
	v_mul_f32_e32 v44, v59, v39
	v_mov_b32_e32 v45, 0
	v_permlane32_swap_b32_e32 v42, v43
	v_fmac_f32_dpp v44, -v54, v0 row_newbcast:0 row_mask:0xf bank_mask:0xf
	v_fmac_f32_dpp v45, -v54, v1 row_newbcast:1 row_mask:0xf bank_mask:0xf
	v_add_f32_dpp v30, v42, v43 quad_perm:[0,1,2,3] row_mask:0xc bank_mask:0xf
	v_fmac_f32_dpp v44, -v54, v2 row_newbcast:2 row_mask:0xf bank_mask:0xf
	v_fmac_f32_dpp v45, -v54, v3 row_newbcast:3 row_mask:0xf bank_mask:0xf
	v_fmac_f32_dpp v44, -v54, v4 row_newbcast:4 row_mask:0xf bank_mask:0xf
	v_fmac_f32_dpp v45, -v54, v5 row_newbcast:5 row_mask:0xf bank_mask:0xf
	v_fmac_f32_dpp v44, -v54, v6 row_newbcast:6 row_mask:0xf bank_mask:0xf
	v_fmac_f32_dpp v45, -v54, v7 row_newbcast:7 row_mask:0xf bank_mask:0xf
	v_fmac_f32_dpp v44, -v54, v8 row_newbcast:8 row_mask:0xf bank_mask:0xf
	v_fmac_f32_dpp v45, -v54, v9 row_newbcast:9 row_mask:0xf bank_mask:0xf
	v_fmac_f32_dpp v44, -v54, v10 row_newbcast:10 row_mask:0xf bank_mask:0xf
	v_fmac_f32_dpp v45, -v54, v11 row_newbcast:11 row_mask:0xf bank_mask:0xf
	v_fmac_f32_dpp v44, -v54, v12 row_newbcast:12 row_mask:0xf bank_mask:0xf
	v_fmac_f32_dpp v45, -v54, v13 row_newbcast:13 row_mask:0xf bank_mask:0xf
	v_fmac_f32_dpp v44, -v54, v14 row_newbcast:14 row_mask:0xf bank_mask:0xf
	v_fmac_f32_dpp v45, -v54, v15 row_newbcast:15 row_mask:0xf bank_mask:0xf
	v_fmac_f32_dpp v44, -v55, v16 row_newbcast:0 row_mask:0xf bank_mask:0xf
	v_fmac_f32_dpp v45, -v55, v17 row_newbcast:1 row_mask:0xf bank_mask:0xf
	v_fmac_f32_dpp v44, -v55, v18 row_newbcast:2 row_mask:0xf bank_mask:0xf
	v_fmac_f32_dpp v45, -v55, v19 row_newbcast:3 row_mask:0xf bank_mask:0xf
	v_fmac_f32_dpp v44, -v55, v20 row_newbcast:4 row_mask:0xf bank_mask:0xf
	v_fmac_f32_dpp v45, -v55, v21 row_newbcast:5 row_mask:0xf bank_mask:0xf
	v_fmac_f32_dpp v44, -v55, v22 row_newbcast:6 row_mask:0xf bank_mask:0xf
	v_fmac_f32_dpp v45, -v55, v23 row_newbcast:7 row_mask:0xf bank_mask:0xf
	v_fmac_f32_dpp v44, -v55, v24 row_newbcast:8 row_mask:0xf bank_mask:0xf
	v_fmac_f32_dpp v45, -v55, v25 row_newbcast:9 row_mask:0xf bank_mask:0xf
	v_fmac_f32_dpp v44, -v55, v26 row_newbcast:10 row_mask:0xf bank_mask:0xf
	v_fmac_f32_dpp v45, -v55, v27 row_newbcast:11 row_mask:0xf bank_mask:0xf
	v_fmac_f32_dpp v44, -v55, v28 row_newbcast:12 row_mask:0xf bank_mask:0xf
	v_fmac_f32_dpp v45, -v55, v29 row_newbcast:13 row_mask:0xf bank_mask:0xf
	v_fmac_f32_dpp v45, -v55, v31 row_newbcast:15 row_mask:0xf bank_mask:0xf
	v_fmac_f32_dpp v44, -v55, v30 row_newbcast:14 row_mask:0xf bank_mask:0xf
	v_add_f32_e32 v46, v44, v45
	v_mov_b32_e32 v47, v46
	s_nop 1
	v_permlane32_swap_b32_e32 v46, v47
	s_nop 1
	v_add_f32_dpp v31, v46, v47 quad_perm:[0,1,2,3] row_mask:0xc bank_mask:0xf
	s_cmp_gt_u32 s84, 3
	s_cbranch_scc1 .Lfsub_wdec
	s_lshl_b32 s96, s16, 15
	s_add_u32 s96, s20, s96
	s_addc_u32 s97, s21, 0
	v_lshrrev_b32_e32 v72, 4, v35
	v_lshlrev_b32_e32 v72, 12, v72
	v_and_b32_e32 v73, 15, v35
	v_lshl_add_u32 v72, v73, 4, v72
	v_lshl_add_u32 v72, v34, 3, v72
	global_store_dwordx2 v72, v[0:1], s[96:97]
	global_store_dwordx2 v72, v[2:3], s[96:97] offset:256
	global_store_dwordx2 v72, v[4:5], s[96:97] offset:512
	global_store_dwordx2 v72, v[6:7], s[96:97] offset:768
	global_store_dwordx2 v72, v[8:9], s[96:97] offset:1024
	global_store_dwordx2 v72, v[10:11], s[96:97] offset:1280
	global_store_dwordx2 v72, v[12:13], s[96:97] offset:1536
	global_store_dwordx2 v72, v[14:15], s[96:97] offset:1792
	global_store_dwordx2 v72, v[16:17], s[96:97] offset:2048
	global_store_dwordx2 v72, v[18:19], s[96:97] offset:2304
	global_store_dwordx2 v72, v[20:21], s[96:97] offset:2560
	global_store_dwordx2 v72, v[22:23], s[96:97] offset:2816
	global_store_dwordx2 v72, v[24:25], s[96:97] offset:3072
	global_store_dwordx2 v72, v[26:27], s[96:97] offset:3328
	global_store_dwordx2 v72, v[28:29], s[96:97] offset:3584
	global_store_dwordx2 v72, v[30:31], s[96:97] offset:3840
	s_waitcnt vmcnt(16)
	s_branch .LBB0_663

; #define SCAN_COPY(srcbase, bufidx) do { _Pragma("unroll") for (int k = 0; k < 8; ++k) { const int pc = wave + 8 * k; if (pc < IMG_PIECES) \
;         __builtin_amdgcn_global_load_lds((const unsigned*)((srcbase) + pc * 1024 + lane * 16), (LAS unsigned*)(lds + (bufidx) * IMG_BYTES + pc * 1024), 16, 0, 0); } } while (0)
; #define SCAN_LOAD(n_, uu, z0, z1, gl) do { const float* U_ = U0 + (size_t)(n_) * 8192; const bf16_t* Z_ = Z0 + (size_t)(n_) * 64 * NQ; \
;         z0 = *(const u32x4*)Z_; z1 = *(const u32x4*)(Z_ + 8); \
;         _Pragma("unroll") for (int mm = 0; mm < 4; ++mm) uu[mm] = *(const f32x4*)(U_ + mm * 256); \
;         gl = GL[unit0 + (n_)]; } while (0)
; __device__ __forceinline__ void phase_scan(const Params& p, LAS unsigned char* lds, int bh, int wave_s) {
;     ...
;         { const int np = hasn ? n + 1 : n;
;           SCAN_COPY(chunk0 + (size_t)np * IMG_BYTES, cur ^ 1); SCAN_LOAD(np, unext, zr0, zr1, glnext); }
;         bf16_t ov[16];
;         bf16x8 Sb[4];
; #pragma unroll
;         for (int s = 0; s < 4; ++s) Sb[s] = acc2frag(Sacc[2 * s], Sacc[2 * s + 1]);
;         f32x4 vn[4], o[4];
;         bf16x8 wf[2][4], qf[2][4];
; #pragma unroll
;         for (int s = 0; s < 4; ++s) { wf[0][s] = ldfrag(img + IMG_WD + fr * SWD + 32 * s + 4 * fq); qf[0][s] = ldfrag(img + IMG_QD + fr * SWD + 32 * s + 4 * fq); }
; #pragma unroll
;         for (int mm = 0; mm < 4; ++mm) {
;             if (mm < 3) {
; #pragma unroll
;                 for (int s = 0; s < 4; ++s) { wf[(mm + 1) & 1][s] = ldfrag(img + IMG_WD + (16 * (mm + 1) + fr) * SWD + 32 * s + 4 * fq); qf[(mm + 1) & 1][s] = ldfrag(img + IMG_QD + (16 * (mm + 1) + fr) * SWD + 32 * s + 4 * fq); } }
;             f32x4 c = (f32x4){0.f, 0.f, 0.f, 0.f}, d = (f32x4){0.f, 0.f, 0.f, 0.f};
; #pragma unroll
;             for (int s = 0; s < 4; ++s) {
;                 c = __builtin_amdgcn_mfma_f32_16x16x32_bf16(wf[mm & 1][s], Sb[s], c, 0, 0, 0);
;                 d = __builtin_amdgcn_mfma_f32_16x16x32_bf16(qf[mm & 1][s], Sb[s], d, 0, 0, 0);
;             }
;             vn[mm] = ucur[mm] - c; o[mm] = d;
;         }
.LBB0_918:
	s_add_i32 s36, s3, -1
	s_and_b32 s57, s36, 1
	s_cmp_lg_u32 s50, 0x7c0000
	s_cselect_b32 s56, s3, 31
	s_mul_i32 s36, s56, 0xec00
	v_lshl_add_u64 v[48:49], v[74:75], 0, s[36:37]
	s_xor_b32 s36, s57, 1
	s_mul_i32 s36, s36, 0xec00
	s_add_i32 s36, s36, 0
	v_lshl_add_u64 v[200:201], v[48:49], 0, s[4:5]
	s_add_i32 s84, s36, s4
	v_lshl_add_u64 v[202:203], v[48:49], 0, s[38:39]
	s_add_i32 s85, s36, s38
	v_lshl_add_u64 v[204:205], v[48:49], 0, s[40:41]
	s_add_i32 s86, s36, s40
	v_lshl_add_u64 v[206:207], v[48:49], 0, s[42:43]
	s_add_i32 s87, s36, s42
	v_lshl_add_u64 v[208:209], v[48:49], 0, s[44:45]
	s_add_i32 s88, s36, s44
	v_lshl_add_u64 v[210:211], v[48:49], 0, s[46:47]
	s_add_i32 s89, s36, s46
	v_lshl_add_u64 v[212:213], v[48:49], 0, s[48:49]
	s_add_i32 s90, s36, s48
	v_lshl_add_u64 v[214:215], v[48:49], 0, s[34:35]
	s_add_i32 s91, s36, s34
	s_mov_b32 m0, s84
	s_nop 0
	global_load_lds_dwordx4 v[200:201], off
	s_mov_b32 m0, s85
	s_nop 0
	global_load_lds_dwordx4 v[202:203], off
.LBB0_934:
	s_mul_i32 s36, s57, 0xec00
	s_mov_b32 s57, s37
	s_lshl_b64 s[60:61], s[56:57], 15
	s_ashr_i32 s57, s56, 31
	s_lshl_b64 s[58:59], s[56:57], 2
	s_add_u32 s58, s25, s58
	s_addc_u32 s59, s62, s59
	s_add_i32 s36, s36, 0
	v_lshlrev_b32_e32 v107, 1, v87
	v_add3_u32 v116, s36, v76, v107
	ds_read2_b64 v[48:51], v116 offset1:4
	v_add_u32_e32 v120, 0x4000, v116
	ds_read2_b64 v[64:67], v116 offset0:8 offset1:12
	ds_read2_b64 v[60:63], v120 offset0:64 offset1:68
	v_cvt_pk_bf16_f32 v56, v28, v29
	v_cvt_pk_bf16_f32 v57, v30, v31
	v_cvt_pk_bf16_f32 v58, v24, v25
	v_cvt_pk_bf16_f32 v59, v26, v27
	ds_read2_b64 v[68:71], v120 offset0:72 offset1:76
	v_cvt_pk_bf16_f32 v52, v20, v21
	s_waitcnt lgkmcnt(0)
	v_mfma_f32_16x16x32_bf16 v[48:51], v[48:51], v[56:59], 0
	v_cvt_pk_bf16_f32 v53, v22, v23
	v_cvt_pk_bf16_f32 v54, v16, v17
	v_cvt_pk_bf16_f32 v55, v18, v19
	ds_read2_b64 v[112:115], v116 offset0:16 offset1:20
	v_mfma_f32_16x16x32_bf16 v[60:63], v[60:63], v[56:59], 0
	ds_read2_b64 v[116:119], v116 offset0:24 offset1:28
	v_cvt_pk_bf16_f32 v108, v12, v13
	v_cvt_pk_bf16_f32 v109, v14, v15
	v_mfma_f32_16x16x32_bf16 v[48:51], v[64:67], v[52:55], v[48:51]
	ds_read2_b64 v[64:67], v120 offset0:80 offset1:84
	v_cvt_pk_bf16_f32 v110, v8, v9
	v_cvt_pk_bf16_f32 v111, v10, v11
	v_mfma_f32_16x16x32_bf16 v[60:63], v[68:71], v[52:55], v[60:63]
	v_add3_u32 v107, s36, v107, v76
	v_cvt_pk_bf16_f32 v68, v4, v5
	v_cvt_pk_bf16_f32 v69, v6, v7
	s_waitcnt lgkmcnt(0)
	v_mfma_f32_16x16x32_bf16 v[48:51], v[112:115], v[108:111], v[48:51]
	v_cvt_pk_bf16_f32 v70, v0, v1
	v_cvt_pk_bf16_f32 v71, v2, v3
	v_add_u32_e32 v124, 0x1000, v107
	v_mfma_f32_16x16x32_bf16 v[60:63], v[64:67], v[108:111], v[60:63]
	s_mov_b32 m0, s86
	s_nop 0
	global_load_lds_dwordx4 v[204:205], off
	ds_read2_b64 v[64:67], v120 offset0:88 offset1:92
	v_add_u32_e32 v125, 0x5000, v107
	ds_read2_b64 v[120:123], v125 offset0:88 offset1:92
	v_mfma_f32_16x16x32_bf16 v[112:115], v[116:119], v[68:71], v[48:51]
	ds_read2_b64 v[116:119], v124 offset0:16 offset1:20
	v_add_u32_e32 v132, 0x2000, v107
	v_add_u32_e32 v133, 0x6000, v107
	s_waitcnt lgkmcnt(0)
	v_mfma_f32_16x16x32_bf16 v[48:51], v[64:67], v[68:71], v[60:63]
	ds_read2_b64 v[128:131], v133 offset0:104 offset1:108
	s_nop 1
	ds_read2_b64 v[60:63], v125 offset0:80 offset1:84
	v_add_u32_e32 v137, 0x3000, v107
	v_mfma_f32_16x16x32_bf16 v[64:67], v[116:119], v[56:59], 0
	ds_read2_b64 v[116:119], v124 offset0:24 offset1:28
	v_sub_f32_e32 v136, v35, v115
	v_sub_f32_e32 v138, v34, v114
	s_waitcnt lgkmcnt(0)
	v_mfma_f32_16x16x32_bf16 v[60:63], v[60:63], v[56:59], 0
	v_add_u32_e32 v107, 0x7000, v107
	v_pk_mul_f32 v[30:31], v[30:31], v[84:85] op_sel_hi:[1,0]
	v_pk_mul_f32 v[28:29], v[28:29], v[84:85] op_sel_hi:[1,0]
	v_mfma_f32_16x16x32_bf16 v[64:67], v[116:119], v[52:55], v[64:67]
	ds_read2_b64 v[116:119], v124 offset0:32 offset1:36
	v_pk_mul_f32 v[26:27], v[26:27], v[84:85] op_sel_hi:[1,0]
	v_pk_mul_f32 v[24:25], v[24:25], v[84:85] op_sel_hi:[1,0]
	v_mfma_f32_16x16x32_bf16 v[60:63], v[120:123], v[52:55], v[60:63]
	s_mov_b32 m0, s87
	s_nop 0
	global_load_lds_dwordx4 v[206:207], off
	ds_read2_b64 v[120:123], v125 offset0:96 offset1:100
	v_pk_mul_f32 v[22:23], v[22:23], v[84:85] op_sel_hi:[1,0]
	v_pk_mul_f32 v[20:21], v[20:21], v[84:85] op_sel_hi:[1,0]
	s_waitcnt lgkmcnt(0)
	v_mfma_f32_16x16x32_bf16 v[64:67], v[116:119], v[108:111], v[64:67]
	ds_read2_b64 v[116:119], v124 offset0:40 offset1:44
	v_pk_mul_f32 v[18:19], v[18:19], v[84:85] op_sel_hi:[1,0]
	v_pk_mul_f32 v[16:17], v[16:17], v[84:85] op_sel_hi:[1,0]
	v_mfma_f32_16x16x32_bf16 v[60:63], v[120:123], v[108:111], v[60:63]
	ds_read2_b64 v[120:123], v125 offset0:104 offset1:108
	ds_read2_b64 v[124:127], v132 offset0:40 offset1:44
	v_pk_mul_f32 v[14:15], v[14:15], v[84:85] op_sel_hi:[1,0]
	s_waitcnt lgkmcnt(0)
	v_mfma_f32_16x16x32_bf16 v[64:67], v[116:119], v[68:71], v[64:67]
	ds_read2_b64 v[116:119], v132 offset0:32 offset1:36
	v_pk_mul_f32 v[12:13], v[12:13], v[84:85] op_sel_hi:[1,0]
	v_pk_mul_f32 v[10:11], v[10:11], v[84:85] op_sel_hi:[1,0]
	v_mfma_f32_16x16x32_bf16 v[60:63], v[120:123], v[68:71], v[60:63]
	ds_read2_b64 v[120:123], v133 offset0:96 offset1:100
	s_nop 2
	v_sub_f32_e32 v139, v37, v65
	v_sub_f32_e32 v140, v36, v64
	s_waitcnt lgkmcnt(0)
	v_mfma_f32_16x16x32_bf16 v[116:119], v[116:119], v[56:59], 0
	v_mul_f32_e64 v8, v8, v84
	v_mul_f32_e64 v9, v9, v84
	v_pk_mul_f32 v[6:7], v[6:7], v[84:85] op_sel_hi:[1,0]
	v_pk_mul_f32 v[4:5], v[4:5], v[84:85] op_sel_hi:[1,0]
	v_mfma_f32_16x16x32_bf16 v[120:123], v[120:123], v[56:59], 0
	s_mov_b32 m0, s88
	s_nop 0
	global_load_lds_dwordx4 v[208:209], off
	v_mul_f32_e64 v2, v2, v84
	v_mul_f32_e64 v3, v3, v84
	v_pk_mul_f32 v[0:1], v[0:1], v[84:85] op_sel_hi:[1,0]
	v_mfma_f32_16x16x32_bf16 v[116:119], v[124:127], v[52:55], v[116:119]
	ds_read2_b64 v[124:127], v132 offset0:48 offset1:52
	v_mfma_f32_16x16x32_bf16 v[120:123], v[128:131], v[52:55], v[120:123]
	ds_read2_b64 v[128:131], v133 offset0:112 offset1:116
	s_waitcnt lgkmcnt(0)
; __device__ __forceinline__ void phase_scan(const Params& p, LAS unsigned char* lds, int bh, int wave_s) {
;     ...
;         bf16x8 kq[4][2], kt[4][2];
; #pragma unroll
;         for (int mm = 0; mm < 4; ++mm)
; #pragma unroll
;             for (int s = 0; s < 2; ++s) kq[mm][s] = ldfrag(img + IMG_QK + (16 * mm + fr) * SKT + 32 * s + 4 * fq);
; #pragma unroll
;         for (int m = 0; m < 4; ++m)
; #pragma unroll
;             for (int s = 0; s < 2; ++s) kt[m][s] = ldfrag(img + IMG_KT + (16 * m + fr) * SKT + 32 * s + 4 * fq);
;         bf16x8 vb[2];
; #pragma unroll
;         for (int s = 0; s < 2; ++s) vb[s] = acc2frag(vn[2 * s], vn[2 * s + 1]);
; #pragma unroll
;         for (int mm = 0; mm < 4; ++mm)
; #pragma unroll
;             for (int s = 0; s < 2; ++s) o[mm] = __builtin_amdgcn_mfma_f32_16x16x32_bf16(kq[mm][s], vb[s], o[mm], 0, 0, 0);
; #pragma unroll
;         for (int m = 0; m < 4; ++m)
; #pragma unroll
;             for (int s = 0; s < 2; ++s) kq[m][s] = ldfrag(img + IMG_KT + (16 * (m + 4) + fr) * SKT + 32 * s + 4 * fq);
; #pragma unroll
;         for (int m = 0; m < 4; ++m) {
;             f32x4 c = Sacc[m] * glcur;
; #pragma unroll
;             for (int s = 0; s < 2; ++s) c = __builtin_amdgcn_mfma_f32_16x16x32_bf16(kt[m][s], vb[s], c, 0, 0, 0);
;             Sacc[m] = c;
;         }
; #pragma unroll
;         for (int m = 0; m < 4; ++m) {
;             f32x4 c = Sacc[m + 4] * glcur;
; #pragma unroll
;             for (int s = 0; s < 2; ++s) c = __builtin_amdgcn_mfma_f32_16x16x32_bf16(kq[m][s], vb[s], c, 0, 0, 0);
;             Sacc[m + 4] = c;
;         }
	v_mfma_f32_16x16x32_bf16 v[116:119], v[124:127], v[108:111], v[116:119]
	ds_read2_b64 v[124:127], v132 offset0:56 offset1:60
	ds_read2_b64 v[132:135], v133 offset0:120 offset1:124
	v_mfma_f32_16x16x32_bf16 v[120:123], v[128:131], v[108:111], v[120:123]
	ds_read2_b64 v[128:131], v137 offset0:48 offset1:52
	s_waitcnt lgkmcnt(0)
	v_mfma_f32_16x16x32_bf16 v[120:123], v[132:135], v[68:71], v[120:123]
	v_sub_f32_e32 v132, v33, v113
	v_sub_f32_e32 v133, v32, v112
	ds_read2_b64 v[32:35], v137 offset0:56 offset1:60
	v_mfma_f32_16x16x32_bf16 v[112:115], v[128:131], v[56:59], 0
	s_mov_b32 m0, s89
	s_nop 0
	global_load_lds_dwordx4 v[210:211], off
	ds_read2_b64 v[128:131], v137 offset0:64 offset1:68
	v_sub_f32_e32 v134, v39, v67
	v_sub_f32_e32 v135, v38, v66
	v_mfma_f32_16x16x32_bf16 v[116:119], v[124:127], v[68:71], v[116:119]
	ds_read2_b64 v[124:127], v107 offset0:112 offset1:116
	ds_read2_b64 v[36:39], v137 offset0:72 offset1:76
	s_waitcnt lgkmcnt(0)
	v_mfma_f32_16x16x32_bf16 v[32:35], v[32:35], v[52:55], v[112:115]
	v_mfma_f32_16x16x32_bf16 v[32:35], v[128:131], v[108:111], v[32:35]
	v_add3_u32 v130, s36, v89, v96
	s_nop 1
	v_sub_f32_e32 v116, v40, v116
	v_add_u32_e32 v40, 0xc800, v130
	v_mfma_f32_16x16x32_bf16 v[56:59], v[124:127], v[56:59], 0
	ds_read2_b64 v[64:67], v107 offset0:120 offset1:124
	ds_read2_b64 v[112:115], v107 offset0:128 offset1:132
	ds_read2_b64 v[124:127], v107 offset0:136 offset1:140
	v_sub_f32_e32 v107, v43, v119
	v_sub_f32_e32 v118, v42, v118
	v_mfma_f32_16x16x32_bf16 v[32:35], v[36:39], v[68:71], v[32:35]
	v_sub_f32_e32 v117, v41, v117
	v_add_u32_e32 v131, 0x8000, v130
	s_nop 5
	v_sub_f32_e32 v119, v47, v35
	v_sub_f32_e32 v128, v46, v34
	s_waitcnt lgkmcnt(0)
	v_mfma_f32_16x16x32_bf16 v[34:37], v[64:67], v[52:55], v[56:59]
	s_mov_b32 m0, s90
	s_nop 0
	global_load_lds_dwordx4 v[212:213], off
	v_sub_f32_e32 v52, v45, v33
	v_sub_f32_e32 v53, v44, v32
	v_add_u32_e32 v54, 0xd000, v130
	v_mfma_f32_16x16x32_bf16 v[32:35], v[112:115], v[108:111], v[34:37]
	s_nop 3
	ds_read2_b64 v[36:39], v40 offset1:4
	ds_read2_b64 v[40:43], v40 offset0:8 offset1:12
	v_cvt_pk_bf16_f32 v108, v133, v132
	v_cvt_pk_bf16_f32 v109, v138, v136
	v_cvt_pk_bf16_f32 v110, v140, v139
	v_cvt_pk_bf16_f32 v111, v135, v134
	v_mfma_f32_16x16x32_bf16 v[44:47], v[124:127], v[68:71], v[32:35]
	v_cvt_pk_bf16_f32 v112, v116, v117
	v_cvt_pk_bf16_f32 v113, v118, v107
	v_cvt_pk_bf16_f32 v114, v53, v52
	ds_read2_b64 v[32:35], v54 offset0:16 offset1:20
	s_waitcnt lgkmcnt(0)
	v_mfma_f32_16x16x32_bf16 v[36:39], v[36:39], v[108:111], v[48:51]
	v_cvt_pk_bf16_f32 v115, v128, v119
	v_lshl_add_u64 v[128:129], v[80:81], 0, s[60:61]
	s_nop 0
	v_mfma_f32_16x16x32_bf16 v[68:71], v[40:43], v[112:115], v[36:39]
	v_add_u32_e32 v48, 0xd800, v130
	ds_read2_b64 v[40:43], v48 offset0:32 offset1:36
	ds_read2_b64 v[56:59], v48 offset0:40 offset1:44
	s_nop 0
	ds_read2_b64 v[36:39], v54 offset0:24 offset1:28
	v_mfma_f32_16x16x32_bf16 v[32:35], v[32:35], v[108:111], v[60:63]
	s_nop 1
	v_mul_f32_e32 v84, v68, v68
	s_waitcnt lgkmcnt(0)
	v_mfma_f32_16x16x32_bf16 v[64:67], v[36:39], v[112:115], v[32:35]
	s_cmp_lt_u32 s4, 0xc00
	s_cbranch_scc0 .Lscan_dma7_skip
	s_mov_b32 m0, s91
	s_nop 0
	global_load_lds_dwordx4 v[214:215], off
.Lscan_dma7_skip:
	v_add_u32_e32 v38, 0xe000, v130
	ds_read2_b64 v[116:119], v38 offset0:48 offset1:52
	v_mad_u64_u32 v[36:37], s[56:57], s56, v105, v[78:79]
	v_mfma_f32_16x16x32_bf16 v[32:35], v[40:43], v[108:111], v[120:123]
	global_load_dwordx4 v[48:51], v[36:37], off offset:16
	global_load_dwordx4 v[52:55], v[36:37], off
	v_mov_b32_dpp v84, v84 quad_perm:[1,0,3,2] row_mask:0xf bank_mask:0xf bound_ctrl:1
	ds_read2_b64 v[120:123], v38 offset0:56 offset1:60
	v_mfma_f32_16x16x32_bf16 v[60:63], v[56:59], v[112:115], v[32:35]
	s_nop 2
	global_load_dwordx4 v[32:35], v[128:129], off
	global_load_dwordx4 v[36:39], v[128:129], off offset:1024
	ds_read2_b64 v[124:127], v131 offset0:128 offset1:132
	v_fmac_f32_e32 v84, v68, v68
	s_waitcnt lgkmcnt(0)
	v_mfma_f32_16x16x32_bf16 v[56:59], v[116:119], v[108:111], v[44:47]
	global_load_dwordx4 v[40:43], v[128:129], off offset:2048
	s_nop 1
	global_load_dwordx4 v[44:47], v[128:129], off offset:3072
	global_load_dword v107, v77, s[58:59]
	ds_read2_b64 v[116:119], v131 offset0:136 offset1:140
	v_add_u32_e32 v128, 0x8800, v130
	v_mfma_f32_16x16x32_bf16 v[56:59], v[120:123], v[112:115], v[56:59]
	v_add_f32_dpp v84, v84, v84 quad_perm:[2,3,0,1] row_mask:0xf bank_mask:0xf bound_ctrl:1
	v_mfma_f32_16x16x32_bf16 v[28:31], v[124:127], v[108:111], v[28:31]
	ds_read2_b64 v[120:123], v128 offset0:144 offset1:148
	ds_read2_b64 v[124:127], v128 offset0:152 offset1:156
	v_add_u32_e32 v128, 0x9000, v130
	v_add_f32_dpp v84, v84, v84 row_half_mirror row_mask:0xf bank_mask:0xf bound_ctrl:1
	s_waitcnt lgkmcnt(0)
	v_mfma_f32_16x16x32_bf16 v[24:27], v[120:123], v[108:111], v[24:27]
	v_mfma_f32_16x16x32_bf16 v[28:31], v[116:119], v[112:115], v[28:31]
	ds_read2_b64 v[116:119], v128 offset0:160 offset1:164
	ds_read2_b64 v[120:123], v128 offset0:168 offset1:172
	v_mfma_f32_16x16x32_bf16 v[24:27], v[124:127], v[112:115], v[24:27]
	v_add_u32_e32 v124, 0x9800, v130
	s_waitcnt lgkmcnt(0)
	v_mfma_f32_16x16x32_bf16 v[20:23], v[116:119], v[108:111], v[20:23]
	ds_read2_b64 v[116:119], v124 offset0:176 offset1:180
	ds_read2_b64 v[124:127], v124 offset0:184 offset1:188
	v_mfma_f32_16x16x32_bf16 v[20:23], v[120:123], v[112:115], v[20:23]
	v_add_u32_e32 v120, 0xa000, v130
	s_waitcnt lgkmcnt(0)
	v_mfma_f32_16x16x32_bf16 v[16:19], v[116:119], v[108:111], v[16:19]
	ds_read2_b64 v[116:119], v120 offset0:192 offset1:196
	ds_read2_b64 v[120:123], v120 offset0:200 offset1:204
	v_mfma_f32_16x16x32_bf16 v[16:19], v[124:127], v[112:115], v[16:19]
	v_add_u32_e32 v124, 0xa800, v130
	s_waitcnt lgkmcnt(0)
; __device__ __forceinline__ void phase_scan(const Params& p, LAS unsigned char* lds, int bh, int wave_s) {
;     ...
;         for (int m = 0; m < 4; ++m) {
;             f32x4 c = Sacc[m] * glcur;
; #pragma unroll
;             for (int s = 0; s < 2; ++s) c = __builtin_amdgcn_mfma_f32_16x16x32_bf16(kt[m][s], vb[s], c, 0, 0, 0);
;             Sacc[m] = c;
;         }
; #pragma unroll
;         for (int m = 0; m < 4; ++m) {
;             f32x4 c = Sacc[m + 4] * glcur;
; #pragma unroll
;             for (int s = 0; s < 2; ++s) c = __builtin_amdgcn_mfma_f32_16x16x32_bf16(kq[m][s], vb[s], c, 0, 0, 0);
;             Sacc[m + 4] = c;
;         }
; #pragma unroll
;         for (int mm = 0; mm < 4; ++mm)
; #pragma unroll
;             for (int rg = 0; rg < 4; ++rg) { const float sr = dpp_sum16(o[mm][rg] * o[mm][rg]);
;                 if (fr == 0) SCR[(16 * mm + 4 * fq + rg) * 8 + wave] = sr; }
	v_mfma_f32_16x16x32_bf16 v[12:15], v[116:119], v[108:111], v[12:15]
	ds_read2_b64 v[116:119], v124 offset0:208 offset1:212
	ds_read2_b64 v[124:127], v124 offset0:216 offset1:220
	v_mfma_f32_16x16x32_bf16 v[12:15], v[120:123], v[112:115], v[12:15]
	v_add_u32_e32 v120, 0xb000, v130
	s_waitcnt lgkmcnt(0)
	v_mfma_f32_16x16x32_bf16 v[8:11], v[116:119], v[108:111], v[8:11]
	ds_read2_b64 v[116:119], v120 offset0:224 offset1:228
	ds_read2_b64 v[120:123], v120 offset0:232 offset1:236
	v_mfma_f32_16x16x32_bf16 v[8:11], v[124:127], v[112:115], v[8:11]
	v_add_u32_e32 v124, 0xb800, v130
	s_waitcnt lgkmcnt(0)
	v_mfma_f32_16x16x32_bf16 v[4:7], v[116:119], v[108:111], v[4:7]
	ds_read2_b64 v[116:119], v124 offset0:240 offset1:244
	ds_read2_b64 v[124:127], v124 offset0:248 offset1:252
	s_waitcnt lgkmcnt(0)
	v_mfma_f32_16x16x32_bf16 v[0:3], v[116:119], v[108:111], v[0:3]
	v_mov_b32_dpp v108, v84 row_mirror row_mask:0xf bank_mask:0xf bound_ctrl:1
	v_mfma_f32_16x16x32_bf16 v[4:7], v[120:123], v[112:115], v[4:7]
	v_mfma_f32_16x16x32_bf16 v[0:3], v[124:127], v[112:115], v[0:3]
	s_and_saveexec_b64 s[56:57], s[0:1]
	v_add_f32_e32 v84, v84, v108
	ds_write_b32 v106, v84
	s_or_b64 exec, exec, s[56:57]
	v_mul_f32_e32 v84, v69, v69
	s_nop 1
	v_mov_b32_dpp v84, v84 quad_perm:[1,0,3,2] row_mask:0xf bank_mask:0xf bound_ctrl:1
	v_fmac_f32_e32 v84, v69, v69
	s_nop 1
	v_add_f32_dpp v84, v84, v84 quad_perm:[2,3,0,1] row_mask:0xf bank_mask:0xf bound_ctrl:1
	s_nop 1
	v_add_f32_dpp v84, v84, v84 row_half_mirror row_mask:0xf bank_mask:0xf bound_ctrl:1
	s_nop 1
	v_mov_b32_dpp v108, v84 row_mirror row_mask:0xf bank_mask:0xf bound_ctrl:1
	s_and_saveexec_b64 s[56:57], s[0:1]
	v_add_f32_e32 v84, v84, v108
	ds_write_b32 v106, v84 offset:32
	s_or_b64 exec, exec, s[56:57]
	v_mul_f32_e32 v84, v70, v70
	s_nop 1
	v_mov_b32_dpp v84, v84 quad_perm:[1,0,3,2] row_mask:0xf bank_mask:0xf bound_ctrl:1
	v_fmac_f32_e32 v84, v70, v70
	s_nop 1
	v_add_f32_dpp v84, v84, v84 quad_perm:[2,3,0,1] row_mask:0xf bank_mask:0xf bound_ctrl:1
	s_nop 1
	v_add_f32_dpp v84, v84, v84 row_half_mirror row_mask:0xf bank_mask:0xf bound_ctrl:1
	s_nop 1
	v_mov_b32_dpp v108, v84 row_mirror row_mask:0xf bank_mask:0xf bound_ctrl:1
	s_and_saveexec_b64 s[56:57], s[0:1]
	v_add_f32_e32 v84, v84, v108
	ds_write_b32 v106, v84 offset:64
	s_or_b64 exec, exec, s[56:57]
	v_mul_f32_e32 v84, v71, v71
	s_nop 1
	v_mov_b32_dpp v84, v84 quad_perm:[1,0,3,2] row_mask:0xf bank_mask:0xf bound_ctrl:1
	v_fmac_f32_e32 v84, v71, v71
	s_nop 1
	v_add_f32_dpp v84, v84, v84 quad_perm:[2,3,0,1] row_mask:0xf bank_mask:0xf bound_ctrl:1
	s_nop 1
	v_add_f32_dpp v84, v84, v84 row_half_mirror row_mask:0xf bank_mask:0xf bound_ctrl:1
	s_nop 1
	v_mov_b32_dpp v108, v84 row_mirror row_mask:0xf bank_mask:0xf bound_ctrl:1
	s_and_saveexec_b64 s[56:57], s[0:1]
	v_add_f32_e32 v84, v84, v108
	ds_write_b32 v106, v84 offset:96
	s_or_b64 exec, exec, s[56:57]
	v_mul_f32_e32 v84, v64, v64
	s_nop 1
	v_mov_b32_dpp v84, v84 quad_perm:[1,0,3,2] row_mask:0xf bank_mask:0xf bound_ctrl:1
	v_fmac_f32_e32 v84, v64, v64
	s_nop 1
	v_add_f32_dpp v84, v84, v84 quad_perm:[2,3,0,1] row_mask:0xf bank_mask:0xf bound_ctrl:1
	s_nop 1
	v_add_f32_dpp v84, v84, v84 row_half_mirror row_mask:0xf bank_mask:0xf bound_ctrl:1
	s_nop 1
	v_mov_b32_dpp v108, v84 row_mirror row_mask:0xf bank_mask:0xf bound_ctrl:1
	s_and_saveexec_b64 s[56:57], s[0:1]
	v_add_f32_e32 v84, v84, v108
	ds_write_b32 v97, v84
	s_or_b64 exec, exec, s[56:57]
	v_mul_f32_e32 v84, v65, v65
	s_nop 1
	v_mov_b32_dpp v84, v84 quad_perm:[1,0,3,2] row_mask:0xf bank_mask:0xf bound_ctrl:1
	v_fmac_f32_e32 v84, v65, v65
	s_nop 1
	v_add_f32_dpp v84, v84, v84 quad_perm:[2,3,0,1] row_mask:0xf bank_mask:0xf bound_ctrl:1
	s_nop 1
	v_add_f32_dpp v84, v84, v84 row_half_mirror row_mask:0xf bank_mask:0xf bound_ctrl:1
	s_nop 1
	v_mov_b32_dpp v108, v84 row_mirror row_mask:0xf bank_mask:0xf bound_ctrl:1
	s_and_saveexec_b64 s[56:57], s[0:1]
	v_add_f32_e32 v84, v84, v108
	ds_write_b32 v106, v84 offset:544
	s_or_b64 exec, exec, s[56:57]
	v_mul_f32_e32 v84, v66, v66
	s_nop 1
	v_mov_b32_dpp v84, v84 quad_perm:[1,0,3,2] row_mask:0xf bank_mask:0xf bound_ctrl:1
	v_fmac_f32_e32 v84, v66, v66
	s_nop 1
	v_add_f32_dpp v84, v84, v84 quad_perm:[2,3,0,1] row_mask:0xf bank_mask:0xf bound_ctrl:1
	s_nop 1
	v_add_f32_dpp v84, v84, v84 row_half_mirror row_mask:0xf bank_mask:0xf bound_ctrl:1
	s_nop 1
	v_mov_b32_dpp v108, v84 row_mirror row_mask:0xf bank_mask:0xf bound_ctrl:1
	s_and_saveexec_b64 s[56:57], s[0:1]
	v_add_f32_e32 v84, v84, v108
	ds_write_b32 v106, v84 offset:576
	s_or_b64 exec, exec, s[56:57]
	v_mul_f32_e32 v84, v67, v67
	s_nop 1
	v_mov_b32_dpp v84, v84 quad_perm:[1,0,3,2] row_mask:0xf bank_mask:0xf bound_ctrl:1
	v_fmac_f32_e32 v84, v67, v67
	s_nop 1
	v_add_f32_dpp v84, v84, v84 quad_perm:[2,3,0,1] row_mask:0xf bank_mask:0xf bound_ctrl:1
; #define BAR_LDS() do { asm volatile("s_waitcnt lgkmcnt(0)" ::: "memory"); __builtin_amdgcn_s_barrier(); asm volatile("" ::: "memory"); } while (0)
; __device__ __forceinline__ void phase_scan(const Params& p, LAS unsigned char* lds, int bh, int wave_s) {
;     ...
; #pragma unroll
;         for (int mm = 0; mm < 4; ++mm)
; #pragma unroll
;             for (int rg = 0; rg < 4; ++rg) { const float sr = dpp_sum16(o[mm][rg] * o[mm][rg]);
;                 if (fr == 0) SCR[(16 * mm + 4 * fq + rg) * 8 + wave] = sr; }
;         BAR_LDS();
	s_nop 1
	v_add_f32_dpp v84, v84, v84 row_half_mirror row_mask:0xf bank_mask:0xf bound_ctrl:1
	s_nop 1
	v_mov_b32_dpp v108, v84 row_mirror row_mask:0xf bank_mask:0xf bound_ctrl:1
	s_and_saveexec_b64 s[56:57], s[0:1]
	v_add_f32_e32 v84, v84, v108
	ds_write_b32 v106, v84 offset:608
	s_or_b64 exec, exec, s[56:57]
	v_mul_f32_e32 v84, v60, v60
	s_nop 1
	v_mov_b32_dpp v84, v84 quad_perm:[1,0,3,2] row_mask:0xf bank_mask:0xf bound_ctrl:1
	v_fmac_f32_e32 v84, v60, v60
	s_nop 1
	v_add_f32_dpp v84, v84, v84 quad_perm:[2,3,0,1] row_mask:0xf bank_mask:0xf bound_ctrl:1
	s_nop 1
	v_add_f32_dpp v84, v84, v84 row_half_mirror row_mask:0xf bank_mask:0xf bound_ctrl:1
	s_nop 1
	v_mov_b32_dpp v108, v84 row_mirror row_mask:0xf bank_mask:0xf bound_ctrl:1
	s_and_saveexec_b64 s[56:57], s[0:1]
	v_add_f32_e32 v84, v84, v108
	ds_write_b32 v98, v84
	s_or_b64 exec, exec, s[56:57]
	v_mul_f32_e32 v84, v61, v61
	s_nop 1
	v_mov_b32_dpp v84, v84 quad_perm:[1,0,3,2] row_mask:0xf bank_mask:0xf bound_ctrl:1
	v_fmac_f32_e32 v84, v61, v61
	s_nop 1
	v_add_f32_dpp v84, v84, v84 quad_perm:[2,3,0,1] row_mask:0xf bank_mask:0xf bound_ctrl:1
	s_nop 1
	v_add_f32_dpp v84, v84, v84 row_half_mirror row_mask:0xf bank_mask:0xf bound_ctrl:1
	s_nop 1
	v_mov_b32_dpp v108, v84 row_mirror row_mask:0xf bank_mask:0xf bound_ctrl:1
	s_and_saveexec_b64 s[56:57], s[0:1]
	v_add_f32_e32 v84, v84, v108
	ds_write_b32 v106, v84 offset:1056
	s_or_b64 exec, exec, s[56:57]
	v_mul_f32_e32 v84, v62, v62
	s_nop 1
	v_mov_b32_dpp v84, v84 quad_perm:[1,0,3,2] row_mask:0xf bank_mask:0xf bound_ctrl:1
	v_fmac_f32_e32 v84, v62, v62
	s_nop 1
	v_add_f32_dpp v84, v84, v84 quad_perm:[2,3,0,1] row_mask:0xf bank_mask:0xf bound_ctrl:1
	s_nop 1
	v_add_f32_dpp v84, v84, v84 row_half_mirror row_mask:0xf bank_mask:0xf bound_ctrl:1
	s_nop 1
	v_mov_b32_dpp v108, v84 row_mirror row_mask:0xf bank_mask:0xf bound_ctrl:1
	s_and_saveexec_b64 s[56:57], s[0:1]
	v_add_f32_e32 v84, v84, v108
	ds_write_b32 v106, v84 offset:1088
	s_or_b64 exec, exec, s[56:57]
	v_mul_f32_e32 v84, v63, v63
	s_nop 1
	v_mov_b32_dpp v84, v84 quad_perm:[1,0,3,2] row_mask:0xf bank_mask:0xf bound_ctrl:1
	v_fmac_f32_e32 v84, v63, v63
	s_nop 1
	v_add_f32_dpp v84, v84, v84 quad_perm:[2,3,0,1] row_mask:0xf bank_mask:0xf bound_ctrl:1
	s_nop 1
	v_add_f32_dpp v84, v84, v84 row_half_mirror row_mask:0xf bank_mask:0xf bound_ctrl:1
	s_nop 1
	v_mov_b32_dpp v108, v84 row_mirror row_mask:0xf bank_mask:0xf bound_ctrl:1
	s_and_saveexec_b64 s[56:57], s[0:1]
	v_add_f32_e32 v84, v84, v108
	ds_write_b32 v106, v84 offset:1120
	s_or_b64 exec, exec, s[56:57]
	v_mul_f32_e32 v84, v56, v56
	s_nop 1
	v_mov_b32_dpp v84, v84 quad_perm:[1,0,3,2] row_mask:0xf bank_mask:0xf bound_ctrl:1
	v_fmac_f32_e32 v84, v56, v56
	s_nop 1
	v_add_f32_dpp v84, v84, v84 quad_perm:[2,3,0,1] row_mask:0xf bank_mask:0xf bound_ctrl:1
	s_nop 1
	v_add_f32_dpp v84, v84, v84 row_half_mirror row_mask:0xf bank_mask:0xf bound_ctrl:1
	s_nop 1
	v_mov_b32_dpp v108, v84 row_mirror row_mask:0xf bank_mask:0xf bound_ctrl:1
	s_and_saveexec_b64 s[56:57], s[0:1]
	v_add_f32_e32 v84, v84, v108
	ds_write_b32 v99, v84
	s_or_b64 exec, exec, s[56:57]
	v_mul_f32_e32 v84, v57, v57
	s_nop 1
	v_mov_b32_dpp v84, v84 quad_perm:[1,0,3,2] row_mask:0xf bank_mask:0xf bound_ctrl:1
	v_fmac_f32_e32 v84, v57, v57
	s_nop 1
	v_add_f32_dpp v84, v84, v84 quad_perm:[2,3,0,1] row_mask:0xf bank_mask:0xf bound_ctrl:1
	s_nop 1
	v_add_f32_dpp v84, v84, v84 row_half_mirror row_mask:0xf bank_mask:0xf bound_ctrl:1
	s_nop 1
	v_mov_b32_dpp v108, v84 row_mirror row_mask:0xf bank_mask:0xf bound_ctrl:1
	s_and_saveexec_b64 s[56:57], s[0:1]
	v_add_f32_e32 v84, v84, v108
	ds_write_b32 v106, v84 offset:1568
	s_or_b64 exec, exec, s[56:57]
	v_mul_f32_e32 v84, v58, v58
	s_nop 1
	v_mov_b32_dpp v84, v84 quad_perm:[1,0,3,2] row_mask:0xf bank_mask:0xf bound_ctrl:1
	v_fmac_f32_e32 v84, v58, v58
	s_nop 1
	v_add_f32_dpp v84, v84, v84 quad_perm:[2,3,0,1] row_mask:0xf bank_mask:0xf bound_ctrl:1
	s_nop 1
	v_add_f32_dpp v84, v84, v84 row_half_mirror row_mask:0xf bank_mask:0xf bound_ctrl:1
	s_nop 1
	v_mov_b32_dpp v108, v84 row_mirror row_mask:0xf bank_mask:0xf bound_ctrl:1
	s_and_saveexec_b64 s[56:57], s[0:1]
	v_add_f32_e32 v84, v84, v108
	ds_write_b32 v106, v84 offset:1600
	s_or_b64 exec, exec, s[56:57]
	v_mul_f32_e32 v84, v59, v59
	s_nop 1
	v_mov_b32_dpp v84, v84 quad_perm:[1,0,3,2] row_mask:0xf bank_mask:0xf bound_ctrl:1
	v_fmac_f32_e32 v84, v59, v59
	s_nop 1
	v_add_f32_dpp v84, v84, v84 quad_perm:[2,3,0,1] row_mask:0xf bank_mask:0xf bound_ctrl:1
	s_nop 1
	v_add_f32_dpp v84, v84, v84 row_half_mirror row_mask:0xf bank_mask:0xf bound_ctrl:1
	s_nop 1
	v_mov_b32_dpp v108, v84 row_mirror row_mask:0xf bank_mask:0xf bound_ctrl:1
	s_and_saveexec_b64 s[56:57], s[0:1]
	s_cbranch_execz .LBB0_917
	v_add_f32_e32 v84, v84, v108
	ds_write_b32 v100, v84
	s_branch .LBB0_917
